# GEMM K-loops: dropped the per-phase s_setprio 1/0 toggles around the MFMA sections (on top of duplicate-wait removal)
# speedup vs baseline: 1.0093x; 1.0028x over previous
.LBB0_175:
	ds_read_b128 v[16:19], v233
	ds_read_b128 v[20:23], v233 offset:1024
	ds_read_b128 v[24:27], v233 offset:2048
	ds_read_b128 v[28:31], v233 offset:3072
	s_add_u32 s6, s4, 0xfffc0080
	s_addc_u32 s7, s5, -1
	s_cmp_eq_u32 s34, 12
	s_cselect_b32 s9, s10, s7
	s_cselect_b32 s8, s11, s6
	s_cselect_b32 s7, s25, s31
	s_cselect_b32 s6, s29, s30
	v_lshl_add_u64 v[202:203], s[4:5], 0, v[182:183]
	s_add_i32 m0, s92, 0xc000
	ds_read_b128 v[40:43], v234
	ds_read_b128 v[44:47], v234 offset:1024
	ds_read_b128 v[48:51], v234 offset:2048
	ds_read_b128 v[52:55], v234 offset:3072
	ds_read_b128 v[186:189], v234 offset:4096
	ds_read_b128 v[190:193], v234 offset:5120
	ds_read_b128 v[194:197], v234 offset:6144
	ds_read_b128 v[198:201], v234 offset:7168
	global_load_lds_dwordx4 v[202:203], off
	v_lshl_add_u64 v[202:203], s[4:5], 0, v[184:185]
	s_add_i32 m0, s92, 0xe000
	s_nop 0
	global_load_lds_dwordx4 v[202:203], off
	s_waitcnt lgkmcnt(8)
	s_barrier
	s_waitcnt lgkmcnt(0)
	v_mfma_f32_16x16x32_bf16 v[156:159], v[16:19], v[40:43], v[156:159]
	v_mfma_f32_16x16x32_bf16 v[152:155], v[24:27], v[40:43], v[152:155]
	v_mfma_f32_16x16x32_bf16 v[140:143], v[16:19], v[48:51], v[140:143]
	v_mfma_f32_16x16x32_bf16 v[136:139], v[24:27], v[48:51], v[136:139]
	v_mfma_f32_16x16x32_bf16 v[124:127], v[16:19], v[186:189], v[124:127]
	v_mfma_f32_16x16x32_bf16 v[120:123], v[24:27], v[186:189], v[120:123]
	v_mfma_f32_16x16x32_bf16 v[108:111], v[16:19], v[194:197], v[108:111]
	v_mfma_f32_16x16x32_bf16 v[104:107], v[24:27], v[194:197], v[104:107]
	v_mfma_f32_16x16x32_bf16 v[156:159], v[20:23], v[44:47], v[156:159]
	v_mfma_f32_16x16x32_bf16 v[152:155], v[28:31], v[44:47], v[152:155]
	v_mfma_f32_16x16x32_bf16 v[140:143], v[20:23], v[52:55], v[140:143]
	v_mfma_f32_16x16x32_bf16 v[136:139], v[28:31], v[52:55], v[136:139]
	v_mfma_f32_16x16x32_bf16 v[124:127], v[20:23], v[190:193], v[124:127]
	v_mfma_f32_16x16x32_bf16 v[120:123], v[28:31], v[190:193], v[120:123]
	v_mfma_f32_16x16x32_bf16 v[108:111], v[20:23], v[198:201], v[108:111]
	v_mfma_f32_16x16x32_bf16 v[104:107], v[28:31], v[198:201], v[104:107]
	s_barrier
	s_add_i32 s35, s1, s33
	v_lshl_add_u64 v[218:219], s[6:7], 0, v[166:167]
	s_mov_b32 m0, s35
	ds_read_b128 v[202:205], v235
	ds_read_b128 v[206:209], v235 offset:1024
	ds_read_b128 v[210:213], v235 offset:2048
	ds_read_b128 v[214:217], v235 offset:3072
	global_load_lds_dwordx4 v[218:219], off
	v_lshl_add_u64 v[246:247], s[6:7], 0, v[162:163]
	s_add_i32 m0, s35, 0x2000
	s_nop 0
	global_load_lds_dwordx4 v[246:247], off
	s_barrier
	s_waitcnt lgkmcnt(0)
	v_mfma_f32_16x16x32_bf16 v[148:151], v[202:205], v[40:43], v[148:151]
	v_mfma_f32_16x16x32_bf16 v[40:43], v[210:213], v[40:43], v[144:147]
	v_mfma_f32_16x16x32_bf16 v[148:151], v[206:209], v[44:47], v[148:151]
	v_mfma_f32_16x16x32_bf16 v[40:43], v[214:217], v[44:47], v[40:43]
	v_mfma_f32_16x16x32_bf16 v[44:47], v[202:205], v[48:51], v[132:135]
	v_mfma_f32_16x16x32_bf16 v[48:51], v[210:213], v[48:51], v[128:131]
	v_mfma_f32_16x16x32_bf16 v[112:115], v[210:213], v[186:189], v[112:115]
	v_mfma_f32_16x16x32_bf16 v[100:103], v[202:205], v[194:197], v[100:103]
	v_mfma_f32_16x16x32_bf16 v[96:99], v[210:213], v[194:197], v[96:99]
	v_mfma_f32_16x16x32_bf16 v[44:47], v[206:209], v[52:55], v[44:47]
	v_mfma_f32_16x16x32_bf16 v[48:51], v[214:217], v[52:55], v[48:51]
	v_mfma_f32_16x16x32_bf16 v[52:55], v[202:205], v[186:189], v[116:119]
	v_mfma_f32_16x16x32_bf16 v[112:115], v[214:217], v[190:193], v[112:115]
	v_mfma_f32_16x16x32_bf16 v[100:103], v[206:209], v[198:201], v[100:103]
	v_mfma_f32_16x16x32_bf16 v[96:99], v[214:217], v[198:201], v[96:99]
	v_mfma_f32_16x16x32_bf16 v[52:55], v[206:209], v[190:193], v[52:55]
	s_mov_b32 m0, s92
	v_lshl_add_u64 v[248:249], s[8:9], 0, v[168:169]
	s_barrier
	ds_read_b128 v[116:119], v234 offset:16384
	ds_read_b128 v[128:131], v234 offset:17408
	ds_read_b128 v[132:135], v234 offset:18432
	ds_read_b128 v[144:147], v234 offset:19456
	ds_read_b128 v[186:189], v234 offset:20480
	ds_read_b128 v[190:193], v234 offset:21504
	ds_read_b128 v[194:197], v234 offset:22528
	ds_read_b128 v[198:201], v234 offset:23552
	global_load_lds_dwordx4 v[248:249], off
	v_lshl_add_u64 v[250:251], s[8:9], 0, v[164:165]
	s_mov_b32 m0, s93
	s_nop 0
	global_load_lds_dwordx4 v[250:251], off
	s_barrier
	s_waitcnt lgkmcnt(0)
	v_mfma_f32_16x16x32_bf16 v[92:95], v[16:19], v[116:119], v[92:95]
	v_mfma_f32_16x16x32_bf16 v[88:91], v[24:27], v[116:119], v[88:91]
	v_mfma_f32_16x16x32_bf16 v[76:79], v[16:19], v[132:135], v[76:79]
	v_mfma_f32_16x16x32_bf16 v[72:75], v[24:27], v[132:135], v[72:75]
	v_mfma_f32_16x16x32_bf16 v[60:63], v[16:19], v[186:189], v[60:63]
	v_mfma_f32_16x16x32_bf16 v[56:59], v[24:27], v[186:189], v[56:59]
	v_mfma_f32_16x16x32_bf16 v[12:15], v[16:19], v[194:197], v[12:15]
	v_mfma_f32_16x16x32_bf16 v[8:11], v[24:27], v[194:197], v[8:11]
	v_mfma_f32_16x16x32_bf16 v[92:95], v[20:23], v[128:131], v[92:95]
	v_mfma_f32_16x16x32_bf16 v[88:91], v[28:31], v[128:131], v[88:91]
	v_mfma_f32_16x16x32_bf16 v[76:79], v[20:23], v[144:147], v[76:79]
	v_mfma_f32_16x16x32_bf16 v[72:75], v[28:31], v[144:147], v[72:75]
	v_mfma_f32_16x16x32_bf16 v[60:63], v[20:23], v[190:193], v[60:63]
	v_mfma_f32_16x16x32_bf16 v[56:59], v[28:31], v[190:193], v[56:59]
	v_mfma_f32_16x16x32_bf16 v[12:15], v[20:23], v[198:201], v[12:15]
	v_mfma_f32_16x16x32_bf16 v[8:11], v[28:31], v[198:201], v[8:11]
	s_barrier
	s_add_u32 s56, s6, 0x40000
	s_addc_u32 s57, s7, 0
	s_add_i32 s35, s18, s33
	v_lshl_add_u64 v[16:17], s[56:57], 0, v[166:167]
	s_mov_b32 m0, s35
	s_nop 0
	global_load_lds_dwordx4 v[16:17], off
	v_lshl_add_u64 v[16:17], s[56:57], 0, v[162:163]
	s_add_i32 m0, s35, 0x2000
	s_nop 0
	global_load_lds_dwordx4 v[16:17], off
	s_waitcnt vmcnt(6)
	s_barrier
	v_mfma_f32_16x16x32_bf16 v[36:39], v[202:205], v[186:189], v[36:39]
	v_mfma_f32_16x16x32_bf16 v[32:35], v[210:213], v[186:189], v[32:35]
	v_mfma_f32_16x16x32_bf16 v[4:7], v[202:205], v[194:197], v[4:7]
	v_mfma_f32_16x16x32_bf16 v[0:3], v[210:213], v[194:197], v[0:3]
	v_mfma_f32_16x16x32_bf16 v[16:19], v[202:205], v[116:119], v[84:87]
	v_mfma_f32_16x16x32_bf16 v[20:23], v[210:213], v[116:119], v[80:83]
	v_mfma_f32_16x16x32_bf16 v[24:27], v[202:205], v[132:135], v[68:71]
	v_mfma_f32_16x16x32_bf16 v[28:31], v[210:213], v[132:135], v[64:67]
	v_mfma_f32_16x16x32_bf16 v[36:39], v[206:209], v[190:193], v[36:39]
	v_mfma_f32_16x16x32_bf16 v[32:35], v[214:217], v[190:193], v[32:35]
	v_mfma_f32_16x16x32_bf16 v[4:7], v[206:209], v[198:201], v[4:7]
	v_mfma_f32_16x16x32_bf16 v[0:3], v[214:217], v[198:201], v[0:3]
	v_mfma_f32_16x16x32_bf16 v[16:19], v[206:209], v[128:131], v[16:19]
	v_mfma_f32_16x16x32_bf16 v[20:23], v[214:217], v[128:131], v[20:23]
	v_mfma_f32_16x16x32_bf16 v[24:27], v[206:209], v[144:147], v[24:27]
	v_mfma_f32_16x16x32_bf16 v[28:31], v[214:217], v[144:147], v[28:31]
	s_add_i32 s35, 0, 0x18000
	v_add_u32_e32 v84, s35, v232
	s_barrier
	ds_read_b128 v[64:67], v84
	ds_read_b128 v[68:71], v84 offset:1024
	ds_read_b128 v[80:83], v84 offset:2048
	ds_read_b128 v[84:87], v84 offset:3072
	s_add_u32 s8, s8, 0x40000
	s_addc_u32 s9, s9, 0
	s_mov_b32 m0, s96
	v_lshl_add_u64 v[132:133], s[8:9], 0, v[168:169]
	ds_read_b128 v[116:119], v234 offset:32768
	ds_read_b128 v[128:131], v234 offset:33792
	ds_read_b128 v[186:189], v234 offset:34816
	ds_read_b128 v[190:193], v234 offset:35840
	ds_read_b128 v[194:197], v234 offset:36864
	ds_read_b128 v[198:201], v234 offset:37888
	ds_read_b128 v[202:205], v234 offset:38912
	ds_read_b128 v[206:209], v234 offset:39936
	global_load_lds_dwordx4 v[132:133], off
	v_lshl_add_u64 v[132:133], s[8:9], 0, v[164:165]
	s_mov_b32 m0, s97
	s_nop 0
	global_load_lds_dwordx4 v[132:133], off
	s_waitcnt lgkmcnt(8)
	s_barrier
	s_waitcnt lgkmcnt(0)
	v_mfma_f32_16x16x32_bf16 v[132:135], v[64:67], v[116:119], v[156:159]
	v_mfma_f32_16x16x32_bf16 v[156:159], v[68:71], v[128:131], v[132:135]
	v_mfma_f32_16x16x32_bf16 v[132:135], v[80:83], v[116:119], v[152:155]
	v_mfma_f32_16x16x32_bf16 v[152:155], v[84:87], v[128:131], v[132:135]
	v_mfma_f32_16x16x32_bf16 v[132:135], v[64:67], v[186:189], v[140:143]
	v_mfma_f32_16x16x32_bf16 v[140:143], v[68:71], v[190:193], v[132:135]
	v_mfma_f32_16x16x32_bf16 v[132:135], v[80:83], v[186:189], v[136:139]
	v_mfma_f32_16x16x32_bf16 v[124:127], v[64:67], v[194:197], v[124:127]
	v_mfma_f32_16x16x32_bf16 v[120:123], v[80:83], v[194:197], v[120:123]
	v_mfma_f32_16x16x32_bf16 v[108:111], v[64:67], v[202:205], v[108:111]
	v_mfma_f32_16x16x32_bf16 v[104:107], v[80:83], v[202:205], v[104:107]
	v_mfma_f32_16x16x32_bf16 v[136:139], v[84:87], v[190:193], v[132:135]
	v_mfma_f32_16x16x32_bf16 v[124:127], v[68:71], v[198:201], v[124:127]
	v_mfma_f32_16x16x32_bf16 v[120:123], v[84:87], v[198:201], v[120:123]
	v_mfma_f32_16x16x32_bf16 v[108:111], v[68:71], v[206:209], v[108:111]
	v_mfma_f32_16x16x32_bf16 v[104:107], v[84:87], v[206:209], v[104:107]
	s_barrier
	s_add_i32 s8, 0, 0x1c000
	v_add_u32_e32 v132, s8, v232
	s_add_i32 s9, s35, s33
	ds_read_b128 v[210:213], v132
	ds_read_b128 v[214:217], v132 offset:1024
	ds_read_b128 v[238:241], v132 offset:2048
	ds_read_b128 v[242:245], v132 offset:3072
	v_lshl_add_u64 v[132:133], v[218:219], 0, s[14:15]
	s_mov_b32 m0, s9
	s_nop 0
	global_load_lds_dwordx4 v[132:133], off
	v_lshl_add_u64 v[132:133], v[246:247], 0, s[14:15]
	s_add_i32 m0, s9, 0x2000
	s_nop 0
	global_load_lds_dwordx4 v[132:133], off
	s_barrier
	s_waitcnt lgkmcnt(0)
	v_mfma_f32_16x16x32_bf16 v[40:43], v[238:241], v[116:119], v[40:43]
	v_mfma_f32_16x16x32_bf16 v[132:135], v[210:213], v[116:119], v[148:151]
	v_mfma_f32_16x16x32_bf16 v[144:147], v[242:245], v[128:131], v[40:43]
	v_mfma_f32_16x16x32_bf16 v[40:43], v[210:213], v[186:189], v[44:47]
	v_mfma_f32_16x16x32_bf16 v[148:151], v[214:217], v[128:131], v[132:135]
	v_mfma_f32_16x16x32_bf16 v[132:135], v[214:217], v[190:193], v[40:43]
	v_mfma_f32_16x16x32_bf16 v[40:43], v[238:241], v[186:189], v[48:51]
	v_mfma_f32_16x16x32_bf16 v[128:131], v[242:245], v[190:193], v[40:43]
	v_mfma_f32_16x16x32_bf16 v[40:43], v[210:213], v[194:197], v[52:55]
	v_mfma_f32_16x16x32_bf16 v[116:119], v[214:217], v[198:201], v[40:43]
	v_mfma_f32_16x16x32_bf16 v[40:43], v[238:241], v[194:197], v[112:115]
	v_mfma_f32_16x16x32_bf16 v[112:115], v[242:245], v[198:201], v[40:43]
	v_mfma_f32_16x16x32_bf16 v[40:43], v[210:213], v[202:205], v[100:103]
	v_mfma_f32_16x16x32_bf16 v[100:103], v[214:217], v[206:209], v[40:43]
	v_mfma_f32_16x16x32_bf16 v[40:43], v[238:241], v[202:205], v[96:99]
	v_mfma_f32_16x16x32_bf16 v[96:99], v[242:245], v[206:209], v[40:43]
	s_mov_b32 m0, s53
	v_lshl_add_u64 v[202:203], v[248:249], 0, s[14:15]
	s_barrier
	s_nop 2
	ds_read_b128 v[40:43], v234 offset:49152
	ds_read_b128 v[44:47], v234 offset:50176
	ds_read_b128 v[48:51], v234 offset:51200
	ds_read_b128 v[52:55], v234 offset:52224
	ds_read_b128 v[186:189], v234 offset:53248
	ds_read_b128 v[190:193], v234 offset:54272
	ds_read_b128 v[194:197], v234 offset:55296
	ds_read_b128 v[198:201], v234 offset:56320
	global_load_lds_dwordx4 v[202:203], off
	v_lshl_add_u64 v[202:203], v[250:251], 0, s[14:15]
	s_mov_b32 m0, s23
	s_nop 0
	global_load_lds_dwordx4 v[202:203], off
	s_barrier
	s_waitcnt lgkmcnt(0)
	v_mfma_f32_16x16x32_bf16 v[92:95], v[64:67], v[40:43], v[92:95]
	v_mfma_f32_16x16x32_bf16 v[88:91], v[80:83], v[40:43], v[88:91]
	v_mfma_f32_16x16x32_bf16 v[76:79], v[64:67], v[48:51], v[76:79]
	v_mfma_f32_16x16x32_bf16 v[72:75], v[80:83], v[48:51], v[72:75]
	v_mfma_f32_16x16x32_bf16 v[60:63], v[64:67], v[186:189], v[60:63]
	v_mfma_f32_16x16x32_bf16 v[56:59], v[80:83], v[186:189], v[56:59]
	v_mfma_f32_16x16x32_bf16 v[12:15], v[64:67], v[194:197], v[12:15]
	v_mfma_f32_16x16x32_bf16 v[8:11], v[80:83], v[194:197], v[8:11]
	v_mfma_f32_16x16x32_bf16 v[92:95], v[68:71], v[44:47], v[92:95]
	v_mfma_f32_16x16x32_bf16 v[88:91], v[84:87], v[44:47], v[88:91]
	v_mfma_f32_16x16x32_bf16 v[76:79], v[68:71], v[52:55], v[76:79]
	v_mfma_f32_16x16x32_bf16 v[72:75], v[84:87], v[52:55], v[72:75]
	v_mfma_f32_16x16x32_bf16 v[60:63], v[68:71], v[190:193], v[60:63]
	v_mfma_f32_16x16x32_bf16 v[56:59], v[84:87], v[190:193], v[56:59]
	v_mfma_f32_16x16x32_bf16 v[12:15], v[68:71], v[198:201], v[12:15]
	v_mfma_f32_16x16x32_bf16 v[8:11], v[84:87], v[198:201], v[8:11]
	s_barrier
	s_add_u32 s6, s6, 0x40080
	s_addc_u32 s7, s7, 0
	s_add_i32 s8, s8, s33
	v_lshl_add_u64 v[64:65], s[6:7], 0, v[166:167]
	s_mov_b32 m0, s8
	s_nop 0
	global_load_lds_dwordx4 v[64:65], off
	v_lshl_add_u64 v[64:65], s[6:7], 0, v[162:163]
	s_add_i32 m0, s8, 0x2000
	s_nop 0
	global_load_lds_dwordx4 v[64:65], off
	s_waitcnt vmcnt(6)
	s_barrier
	v_mfma_f32_16x16x32_bf16 v[16:19], v[210:213], v[40:43], v[16:19]
	v_mfma_f32_16x16x32_bf16 v[84:87], v[214:217], v[44:47], v[16:19]
	v_mfma_f32_16x16x32_bf16 v[16:19], v[238:241], v[40:43], v[20:23]
	v_mfma_f32_16x16x32_bf16 v[80:83], v[242:245], v[44:47], v[16:19]
	v_mfma_f32_16x16x32_bf16 v[16:19], v[210:213], v[48:51], v[24:27]
	v_mfma_f32_16x16x32_bf16 v[68:71], v[214:217], v[52:55], v[16:19]
	v_mfma_f32_16x16x32_bf16 v[16:19], v[238:241], v[48:51], v[28:31]
	v_mfma_f32_16x16x32_bf16 v[64:67], v[242:245], v[52:55], v[16:19]
	v_mfma_f32_16x16x32_bf16 v[16:19], v[210:213], v[186:189], v[36:39]
	v_mfma_f32_16x16x32_bf16 v[36:39], v[214:217], v[190:193], v[16:19]
	v_mfma_f32_16x16x32_bf16 v[16:19], v[238:241], v[186:189], v[32:35]
	v_mfma_f32_16x16x32_bf16 v[4:7], v[210:213], v[194:197], v[4:7]
	v_mfma_f32_16x16x32_bf16 v[0:3], v[238:241], v[194:197], v[0:3]
	v_mfma_f32_16x16x32_bf16 v[32:35], v[242:245], v[190:193], v[16:19]
	v_mfma_f32_16x16x32_bf16 v[4:7], v[214:217], v[198:201], v[4:7]
	v_mfma_f32_16x16x32_bf16 v[0:3], v[242:245], v[198:201], v[0:3]
	s_add_i32 s34, s34, 2
	s_add_u32 s4, s4, 0x100
	s_addc_u32 s5, s5, 0
	s_add_u32 s30, s30, 0x100
	s_addc_u32 s31, s31, 0
	s_cmp_gt_u32 s34, 13
	s_barrier
	s_cbranch_scc0 .LBB0_175
	s_cmp_gt_i32 s28, 1
	s_cselect_b64 s[6:7], -1, 0
	s_cmp_lt_i32 s28, 2
	s_cselect_b64 s[4:5], -1, 0
	s_add_i32 s8, s28, -3
	s_cmp_lt_u32 s8, 2
	s_cselect_b64 s[8:9], -1, 0
	s_lshl_b32 s29, s12, 8
	s_add_i32 s29, s29, s52
	v_or_b32_e32 v196, s29, v179
	s_nop 0
	v_ashrrev_i32_e32 v197, 31, v196
	v_readlane_b32 s72, v253, 63
	v_readlane_b32 s73, v252, 0
	s_or_b64 s[4:5], s[4:5], s[8:9]
	s_and_b32 s8, s29, 0xfc0
	v_lshl_add_u64 v[16:17], v[196:197], 2, s[72:73]
	global_load_dword v204, v[16:17], off
	global_load_dword v200, v[16:17], off offset:64
	global_load_dword v198, v[16:17], off offset:128
	global_load_dword v194, v[16:17], off offset:192
	global_load_dword v192, v[16:17], off offset:512
	global_load_dword v190, v[16:17], off offset:576
	global_load_dword v188, v[16:17], off offset:640
	global_load_dword v186, v[16:17], off offset:704
	v_or_b32_e32 v16, s8, v179
	v_readlane_b32 s8, v252, 45
	v_readlane_b32 s9, v252, 46
	s_and_b64 s[62:63], s[8:9], s[4:5]
	v_cndmask_b32_e64 v17, 0, 1, s[62:63]
	v_readlane_b32 s68, v253, 59
	v_readlane_b32 s69, v253, 60
	v_readlane_b32 s76, v252, 3
	v_readlane_b32 s77, v252, 4
	v_readlane_b32 s78, v252, 5
	v_readlane_b32 s79, v252, 6
	v_cmp_ne_u32_e64 s[4:5], 1, v17
	s_andn2_b64 vcc, exec, s[62:63]
	v_lshlrev_b32_e32 v187, 6, v16
	s_nop 6
	s_cbranch_vccnz .LBB0_178
	global_load_dwordx4 v[40:43], v187, s[76:77] offset:48
	global_load_dwordx4 v[44:47], v187, s[76:77] offset:32
	global_load_dwordx4 v[48:51], v187, s[76:77] offset:16
	global_load_dwordx4 v[52:55], v187, s[76:77]
	global_load_dwordx4 v[16:19], v187, s[76:77] offset:1072
	global_load_dwordx4 v[20:23], v187, s[76:77] offset:1056
	global_load_dwordx4 v[24:27], v187, s[76:77] offset:1040
	global_load_dwordx4 v[28:31], v187, s[76:77] offset:1024

.LBB0_612:
	ds_read_b128 v[164:167], v159
	ds_read_b128 v[168:171], v159 offset:1024
	ds_read_b128 v[180:183], v159 offset:2048
	ds_read_b128 v[184:187], v159 offset:3072
	s_add_u32 s24, s22, 0xfffc0080
	s_addc_u32 s25, s23, -1
	s_cmp_eq_u32 s45, 4
	s_cselect_b32 s35, s9, s25
	s_cselect_b32 s34, s41, s24
	s_cselect_b32 s25, s7, s44
	s_cselect_b32 s24, s42, s43
	v_lshl_add_u64 v[172:173], s[22:23], 0, v[154:155]
	s_add_i32 m0, s3, 0xc000
	ds_read_b128 v[188:191], v162
	ds_read_b128 v[192:195], v162 offset:1024
	ds_read_b128 v[196:199], v162 offset:2048
	ds_read_b128 v[200:203], v162 offset:3072
	ds_read_b128 v[204:207], v162 offset:4096
	ds_read_b128 v[208:211], v162 offset:5120
	ds_read_b128 v[212:215], v162 offset:6144
	ds_read_b128 v[216:219], v162 offset:7168
	global_load_lds_dwordx4 v[172:173], off
	v_lshl_add_u64 v[172:173], s[22:23], 0, v[156:157]
	s_add_i32 m0, s3, 0xe000
	s_nop 0
	global_load_lds_dwordx4 v[172:173], off
	s_waitcnt lgkmcnt(8)
	s_barrier
	s_waitcnt lgkmcnt(0)
	v_mfma_f32_16x16x32_bf16 v[124:127], v[164:167], v[188:191], v[124:127]
	v_mfma_f32_16x16x32_bf16 v[120:123], v[180:183], v[188:191], v[120:123]
	v_mfma_f32_16x16x32_bf16 v[116:119], v[164:167], v[196:199], v[116:119]
	v_mfma_f32_16x16x32_bf16 v[112:115], v[180:183], v[196:199], v[112:115]
	v_mfma_f32_16x16x32_bf16 v[108:111], v[164:167], v[204:207], v[108:111]
	v_mfma_f32_16x16x32_bf16 v[100:103], v[180:183], v[204:207], v[100:103]
	v_mfma_f32_16x16x32_bf16 v[92:95], v[164:167], v[212:215], v[92:95]
	v_mfma_f32_16x16x32_bf16 v[84:87], v[180:183], v[212:215], v[84:87]
	v_mfma_f32_16x16x32_bf16 v[124:127], v[168:171], v[192:195], v[124:127]
	v_mfma_f32_16x16x32_bf16 v[120:123], v[184:187], v[192:195], v[120:123]
	v_mfma_f32_16x16x32_bf16 v[116:119], v[168:171], v[200:203], v[116:119]
	v_mfma_f32_16x16x32_bf16 v[112:115], v[184:187], v[200:203], v[112:115]
	v_mfma_f32_16x16x32_bf16 v[108:111], v[168:171], v[208:211], v[108:111]
	v_mfma_f32_16x16x32_bf16 v[100:103], v[184:187], v[208:211], v[100:103]
	v_mfma_f32_16x16x32_bf16 v[92:95], v[168:171], v[216:219], v[92:95]
	v_mfma_f32_16x16x32_bf16 v[84:87], v[184:187], v[216:219], v[84:87]
	s_barrier
	s_add_i32 s52, s31, s19
	v_lshl_add_u64 v[172:173], s[24:25], 0, v[130:131]
	s_mov_b32 m0, s52
	ds_read_b128 v[232:235], v163
	ds_read_b128 v[236:239], v163 offset:1024
	ds_read_b128 v[240:243], v163 offset:2048
	ds_read_b128 v[244:247], v163 offset:3072
	global_load_lds_dwordx4 v[172:173], off
	v_lshl_add_u64 v[176:177], s[24:25], 0, v[134:135]
	s_add_i32 m0, s52, 0x2000
	s_nop 0
	global_load_lds_dwordx4 v[176:177], off
	s_barrier
	s_waitcnt lgkmcnt(0)
	v_mfma_f32_16x16x32_bf16 v[104:107], v[232:235], v[188:191], v[104:107]
	v_mfma_f32_16x16x32_bf16 v[96:99], v[240:243], v[188:191], v[96:99]
	v_mfma_f32_16x16x32_bf16 v[88:91], v[232:235], v[196:199], v[88:91]
	v_mfma_f32_16x16x32_bf16 v[80:83], v[240:243], v[196:199], v[80:83]
	v_mfma_f32_16x16x32_bf16 v[76:79], v[232:235], v[204:207], v[76:79]
	v_mfma_f32_16x16x32_bf16 v[72:75], v[240:243], v[204:207], v[72:75]
	v_mfma_f32_16x16x32_bf16 v[68:71], v[232:235], v[212:215], v[68:71]
	v_mfma_f32_16x16x32_bf16 v[64:67], v[240:243], v[212:215], v[64:67]
	v_mfma_f32_16x16x32_bf16 v[104:107], v[236:239], v[192:195], v[104:107]
	v_mfma_f32_16x16x32_bf16 v[96:99], v[244:247], v[192:195], v[96:99]
	v_mfma_f32_16x16x32_bf16 v[88:91], v[236:239], v[200:203], v[88:91]
	v_mfma_f32_16x16x32_bf16 v[80:83], v[244:247], v[200:203], v[80:83]
	v_mfma_f32_16x16x32_bf16 v[76:79], v[236:239], v[208:211], v[76:79]
	v_mfma_f32_16x16x32_bf16 v[72:75], v[244:247], v[208:211], v[72:75]
	v_mfma_f32_16x16x32_bf16 v[68:71], v[236:239], v[216:219], v[68:71]
	v_mfma_f32_16x16x32_bf16 v[64:67], v[244:247], v[216:219], v[64:67]
	s_mov_b32 m0, s3
	v_lshl_add_u64 v[248:249], s[34:35], 0, v[128:129]
	s_barrier
	ds_read_b128 v[188:191], v162 offset:16384
	ds_read_b128 v[192:195], v162 offset:17408
	ds_read_b128 v[196:199], v162 offset:18432
	ds_read_b128 v[200:203], v162 offset:19456
	ds_read_b128 v[204:207], v162 offset:20480
	ds_read_b128 v[208:211], v162 offset:21504
	ds_read_b128 v[212:215], v162 offset:22528
	ds_read_b128 v[216:219], v162 offset:23552
	global_load_lds_dwordx4 v[248:249], off
	v_lshl_add_u64 v[250:251], s[34:35], 0, v[132:133]
	s_mov_b32 m0, s20
	s_nop 0
	global_load_lds_dwordx4 v[250:251], off
	s_barrier
	s_waitcnt lgkmcnt(0)
	v_mfma_f32_16x16x32_bf16 v[60:63], v[164:167], v[188:191], v[60:63]
	v_mfma_f32_16x16x32_bf16 v[56:59], v[180:183], v[188:191], v[56:59]
	v_mfma_f32_16x16x32_bf16 v[52:55], v[164:167], v[196:199], v[52:55]
	v_mfma_f32_16x16x32_bf16 v[48:51], v[180:183], v[196:199], v[48:51]
	v_mfma_f32_16x16x32_bf16 v[44:47], v[164:167], v[204:207], v[44:47]
	v_mfma_f32_16x16x32_bf16 v[40:43], v[180:183], v[204:207], v[40:43]
	v_mfma_f32_16x16x32_bf16 v[28:31], v[164:167], v[212:215], v[28:31]
	v_mfma_f32_16x16x32_bf16 v[24:27], v[180:183], v[212:215], v[24:27]
	v_mfma_f32_16x16x32_bf16 v[60:63], v[168:171], v[192:195], v[60:63]
	v_mfma_f32_16x16x32_bf16 v[56:59], v[184:187], v[192:195], v[56:59]
	v_mfma_f32_16x16x32_bf16 v[52:55], v[168:171], v[200:203], v[52:55]
	v_mfma_f32_16x16x32_bf16 v[48:51], v[184:187], v[200:203], v[48:51]
	v_mfma_f32_16x16x32_bf16 v[44:47], v[168:171], v[208:211], v[44:47]
	v_mfma_f32_16x16x32_bf16 v[40:43], v[184:187], v[208:211], v[40:43]
	v_mfma_f32_16x16x32_bf16 v[28:31], v[168:171], v[216:219], v[28:31]
	v_mfma_f32_16x16x32_bf16 v[24:27], v[184:187], v[216:219], v[24:27]
	s_barrier
	s_add_u32 s52, s24, 0x80000
	s_addc_u32 s53, s25, 0
	s_add_i32 s54, s33, s19
	v_lshl_add_u64 v[164:165], s[52:53], 0, v[130:131]
	s_mov_b32 m0, s54
	s_nop 0
	global_load_lds_dwordx4 v[164:165], off
	v_lshl_add_u64 v[164:165], s[52:53], 0, v[134:135]
	s_add_i32 m0, s54, 0x2000
	s_nop 0
	global_load_lds_dwordx4 v[164:165], off
	s_waitcnt vmcnt(6)
	s_barrier
	v_mfma_f32_16x16x32_bf16 v[36:39], v[232:235], v[188:191], v[36:39]
	v_mfma_f32_16x16x32_bf16 v[32:35], v[240:243], v[188:191], v[32:35]
	v_mfma_f32_16x16x32_bf16 v[20:23], v[232:235], v[196:199], v[20:23]
	v_mfma_f32_16x16x32_bf16 v[16:19], v[240:243], v[196:199], v[16:19]
	v_mfma_f32_16x16x32_bf16 v[12:15], v[232:235], v[204:207], v[12:15]
	v_mfma_f32_16x16x32_bf16 v[8:11], v[240:243], v[204:207], v[8:11]
	v_mfma_f32_16x16x32_bf16 v[4:7], v[232:235], v[212:215], v[4:7]
	v_mfma_f32_16x16x32_bf16 v[0:3], v[240:243], v[212:215], v[0:3]
	v_mfma_f32_16x16x32_bf16 v[36:39], v[236:239], v[192:195], v[36:39]
	v_mfma_f32_16x16x32_bf16 v[32:35], v[244:247], v[192:195], v[32:35]
	v_mfma_f32_16x16x32_bf16 v[20:23], v[236:239], v[200:203], v[20:23]
	v_mfma_f32_16x16x32_bf16 v[16:19], v[244:247], v[200:203], v[16:19]
	v_mfma_f32_16x16x32_bf16 v[12:15], v[236:239], v[208:211], v[12:15]
	v_mfma_f32_16x16x32_bf16 v[8:11], v[244:247], v[208:211], v[8:11]
	v_mfma_f32_16x16x32_bf16 v[4:7], v[236:239], v[216:219], v[4:7]
	v_mfma_f32_16x16x32_bf16 v[0:3], v[244:247], v[216:219], v[0:3]
	s_add_i32 s52, 0, 0x18000
	v_add_u32_e32 v174, s52, v158
	s_barrier
	ds_read_b128 v[164:167], v174
	ds_read_b128 v[168:171], v174 offset:1024
	ds_read_b128 v[180:183], v174 offset:2048
	ds_read_b128 v[184:187], v174 offset:3072
	s_add_u32 s34, s34, 0x40000
	s_addc_u32 s35, s35, 0
	s_mov_b32 m0, s21
	v_lshl_add_u64 v[232:233], s[34:35], 0, v[128:129]
	ds_read_b128 v[188:191], v162 offset:32768
	ds_read_b128 v[192:195], v162 offset:33792
	ds_read_b128 v[196:199], v162 offset:34816
	ds_read_b128 v[200:203], v162 offset:35840
	ds_read_b128 v[204:207], v162 offset:36864
	ds_read_b128 v[208:211], v162 offset:37888
	ds_read_b128 v[212:215], v162 offset:38912
	ds_read_b128 v[216:219], v162 offset:39936
	global_load_lds_dwordx4 v[232:233], off
	v_lshl_add_u64 v[232:233], s[34:35], 0, v[132:133]
	s_mov_b32 m0, s27
	s_nop 0
	global_load_lds_dwordx4 v[232:233], off
	s_waitcnt lgkmcnt(8)
	s_barrier
	s_waitcnt lgkmcnt(0)
	v_mfma_f32_16x16x32_bf16 v[124:127], v[164:167], v[188:191], v[124:127]
	v_mfma_f32_16x16x32_bf16 v[120:123], v[180:183], v[188:191], v[120:123]
	v_mfma_f32_16x16x32_bf16 v[116:119], v[164:167], v[196:199], v[116:119]
	v_mfma_f32_16x16x32_bf16 v[112:115], v[180:183], v[196:199], v[112:115]
	v_mfma_f32_16x16x32_bf16 v[108:111], v[164:167], v[204:207], v[108:111]
	v_mfma_f32_16x16x32_bf16 v[100:103], v[180:183], v[204:207], v[100:103]
	v_mfma_f32_16x16x32_bf16 v[92:95], v[164:167], v[212:215], v[92:95]
	v_mfma_f32_16x16x32_bf16 v[84:87], v[180:183], v[212:215], v[84:87]
	v_mfma_f32_16x16x32_bf16 v[124:127], v[168:171], v[192:195], v[124:127]
	v_mfma_f32_16x16x32_bf16 v[120:123], v[184:187], v[192:195], v[120:123]
	v_mfma_f32_16x16x32_bf16 v[116:119], v[168:171], v[200:203], v[116:119]
	v_mfma_f32_16x16x32_bf16 v[112:115], v[184:187], v[200:203], v[112:115]
	v_mfma_f32_16x16x32_bf16 v[108:111], v[168:171], v[208:211], v[108:111]
	v_mfma_f32_16x16x32_bf16 v[100:103], v[184:187], v[208:211], v[100:103]
	v_mfma_f32_16x16x32_bf16 v[92:95], v[168:171], v[216:219], v[92:95]
	v_mfma_f32_16x16x32_bf16 v[84:87], v[184:187], v[216:219], v[84:87]
	s_barrier
	s_add_i32 s34, 0, 0x1c000
	s_add_i32 s35, s52, s19
	v_add_u32_e32 v174, s34, v158
	v_lshl_add_u64 v[172:173], v[172:173], 0, s[4:5]
	s_mov_b32 m0, s35
	ds_read_b128 v[232:235], v174
	ds_read_b128 v[236:239], v174 offset:1024
	ds_read_b128 v[240:243], v174 offset:2048
	ds_read_b128 v[244:247], v174 offset:3072
	global_load_lds_dwordx4 v[172:173], off
	v_lshl_add_u64 v[172:173], v[176:177], 0, s[4:5]
	s_add_i32 m0, s35, 0x2000
	s_nop 0
	global_load_lds_dwordx4 v[172:173], off
	s_barrier
	s_waitcnt lgkmcnt(0)
	v_mfma_f32_16x16x32_bf16 v[104:107], v[232:235], v[188:191], v[104:107]
	v_mfma_f32_16x16x32_bf16 v[96:99], v[240:243], v[188:191], v[96:99]
	v_mfma_f32_16x16x32_bf16 v[88:91], v[232:235], v[196:199], v[88:91]
	v_mfma_f32_16x16x32_bf16 v[80:83], v[240:243], v[196:199], v[80:83]
	v_mfma_f32_16x16x32_bf16 v[76:79], v[232:235], v[204:207], v[76:79]
	v_mfma_f32_16x16x32_bf16 v[72:75], v[240:243], v[204:207], v[72:75]
	v_mfma_f32_16x16x32_bf16 v[68:71], v[232:235], v[212:215], v[68:71]
	v_mfma_f32_16x16x32_bf16 v[64:67], v[240:243], v[212:215], v[64:67]
	v_mfma_f32_16x16x32_bf16 v[104:107], v[236:239], v[192:195], v[104:107]
	v_mfma_f32_16x16x32_bf16 v[96:99], v[244:247], v[192:195], v[96:99]
	v_mfma_f32_16x16x32_bf16 v[88:91], v[236:239], v[200:203], v[88:91]
	v_mfma_f32_16x16x32_bf16 v[80:83], v[244:247], v[200:203], v[80:83]
	v_mfma_f32_16x16x32_bf16 v[76:79], v[236:239], v[208:211], v[76:79]
	v_mfma_f32_16x16x32_bf16 v[72:75], v[244:247], v[208:211], v[72:75]
	v_mfma_f32_16x16x32_bf16 v[68:71], v[236:239], v[216:219], v[68:71]
	v_mfma_f32_16x16x32_bf16 v[64:67], v[244:247], v[216:219], v[64:67]
	s_mov_b32 m0, s29
	v_lshl_add_u64 v[172:173], v[248:249], 0, s[4:5]
	s_barrier
	ds_read_b128 v[188:191], v162 offset:49152
	ds_read_b128 v[192:195], v162 offset:50176
	ds_read_b128 v[196:199], v162 offset:51200
	ds_read_b128 v[200:203], v162 offset:52224
	ds_read_b128 v[204:207], v162 offset:53248
	ds_read_b128 v[208:211], v162 offset:54272
	ds_read_b128 v[212:215], v162 offset:55296
	ds_read_b128 v[216:219], v162 offset:56320
	global_load_lds_dwordx4 v[172:173], off
	v_lshl_add_u64 v[172:173], v[250:251], 0, s[4:5]
	s_mov_b32 m0, s30
	s_nop 0
	global_load_lds_dwordx4 v[172:173], off
	s_barrier
	s_waitcnt lgkmcnt(0)
	v_mfma_f32_16x16x32_bf16 v[60:63], v[164:167], v[188:191], v[60:63]
	v_mfma_f32_16x16x32_bf16 v[56:59], v[180:183], v[188:191], v[56:59]
	v_mfma_f32_16x16x32_bf16 v[52:55], v[164:167], v[196:199], v[52:55]
	v_mfma_f32_16x16x32_bf16 v[48:51], v[180:183], v[196:199], v[48:51]
	v_mfma_f32_16x16x32_bf16 v[44:47], v[164:167], v[204:207], v[44:47]
	v_mfma_f32_16x16x32_bf16 v[40:43], v[180:183], v[204:207], v[40:43]
	v_mfma_f32_16x16x32_bf16 v[28:31], v[164:167], v[212:215], v[28:31]
	v_mfma_f32_16x16x32_bf16 v[24:27], v[180:183], v[212:215], v[24:27]
	v_mfma_f32_16x16x32_bf16 v[60:63], v[168:171], v[192:195], v[60:63]
	v_mfma_f32_16x16x32_bf16 v[56:59], v[184:187], v[192:195], v[56:59]
	v_mfma_f32_16x16x32_bf16 v[52:55], v[168:171], v[200:203], v[52:55]
	v_mfma_f32_16x16x32_bf16 v[48:51], v[184:187], v[200:203], v[48:51]
	v_mfma_f32_16x16x32_bf16 v[44:47], v[168:171], v[208:211], v[44:47]
	v_mfma_f32_16x16x32_bf16 v[40:43], v[184:187], v[208:211], v[40:43]
	v_mfma_f32_16x16x32_bf16 v[28:31], v[168:171], v[216:219], v[28:31]
	v_mfma_f32_16x16x32_bf16 v[24:27], v[184:187], v[216:219], v[24:27]
	s_barrier
	s_add_u32 s24, s24, 0x80080
	s_addc_u32 s25, s25, 0
	s_add_i32 s34, s34, s19
	v_lshl_add_u64 v[164:165], s[24:25], 0, v[130:131]
	s_mov_b32 m0, s34
	s_nop 0
	global_load_lds_dwordx4 v[164:165], off
	v_lshl_add_u64 v[164:165], s[24:25], 0, v[134:135]
	s_add_i32 m0, s34, 0x2000
	s_nop 0
	global_load_lds_dwordx4 v[164:165], off
	s_waitcnt vmcnt(6)
	s_barrier
	v_mfma_f32_16x16x32_bf16 v[36:39], v[232:235], v[188:191], v[36:39]
	v_mfma_f32_16x16x32_bf16 v[32:35], v[240:243], v[188:191], v[32:35]
	v_mfma_f32_16x16x32_bf16 v[20:23], v[232:235], v[196:199], v[20:23]
	v_mfma_f32_16x16x32_bf16 v[16:19], v[240:243], v[196:199], v[16:19]
	v_mfma_f32_16x16x32_bf16 v[12:15], v[232:235], v[204:207], v[12:15]
	v_mfma_f32_16x16x32_bf16 v[8:11], v[240:243], v[204:207], v[8:11]
	v_mfma_f32_16x16x32_bf16 v[4:7], v[232:235], v[212:215], v[4:7]
	v_mfma_f32_16x16x32_bf16 v[0:3], v[240:243], v[212:215], v[0:3]
	v_mfma_f32_16x16x32_bf16 v[36:39], v[236:239], v[192:195], v[36:39]
	v_mfma_f32_16x16x32_bf16 v[32:35], v[244:247], v[192:195], v[32:35]
	v_mfma_f32_16x16x32_bf16 v[20:23], v[236:239], v[200:203], v[20:23]
	v_mfma_f32_16x16x32_bf16 v[16:19], v[244:247], v[200:203], v[16:19]
	v_mfma_f32_16x16x32_bf16 v[12:15], v[236:239], v[208:211], v[12:15]
	v_mfma_f32_16x16x32_bf16 v[8:11], v[244:247], v[208:211], v[8:11]
	v_mfma_f32_16x16x32_bf16 v[4:7], v[236:239], v[216:219], v[4:7]
	v_mfma_f32_16x16x32_bf16 v[0:3], v[244:247], v[216:219], v[0:3]
	s_add_i32 s45, s45, 2
	s_add_u32 s22, s22, 0x100
	s_addc_u32 s23, s23, 0
	s_add_u32 s43, s43, 0x100
	s_addc_u32 s44, s44, 0
	s_cmp_gt_u32 s45, 5
	s_barrier
	s_cbranch_scc0 .LBB0_612
	s_lshl_b32 s7, s26, 2
	s_and_b32 s7, s7, 0x7fffffe0
	s_add_i32 s22, s7, s2
	s_ashr_i32 s23, s22, 31
	s_lshl_b64 s[22:23], s[22:23], 18
	s_add_u32 s22, s82, s22
	s_addc_u32 s23, s83, s23
	v_lshl_add_u64 v[164:165], s[22:23], 0, v[138:139]
	v_lshl_add_u64 v[164:165], v[164:165], 0, v[136:137]
	global_store_dwordx4 v[164:165], v[124:127], off
	global_store_dwordx4 v[164:165], v[120:123], off offset:16
	global_store_dwordx4 v[164:165], v[104:107], off offset:512
	global_store_dwordx4 v[164:165], v[96:99], off offset:528
	s_and_b64 vcc, exec, s[10:11]
	s_mov_b32 s26, s40
	v_lshl_add_u64 v[96:97], s[22:23], 0, v[140:141]
	v_lshl_add_u64 v[96:97], v[96:97], 0, v[136:137]
	global_store_dwordx4 v[96:97], v[116:119], off
	global_store_dwordx4 v[96:97], v[112:115], off offset:16
	global_store_dwordx4 v[96:97], v[88:91], off offset:512
	global_store_dwordx4 v[96:97], v[80:83], off offset:528
	s_mov_b32 s2, s8
	s_mov_b64 s[24:25], s[16:17]
	v_lshl_add_u64 v[80:81], s[22:23], 0, v[142:143]
	v_lshl_add_u64 v[80:81], v[80:81], 0, v[136:137]
	global_store_dwordx4 v[80:81], v[108:111], off
	global_store_dwordx4 v[80:81], v[100:103], off offset:16
	global_store_dwordx4 v[80:81], v[76:79], off offset:512
	global_store_dwordx4 v[80:81], v[72:75], off offset:528
	s_nop 1
	v_lshl_add_u64 v[72:73], s[22:23], 0, v[144:145]
	v_lshl_add_u64 v[72:73], v[72:73], 0, v[136:137]
	global_store_dwordx4 v[72:73], v[92:95], off
	global_store_dwordx4 v[72:73], v[84:87], off offset:16
	global_store_dwordx4 v[72:73], v[68:71], off offset:512
	global_store_dwordx4 v[72:73], v[64:67], off offset:528
	s_nop 1
	v_lshl_add_u64 v[64:65], s[22:23], 0, v[146:147]
	v_lshl_add_u64 v[64:65], v[64:65], 0, v[136:137]
	global_store_dwordx4 v[64:65], v[60:63], off
	global_store_dwordx4 v[64:65], v[56:59], off offset:16
	global_store_dwordx4 v[64:65], v[36:39], off offset:512
	global_store_dwordx4 v[64:65], v[32:35], off offset:528
	s_nop 1
	v_lshl_add_u64 v[32:33], s[22:23], 0, v[148:149]
	v_lshl_add_u64 v[32:33], v[32:33], 0, v[136:137]
	global_store_dwordx4 v[32:33], v[52:55], off
	global_store_dwordx4 v[32:33], v[48:51], off offset:16
	global_store_dwordx4 v[32:33], v[20:23], off offset:512
	global_store_dwordx4 v[32:33], v[16:19], off offset:528
	s_nop 1
	v_lshl_add_u64 v[16:17], s[22:23], 0, v[150:151]
	v_lshl_add_u64 v[16:17], v[16:17], 0, v[136:137]
	global_store_dwordx4 v[16:17], v[44:47], off
	global_store_dwordx4 v[16:17], v[40:43], off offset:16
	global_store_dwordx4 v[16:17], v[12:15], off offset:512
	global_store_dwordx4 v[16:17], v[8:11], off offset:528
	s_nop 1
	v_lshl_add_u64 v[8:9], s[22:23], 0, v[152:153]
	v_lshl_add_u64 v[8:9], v[8:9], 0, v[136:137]
	s_mov_b64 s[22:23], s[14:15]
	global_store_dwordx4 v[8:9], v[28:31], off
	global_store_dwordx4 v[8:9], v[24:27], off offset:16
	global_store_dwordx4 v[8:9], v[4:7], off offset:512
	global_store_dwordx4 v[8:9], v[0:3], off offset:528
	s_cbranch_vccz .LBB0_606
	s_waitcnt vmcnt(0)
	s_cmpk_gt_u32 s18, 0xff
	s_cbranch_scc1 .LBB0_616
	s_barrier

.LBB0_730:
	s_ashr_i32 s45, s44, 31
	s_nop 0
	s_lshl_b64 s[56:57], s[44:45], 17
	v_readlane_b32 s68, v252, 15
	v_readlane_b32 s69, v252, 16
	s_add_u32 s56, s68, s56
	v_add_u32_e32 v157, s53, v154
	s_addc_u32 s57, s69, s57
	ds_read_b128 v[0:3], v157
	ds_read_b128 v[4:7], v157 offset:1024
	s_waitcnt lgkmcnt(0)
	ds_read_b128 v[8:11], v157 offset:2048
	ds_read_b128 v[12:15], v157 offset:3072
	s_nop 7
	s_nop 3
	s_and_b64 s[58:59], s[54:55], exec
	s_cselect_b32 s63, s57, s7
	s_cselect_b32 s62, s56, s6
	s_ashr_i32 s43, s42, 31
	s_nop 0
	s_lshl_b64 s[58:59], s[42:43], 17
	v_readlane_b32 s70, v253, 61
	v_readlane_b32 s71, v253, 62
	s_add_u32 s58, s70, s58
	s_nop 0
	s_addc_u32 s59, s71, s59
	s_and_b64 s[60:61], s[54:55], exec
	s_nop 7
	s_nop 4
	s_cselect_b32 s61, s59, s11
	s_cselect_b32 s60, s58, s10
	s_add_u32 vcc_lo, s6, 0x10080
	s_addc_u32 vcc_hi, s7, 0
	s_mov_b32 m0, s14
	s_waitcnt vmcnt(0)
	v_lshl_add_u64 v[48:49], vcc, 0, v[112:113]
	ds_read_b128 v[16:19], v155
	ds_read_b128 v[20:23], v155 offset:1024
	ds_read_b128 v[24:27], v155 offset:2048
	ds_read_b128 v[28:31], v155 offset:3072
	ds_read_b128 v[32:35], v155 offset:4096
	ds_read_b128 v[36:39], v155 offset:5120
	ds_read_b128 v[40:43], v155 offset:6144
	ds_read_b128 v[44:47], v155 offset:7168
	global_load_lds_dwordx4 v[48:49], off
	v_lshl_add_u64 v[48:49], vcc, 0, v[116:117]
	s_mov_b32 m0, s92
	s_nop 0
	global_load_lds_dwordx4 v[48:49], off
	s_waitcnt lgkmcnt(8)
	s_barrier
	s_waitcnt lgkmcnt(0)
	v_mfma_f32_16x16x32_bf16 v[48:51], v[0:3], v[16:19], 0
	v_mfma_f32_16x16x32_bf16 v[16:19], v[8:11], v[16:19], 0
	v_mfma_f32_16x16x32_bf16 v[48:51], v[4:7], v[20:23], v[48:51]
	v_mfma_f32_16x16x32_bf16 v[16:19], v[12:15], v[20:23], v[16:19]
	v_mfma_f32_16x16x32_bf16 v[20:23], v[0:3], v[24:27], 0
	v_mfma_f32_16x16x32_bf16 v[24:27], v[8:11], v[24:27], 0
	v_mfma_f32_16x16x32_bf16 v[20:23], v[4:7], v[28:31], v[20:23]
	v_mfma_f32_16x16x32_bf16 v[24:27], v[12:15], v[28:31], v[24:27]
	v_mfma_f32_16x16x32_bf16 v[28:31], v[0:3], v[32:35], 0
	v_mfma_f32_16x16x32_bf16 v[32:35], v[8:11], v[32:35], 0
	v_mfma_f32_16x16x32_bf16 v[28:31], v[4:7], v[36:39], v[28:31]
	v_mfma_f32_16x16x32_bf16 v[32:35], v[12:15], v[36:39], v[32:35]
	v_mfma_f32_16x16x32_bf16 v[36:39], v[0:3], v[40:43], 0
	v_mfma_f32_16x16x32_bf16 v[40:43], v[8:11], v[40:43], 0
	v_mfma_f32_16x16x32_bf16 v[36:39], v[4:7], v[44:47], v[36:39]
	v_mfma_f32_16x16x32_bf16 v[40:43], v[12:15], v[44:47], v[40:43]
	s_barrier
	v_lshl_add_u64 v[150:151], s[10:11], 0, v[114:115]
	s_mov_b32 m0, s93
	v_lshl_add_u64 v[44:45], v[150:151], 0, s[34:35]
	v_lshl_add_u64 v[152:153], s[10:11], 0, v[118:119]
	global_load_lds_dwordx4 v[44:45], off
	v_lshl_add_u64 v[44:45], v[152:153], 0, s[34:35]
	s_mov_b32 m0, s94
	s_nop 0
	global_load_lds_dwordx4 v[44:45], off
	s_barrier
	s_waitcnt lgkmcnt(0)
	s_setprio 1
	s_setprio 0
	v_lshl_add_u64 v[158:159], s[6:7], 0, v[112:113]
	s_mov_b32 m0, s19
	v_lshl_add_u64 v[80:81], v[158:159], 0, s[34:35]
	v_lshl_add_u64 v[162:163], s[6:7], 0, v[116:117]
	s_barrier
	ds_read_b128 v[44:47], v155 offset:16384
	ds_read_b128 v[52:55], v155 offset:17408
	ds_read_b128 v[56:59], v155 offset:18432
	ds_read_b128 v[60:63], v155 offset:19456
	ds_read_b128 v[64:67], v155 offset:20480
	ds_read_b128 v[68:71], v155 offset:21504
	ds_read_b128 v[72:75], v155 offset:22528
	ds_read_b128 v[76:79], v155 offset:23552
	global_load_lds_dwordx4 v[80:81], off
	v_lshl_add_u64 v[80:81], v[162:163], 0, s[34:35]
	s_mov_b32 m0, s20
	s_nop 0
	global_load_lds_dwordx4 v[80:81], off
	s_barrier
	s_waitcnt lgkmcnt(0)
	v_mfma_f32_16x16x32_bf16 v[80:83], v[0:3], v[44:47], 0
	v_mfma_f32_16x16x32_bf16 v[44:47], v[8:11], v[44:47], 0
	v_mfma_f32_16x16x32_bf16 v[80:83], v[4:7], v[52:55], v[80:83]
	v_mfma_f32_16x16x32_bf16 v[44:47], v[12:15], v[52:55], v[44:47]
	v_mfma_f32_16x16x32_bf16 v[52:55], v[0:3], v[56:59], 0
	v_mfma_f32_16x16x32_bf16 v[56:59], v[8:11], v[56:59], 0
	v_mfma_f32_16x16x32_bf16 v[52:55], v[4:7], v[60:63], v[52:55]
	v_mfma_f32_16x16x32_bf16 v[56:59], v[12:15], v[60:63], v[56:59]
	v_mfma_f32_16x16x32_bf16 v[60:63], v[0:3], v[64:67], 0
	v_mfma_f32_16x16x32_bf16 v[0:3], v[0:3], v[72:75], 0
	v_mfma_f32_16x16x32_bf16 v[60:63], v[4:7], v[68:71], v[60:63]
	v_mfma_f32_16x16x32_bf16 v[64:67], v[8:11], v[64:67], 0
	v_mfma_f32_16x16x32_bf16 v[0:3], v[4:7], v[76:79], v[0:3]
	v_mfma_f32_16x16x32_bf16 v[4:7], v[8:11], v[72:75], 0
	v_mfma_f32_16x16x32_bf16 v[64:67], v[12:15], v[68:71], v[64:67]
	v_mfma_f32_16x16x32_bf16 v[4:7], v[12:15], v[76:79], v[4:7]
	s_barrier
	s_add_u32 vcc_lo, s10, 0x10100
	s_addc_u32 vcc_hi, s11, 0
	s_mov_b32 m0, s21
	v_lshl_add_u64 v[8:9], vcc, 0, v[114:115]
	global_load_lds_dwordx4 v[8:9], off
	v_lshl_add_u64 v[8:9], vcc, 0, v[118:119]
	s_mov_b32 m0, s26
	s_nop 0
	global_load_lds_dwordx4 v[8:9], off
	s_waitcnt vmcnt(6)
	s_barrier
	s_setprio 1
	s_setprio 0
	v_add_u32_e32 v161, s96, v154
	s_barrier
	ds_read_b128 v[8:11], v161
	ds_read_b128 v[12:15], v161 offset:1024
	ds_read_b128 v[68:71], v161 offset:2048
	ds_read_b128 v[72:75], v161 offset:3072
	s_add_u32 vcc_lo, s6, 0x10100
	s_addc_u32 vcc_hi, s7, 0
	s_mov_b32 m0, s27
	v_lshl_add_u64 v[164:165], vcc, 0, v[112:113]
	ds_read_b128 v[76:79], v155 offset:32768
	ds_read_b128 v[84:87], v155 offset:33792
	ds_read_b128 v[88:91], v155 offset:34816
	ds_read_b128 v[92:95], v155 offset:35840
	ds_read_b128 v[96:99], v155 offset:36864
	ds_read_b128 v[100:103], v155 offset:37888
	ds_read_b128 v[104:107], v155 offset:38912
	ds_read_b128 v[108:111], v155 offset:39936
	global_load_lds_dwordx4 v[164:165], off
	v_lshl_add_u64 v[164:165], vcc, 0, v[116:117]
	s_mov_b32 m0, s28
	s_nop 0
	global_load_lds_dwordx4 v[164:165], off
	s_waitcnt lgkmcnt(8)
	s_barrier
	s_waitcnt lgkmcnt(0)
	v_mfma_f32_16x16x32_bf16 v[48:51], v[8:11], v[76:79], v[48:51]
	v_mfma_f32_16x16x32_bf16 v[16:19], v[68:71], v[76:79], v[16:19]
	v_mfma_f32_16x16x32_bf16 v[20:23], v[8:11], v[88:91], v[20:23]
	v_mfma_f32_16x16x32_bf16 v[24:27], v[68:71], v[88:91], v[24:27]
	v_mfma_f32_16x16x32_bf16 v[28:31], v[8:11], v[96:99], v[28:31]
	v_mfma_f32_16x16x32_bf16 v[32:35], v[68:71], v[96:99], v[32:35]
	v_mfma_f32_16x16x32_bf16 v[36:39], v[8:11], v[104:107], v[36:39]
	v_mfma_f32_16x16x32_bf16 v[40:43], v[68:71], v[104:107], v[40:43]
	v_mfma_f32_16x16x32_bf16 v[48:51], v[12:15], v[84:87], v[48:51]
	v_mfma_f32_16x16x32_bf16 v[16:19], v[72:75], v[84:87], v[16:19]
	v_mfma_f32_16x16x32_bf16 v[20:23], v[12:15], v[92:95], v[20:23]
	v_mfma_f32_16x16x32_bf16 v[24:27], v[72:75], v[92:95], v[24:27]
	v_mfma_f32_16x16x32_bf16 v[28:31], v[12:15], v[100:103], v[28:31]
	v_mfma_f32_16x16x32_bf16 v[32:35], v[72:75], v[100:103], v[32:35]
	v_mfma_f32_16x16x32_bf16 v[36:39], v[12:15], v[108:111], v[36:39]
	v_mfma_f32_16x16x32_bf16 v[40:43], v[72:75], v[108:111], v[40:43]
	s_barrier
	s_mov_b32 m0, s97
	v_lshl_add_u64 v[76:77], v[150:151], 0, s[40:41]
	global_load_lds_dwordx4 v[76:77], off
	v_lshl_add_u64 v[76:77], v[152:153], 0, s[40:41]
	s_mov_b32 m0, s18
	s_nop 0
	global_load_lds_dwordx4 v[76:77], off
	s_barrier
	s_waitcnt lgkmcnt(0)
	s_setprio 1
	s_setprio 0
	s_mov_b32 m0, s29
	v_lshl_add_u64 v[150:151], v[158:159], 0, s[40:41]
	s_barrier
	ds_read_b128 v[76:79], v155 offset:49152
	ds_read_b128 v[84:87], v155 offset:50176
	ds_read_b128 v[88:91], v155 offset:51200
	ds_read_b128 v[92:95], v155 offset:52224
	ds_read_b128 v[96:99], v155 offset:53248
	ds_read_b128 v[100:103], v155 offset:54272
	ds_read_b128 v[104:107], v155 offset:55296
	ds_read_b128 v[108:111], v155 offset:56320
	global_load_lds_dwordx4 v[150:151], off
	v_lshl_add_u64 v[150:151], v[162:163], 0, s[40:41]
	s_mov_b32 m0, s30
	s_nop 0
	global_load_lds_dwordx4 v[150:151], off
	s_barrier
	s_waitcnt lgkmcnt(0)
	v_mfma_f32_16x16x32_bf16 v[80:83], v[8:11], v[76:79], v[80:83]
	v_mfma_f32_16x16x32_bf16 v[44:47], v[68:71], v[76:79], v[44:47]
	v_mfma_f32_16x16x32_bf16 v[52:55], v[8:11], v[88:91], v[52:55]
	v_mfma_f32_16x16x32_bf16 v[56:59], v[68:71], v[88:91], v[56:59]
	v_mfma_f32_16x16x32_bf16 v[60:63], v[8:11], v[96:99], v[60:63]
	v_mfma_f32_16x16x32_bf16 v[64:67], v[68:71], v[96:99], v[64:67]
	v_mfma_f32_16x16x32_bf16 v[0:3], v[8:11], v[104:107], v[0:3]
	v_mfma_f32_16x16x32_bf16 v[4:7], v[68:71], v[104:107], v[4:7]
	v_mfma_f32_16x16x32_bf16 v[80:83], v[12:15], v[84:87], v[80:83]
	v_mfma_f32_16x16x32_bf16 v[44:47], v[72:75], v[84:87], v[44:47]
	v_mfma_f32_16x16x32_bf16 v[52:55], v[12:15], v[92:95], v[52:55]
	v_mfma_f32_16x16x32_bf16 v[56:59], v[72:75], v[92:95], v[56:59]
	v_mfma_f32_16x16x32_bf16 v[60:63], v[12:15], v[100:103], v[60:63]
	v_mfma_f32_16x16x32_bf16 v[64:67], v[72:75], v[100:103], v[64:67]
	v_mfma_f32_16x16x32_bf16 v[0:3], v[12:15], v[108:111], v[0:3]
	v_mfma_f32_16x16x32_bf16 v[4:7], v[72:75], v[108:111], v[4:7]
	s_barrier
	s_add_u32 s10, s10, 0x10180
	s_addc_u32 s11, s11, 0
	s_mov_b32 m0, s31
	v_lshl_add_u64 v[8:9], s[10:11], 0, v[114:115]
	global_load_lds_dwordx4 v[8:9], off
	v_lshl_add_u64 v[8:9], s[10:11], 0, v[118:119]
	s_mov_b32 m0, s33
	s_nop 0
	global_load_lds_dwordx4 v[8:9], off
	s_waitcnt vmcnt(6)
	s_barrier
	s_setprio 1
	s_setprio 0
	s_barrier
	ds_read_b128 v[8:11], v157
	ds_read_b128 v[12:15], v157 offset:1024
	ds_read_b128 v[68:71], v157 offset:2048
	ds_read_b128 v[72:75], v157 offset:3072
	s_add_u32 s6, s6, 0x10180
	s_addc_u32 s7, s7, 0
	s_mov_b32 m0, s14
	v_lshl_add_u64 v[150:151], s[6:7], 0, v[112:113]
	ds_read_b128 v[76:79], v155
	ds_read_b128 v[84:87], v155 offset:1024
	ds_read_b128 v[88:91], v155 offset:2048
	ds_read_b128 v[92:95], v155 offset:3072
	ds_read_b128 v[96:99], v155 offset:4096
	ds_read_b128 v[100:103], v155 offset:5120
	ds_read_b128 v[104:107], v155 offset:6144
	ds_read_b128 v[108:111], v155 offset:7168
	global_load_lds_dwordx4 v[150:151], off
	v_lshl_add_u64 v[150:151], s[6:7], 0, v[116:117]
	s_mov_b32 m0, s92
	s_nop 0
	global_load_lds_dwordx4 v[150:151], off
	s_waitcnt lgkmcnt(8)
	s_barrier
	s_waitcnt lgkmcnt(0)
	v_mfma_f32_16x16x32_bf16 v[48:51], v[8:11], v[76:79], v[48:51]
	v_mfma_f32_16x16x32_bf16 v[16:19], v[68:71], v[76:79], v[16:19]
	v_mfma_f32_16x16x32_bf16 v[20:23], v[8:11], v[88:91], v[20:23]
	v_mfma_f32_16x16x32_bf16 v[24:27], v[68:71], v[88:91], v[24:27]
	v_mfma_f32_16x16x32_bf16 v[28:31], v[8:11], v[96:99], v[28:31]
	v_mfma_f32_16x16x32_bf16 v[32:35], v[68:71], v[96:99], v[32:35]
	v_mfma_f32_16x16x32_bf16 v[36:39], v[8:11], v[104:107], v[36:39]
	v_mfma_f32_16x16x32_bf16 v[40:43], v[68:71], v[104:107], v[40:43]
	v_mfma_f32_16x16x32_bf16 v[48:51], v[12:15], v[84:87], v[48:51]
	v_mfma_f32_16x16x32_bf16 v[16:19], v[72:75], v[84:87], v[16:19]
	v_mfma_f32_16x16x32_bf16 v[20:23], v[12:15], v[92:95], v[20:23]
	v_mfma_f32_16x16x32_bf16 v[24:27], v[72:75], v[92:95], v[24:27]
	v_mfma_f32_16x16x32_bf16 v[28:31], v[12:15], v[100:103], v[28:31]
	v_mfma_f32_16x16x32_bf16 v[32:35], v[72:75], v[100:103], v[32:35]
	v_mfma_f32_16x16x32_bf16 v[36:39], v[12:15], v[108:111], v[36:39]
	v_mfma_f32_16x16x32_bf16 v[40:43], v[72:75], v[108:111], v[40:43]
	s_barrier
	s_mov_b32 m0, s93
	v_lshl_add_u64 v[158:159], s[60:61], 0, v[114:115]
	global_load_lds_dwordx4 v[158:159], off
	v_lshl_add_u64 v[170:171], s[60:61], 0, v[118:119]
	s_mov_b32 m0, s94
	s_nop 0
	global_load_lds_dwordx4 v[170:171], off
	s_barrier
	s_waitcnt lgkmcnt(0)
	s_setprio 1
	s_setprio 0
	s_mov_b32 m0, s19
	v_lshl_add_u64 v[172:173], s[62:63], 0, v[112:113]
	s_barrier
	ds_read_b128 v[76:79], v155 offset:16384
	ds_read_b128 v[84:87], v155 offset:17408
	ds_read_b128 v[88:91], v155 offset:18432
	ds_read_b128 v[92:95], v155 offset:19456
	ds_read_b128 v[96:99], v155 offset:20480
	ds_read_b128 v[100:103], v155 offset:21504
	ds_read_b128 v[104:107], v155 offset:22528
	ds_read_b128 v[108:111], v155 offset:23552
	global_load_lds_dwordx4 v[172:173], off
	v_lshl_add_u64 v[176:177], s[62:63], 0, v[116:117]
	s_mov_b32 m0, s20
	s_nop 0
	global_load_lds_dwordx4 v[176:177], off
	s_barrier
	s_waitcnt lgkmcnt(0)
	v_mfma_f32_16x16x32_bf16 v[52:55], v[8:11], v[88:91], v[52:55]
	v_mfma_f32_16x16x32_bf16 v[80:83], v[8:11], v[76:79], v[80:83]
	v_mfma_f32_16x16x32_bf16 v[44:47], v[68:71], v[76:79], v[44:47]
	v_mfma_f32_16x16x32_bf16 v[76:79], v[12:15], v[92:95], v[52:55]
	v_mfma_f32_16x16x32_bf16 v[52:55], v[68:71], v[88:91], v[56:59]
	v_mfma_f32_16x16x32_bf16 v[56:59], v[72:75], v[92:95], v[52:55]
	v_mfma_f32_16x16x32_bf16 v[52:55], v[8:11], v[96:99], v[60:63]
	v_mfma_f32_16x16x32_bf16 v[60:63], v[12:15], v[100:103], v[52:55]
	v_mfma_f32_16x16x32_bf16 v[52:55], v[68:71], v[96:99], v[64:67]
	v_mfma_f32_16x16x32_bf16 v[0:3], v[8:11], v[104:107], v[0:3]
	v_mfma_f32_16x16x32_bf16 v[4:7], v[68:71], v[104:107], v[4:7]
	v_mfma_f32_16x16x32_bf16 v[80:83], v[12:15], v[84:87], v[80:83]
	v_mfma_f32_16x16x32_bf16 v[44:47], v[72:75], v[84:87], v[44:47]
	v_mfma_f32_16x16x32_bf16 v[64:67], v[72:75], v[100:103], v[52:55]
	v_mfma_f32_16x16x32_bf16 v[0:3], v[12:15], v[108:111], v[0:3]
	v_mfma_f32_16x16x32_bf16 v[4:7], v[72:75], v[108:111], v[4:7]
	s_barrier
	s_add_u32 s6, s60, 0x10000
	s_addc_u32 s7, s61, 0
	s_mov_b32 m0, s21
	v_lshl_add_u64 v[8:9], s[6:7], 0, v[114:115]
	global_load_lds_dwordx4 v[8:9], off
	v_lshl_add_u64 v[8:9], s[6:7], 0, v[118:119]
	s_mov_b32 m0, s26
	s_nop 0
	global_load_lds_dwordx4 v[8:9], off
	s_waitcnt vmcnt(6)
	s_barrier
	s_setprio 1
	s_setprio 0
	s_barrier
	ds_read_b128 v[84:87], v161
	ds_read_b128 v[88:91], v161 offset:1024
	ds_read_b128 v[100:103], v161 offset:2048
	ds_read_b128 v[104:107], v161 offset:3072
	s_add_u32 s6, s62, 0x10000
	s_addc_u32 s7, s63, 0
	s_mov_b32 m0, s27
	v_lshl_add_u64 v[68:69], s[6:7], 0, v[112:113]
	ds_read_b128 v[8:11], v155 offset:32768
	ds_read_b128 v[12:15], v155 offset:33792
	ds_read_b128 v[52:55], v155 offset:34816
	ds_read_b128 v[72:75], v155 offset:35840
	ds_read_b128 v[108:111], v155 offset:36864
	ds_read_b128 v[150:153], v155 offset:37888
	ds_read_b128 v[162:165], v155 offset:38912
	ds_read_b128 v[166:169], v155 offset:39936
	global_load_lds_dwordx4 v[68:69], off
	v_lshl_add_u64 v[68:69], s[6:7], 0, v[116:117]
	s_mov_b32 m0, s28
	s_nop 0
	global_load_lds_dwordx4 v[68:69], off
	s_waitcnt lgkmcnt(8)
	s_barrier
	s_waitcnt lgkmcnt(0)
	v_mfma_f32_16x16x32_bf16 v[48:51], v[84:87], v[8:11], v[48:51]
	v_mfma_f32_16x16x32_bf16 v[8:11], v[100:103], v[8:11], v[16:19]
	v_mfma_f32_16x16x32_bf16 v[96:99], v[104:107], v[12:15], v[8:11]
	v_mfma_f32_16x16x32_bf16 v[8:11], v[84:87], v[52:55], v[20:23]
	v_mfma_f32_16x16x32_bf16 v[68:71], v[88:91], v[72:75], v[8:11]
	v_mfma_f32_16x16x32_bf16 v[8:11], v[100:103], v[52:55], v[24:27]
	v_mfma_f32_16x16x32_bf16 v[72:75], v[104:107], v[72:75], v[8:11]
	v_mfma_f32_16x16x32_bf16 v[8:11], v[84:87], v[108:111], v[28:31]
	v_mfma_f32_16x16x32_bf16 v[92:95], v[88:91], v[12:15], v[48:51]
	v_mfma_f32_16x16x32_bf16 v[48:51], v[88:91], v[150:153], v[8:11]
	v_mfma_f32_16x16x32_bf16 v[8:11], v[100:103], v[108:111], v[32:35]
	v_mfma_f32_16x16x32_bf16 v[52:55], v[104:107], v[150:153], v[8:11]
	v_mfma_f32_16x16x32_bf16 v[8:11], v[84:87], v[162:165], v[36:39]
	v_mfma_f32_16x16x32_bf16 v[32:35], v[88:91], v[166:169], v[8:11]
	v_mfma_f32_16x16x32_bf16 v[8:11], v[100:103], v[162:165], v[40:43]
	v_mfma_f32_16x16x32_bf16 v[36:39], v[104:107], v[166:169], v[8:11]
	s_barrier
	s_mov_b32 m0, s97
	s_nop 3
	v_lshl_add_u64 v[8:9], v[158:159], 0, s[16:17]
	global_load_lds_dwordx4 v[8:9], off
	v_lshl_add_u64 v[8:9], v[170:171], 0, s[16:17]
	s_mov_b32 m0, s18
	s_nop 0
	global_load_lds_dwordx4 v[8:9], off
	s_barrier
	s_waitcnt lgkmcnt(0)
	s_setprio 1
	s_setprio 0
	s_mov_b32 m0, s29
	v_lshl_add_u64 v[16:17], v[172:173], 0, s[16:17]
	s_barrier
	ds_read_b128 v[8:11], v155 offset:49152
	ds_read_b128 v[12:15], v155 offset:50176
	ds_read_b128 v[20:23], v155 offset:51200
	ds_read_b128 v[40:43], v155 offset:52224
	ds_read_b128 v[108:111], v155 offset:53248
	ds_read_b128 v[150:153], v155 offset:54272
	ds_read_b128 v[162:165], v155 offset:55296
	ds_read_b128 v[166:169], v155 offset:56320
	global_load_lds_dwordx4 v[16:17], off
	v_lshl_add_u64 v[16:17], v[176:177], 0, s[16:17]
	s_mov_b32 m0, s30
	s_nop 0
	global_load_lds_dwordx4 v[16:17], off
	s_barrier
	s_waitcnt lgkmcnt(0)
	v_mfma_f32_16x16x32_bf16 v[16:19], v[84:87], v[8:11], v[80:83]
	v_mfma_f32_16x16x32_bf16 v[8:11], v[100:103], v[8:11], v[44:47]
	v_mfma_f32_16x16x32_bf16 v[28:31], v[104:107], v[12:15], v[8:11]
	v_mfma_f32_16x16x32_bf16 v[8:11], v[84:87], v[20:23], v[76:79]
	v_mfma_f32_16x16x32_bf16 v[24:27], v[88:91], v[12:15], v[16:19]
	v_mfma_f32_16x16x32_bf16 v[16:19], v[88:91], v[40:43], v[8:11]
	v_mfma_f32_16x16x32_bf16 v[8:11], v[100:103], v[20:23], v[56:59]
	v_mfma_f32_16x16x32_bf16 v[20:23], v[104:107], v[40:43], v[8:11]
	v_mfma_f32_16x16x32_bf16 v[8:11], v[84:87], v[108:111], v[60:63]
	v_mfma_f32_16x16x32_bf16 v[12:15], v[100:103], v[108:111], v[64:67]
	v_mfma_f32_16x16x32_bf16 v[0:3], v[84:87], v[162:165], v[0:3]
	v_mfma_f32_16x16x32_bf16 v[4:7], v[100:103], v[162:165], v[4:7]
	v_mfma_f32_16x16x32_bf16 v[8:11], v[88:91], v[150:153], v[8:11]
	v_mfma_f32_16x16x32_bf16 v[12:15], v[104:107], v[150:153], v[12:15]
	v_mfma_f32_16x16x32_bf16 v[0:3], v[88:91], v[166:169], v[0:3]
	v_mfma_f32_16x16x32_bf16 v[4:7], v[104:107], v[166:169], v[4:7]
	s_barrier
	s_add_u32 s6, s60, 0x10080
	s_addc_u32 s7, s61, 0
	s_mov_b32 m0, s31
	v_lshl_add_u64 v[40:41], s[6:7], 0, v[114:115]
	global_load_lds_dwordx4 v[40:41], off
	v_lshl_add_u64 v[40:41], s[6:7], 0, v[118:119]
	s_mov_b32 m0, s33
	s_nop 0
	global_load_lds_dwordx4 v[40:41], off
	s_waitcnt vmcnt(6)
	s_barrier
	s_setprio 1
	s_setprio 0
	s_barrier
	global_load_dwordx4 v[88:91], v[136:137], off offset:48
	global_load_dwordx4 v[100:103], v[136:137], off offset:32
	global_load_dwordx4 v[104:107], v[136:137], off offset:16
	global_load_dwordx4 v[108:111], v[136:137], off
	global_load_dwordx4 v[64:67], v[138:139], off offset:48
	global_load_dwordx4 v[76:79], v[138:139], off offset:32
	global_load_dwordx4 v[80:83], v[138:139], off offset:16
	global_load_dwordx4 v[84:87], v[138:139], off
	global_load_dwordx4 v[40:43], v[140:141], off offset:48
	global_load_dwordx4 v[44:47], v[140:141], off offset:32
	global_load_dwordx4 v[56:59], v[140:141], off offset:16
	global_load_dwordx4 v[60:63], v[140:141], off
	s_cmp_lt_u32 s8, 16
	s_cselect_b64 s[10:11], -1, 0
	s_and_b64 s[60:61], s[22:23], s[10:11]
	v_cndmask_b32_e64 v150, 0, 1, s[60:61]
	v_cmp_ne_u32_e64 s[6:7], 1, v150
	s_andn2_b64 vcc, exec, s[60:61]
	s_cbranch_vccnz .LBB0_734
	v_and_b32_e32 v151, 64, v156
	v_xor_b32_e32 v150, 16, v156
	v_add_u32_e32 v151, 64, v151
	v_cmp_lt_i32_e32 vcc, v150, v151
	s_nop 1
	v_cndmask_b32_e32 v150, v156, v150, vcc
	v_lshlrev_b32_e32 v157, 2, v150
	ds_bpermute_b32 v152, v157, v92
	ds_bpermute_b32 v150, v157, v96
	ds_bpermute_b32 v153, v157, v93
	ds_bpermute_b32 v151, v157, v97
	ds_bpermute_b32 v161, v157, v94
	ds_bpermute_b32 v158, v157, v98
	ds_bpermute_b32 v159, v157, v95
	ds_bpermute_b32 v157, v157, v99
	s_and_saveexec_b64 s[60:61], s[0:1]
	s_cbranch_execz .LBB0_733
	global_load_dwordx4 v[162:165], v[134:135], off offset:48
	global_load_dwordx4 v[166:169], v[134:135], off offset:32
	global_load_dwordx4 v[170:173], v[134:135], off offset:16
	global_load_dwordx4 v[180:183], v[134:135], off
	s_waitcnt lgkmcnt(0)
	v_pk_mul_f32 v[152:153], v[124:125], v[152:153]
	v_mul_f32_e32 v158, v124, v158
	v_mul_f32_e32 v161, v124, v161
	v_pk_mul_f32 v[150:151], v[124:125], v[150:151]
	s_waitcnt vmcnt(0)
	v_mul_f32_e32 v98, v98, v162
	v_mul_f32_e32 v158, v163, v158
	v_mul_f32_e32 v163, v124, v157
	v_mov_b32_e32 v177, v182
	v_mov_b32_e32 v182, v181
	v_mov_b32_e32 v176, v180
	v_pk_mul_f32 v[152:153], v[182:183], v[152:153]
	v_mul_f32_e32 v181, v124, v159
	v_mov_b32_e32 v180, v95
	v_mov_b32_e32 v162, v99
	v_pk_mul_f32 v[172:173], v[172:173], v[180:181]
	v_pk_fma_f32 v[92:93], v[92:93], v[176:177], v[152:153]
	v_mov_b32_e32 v153, v168
	v_mov_b32_e32 v168, v167
	v_pk_mul_f32 v[162:163], v[164:165], v[162:163]
	v_mul_f32_e32 v94, v94, v170
	v_mul_f32_e32 v170, v171, v161
	v_mov_b32_e32 v95, v172
	v_mov_b32_e32 v171, v173
	v_mov_b32_e32 v152, v166
	v_pk_mul_f32 v[150:151], v[168:169], v[150:151]
	v_mov_b32_e32 v99, v162
	v_mov_b32_e32 v159, v163
	v_pk_add_f32 v[94:95], v[94:95], v[170:171]
	v_pk_fma_f32 v[96:97], v[96:97], v[152:153], v[150:151]
	v_pk_add_f32 v[98:99], v[98:99], v[158:159]

.LBB0_1268:
	ds_read_b128 v[140:143], v149
	ds_read_b128 v[152:155], v149 offset:1024
	ds_read_b128 v[156:159], v149 offset:2048
	ds_read_b128 v[160:163], v149 offset:3072
	s_add_u32 s22, s10, 0xfffe0080
	s_addc_u32 s23, s11, -1
	s_cmp_eq_u32 s44, 4
	s_cselect_b32 s25, s13, s23
	s_cselect_b32 s24, s40, s22
	s_cselect_b32 s23, s15, s43
	s_cselect_b32 s22, s41, s42
	v_lshl_add_u64 v[144:145], s[10:11], 0, v[136:137]
	s_add_i32 m0, s1, 0xc000
	ds_read_b128 v[164:167], v150
	ds_read_b128 v[168:171], v150 offset:1024
	ds_read_b128 v[172:175], v150 offset:2048
	ds_read_b128 v[180:183], v150 offset:3072
	ds_read_b128 v[184:187], v150 offset:4096
	ds_read_b128 v[188:191], v150 offset:5120
	ds_read_b128 v[192:195], v150 offset:6144
	ds_read_b128 v[196:199], v150 offset:7168
	global_load_lds_dwordx4 v[144:145], off
	v_lshl_add_u64 v[144:145], s[10:11], 0, v[138:139]
	s_add_i32 m0, s1, 0xe000
	s_nop 0
	global_load_lds_dwordx4 v[144:145], off
	s_waitcnt lgkmcnt(8)
	s_barrier
	s_waitcnt lgkmcnt(0)
	v_mfma_f32_16x16x32_bf16 v[124:127], v[140:143], v[164:167], v[124:127]
	v_mfma_f32_16x16x32_bf16 v[120:123], v[156:159], v[164:167], v[120:123]
	v_mfma_f32_16x16x32_bf16 v[112:115], v[140:143], v[172:175], v[112:115]
	v_mfma_f32_16x16x32_bf16 v[104:107], v[156:159], v[172:175], v[104:107]
	v_mfma_f32_16x16x32_bf16 v[96:99], v[140:143], v[184:187], v[96:99]
	v_mfma_f32_16x16x32_bf16 v[88:91], v[156:159], v[184:187], v[88:91]
	v_mfma_f32_16x16x32_bf16 v[80:83], v[140:143], v[192:195], v[80:83]
	v_mfma_f32_16x16x32_bf16 v[72:75], v[156:159], v[192:195], v[72:75]
	v_mfma_f32_16x16x32_bf16 v[124:127], v[152:155], v[168:171], v[124:127]
	v_mfma_f32_16x16x32_bf16 v[120:123], v[160:163], v[168:171], v[120:123]
	v_mfma_f32_16x16x32_bf16 v[112:115], v[152:155], v[180:183], v[112:115]
	v_mfma_f32_16x16x32_bf16 v[104:107], v[160:163], v[180:183], v[104:107]
	v_mfma_f32_16x16x32_bf16 v[96:99], v[152:155], v[188:191], v[96:99]
	v_mfma_f32_16x16x32_bf16 v[88:91], v[160:163], v[188:191], v[88:91]
	v_mfma_f32_16x16x32_bf16 v[80:83], v[152:155], v[196:199], v[80:83]
	v_mfma_f32_16x16x32_bf16 v[72:75], v[160:163], v[196:199], v[72:75]
	s_barrier
	s_add_i32 s45, s35, s27
	v_lshl_add_u64 v[144:145], s[22:23], 0, v[132:133]
	s_mov_b32 m0, s45
	ds_read_b128 v[200:203], v151
	ds_read_b128 v[204:207], v151 offset:1024
	ds_read_b128 v[208:211], v151 offset:2048
	ds_read_b128 v[212:215], v151 offset:3072
	global_load_lds_dwordx4 v[144:145], off
	v_lshl_add_u64 v[176:177], s[22:23], 0, v[128:129]
	s_add_i32 m0, s45, 0x2000
	s_nop 0
	global_load_lds_dwordx4 v[176:177], off
	s_barrier
	s_waitcnt lgkmcnt(0)
	v_mfma_f32_16x16x32_bf16 v[116:119], v[200:203], v[164:167], v[116:119]
	v_mfma_f32_16x16x32_bf16 v[108:111], v[208:211], v[164:167], v[108:111]
	v_mfma_f32_16x16x32_bf16 v[100:103], v[200:203], v[172:175], v[100:103]
	v_mfma_f32_16x16x32_bf16 v[92:95], v[208:211], v[172:175], v[92:95]
	v_mfma_f32_16x16x32_bf16 v[84:87], v[200:203], v[184:187], v[84:87]
	v_mfma_f32_16x16x32_bf16 v[76:79], v[208:211], v[184:187], v[76:79]
	v_mfma_f32_16x16x32_bf16 v[68:71], v[200:203], v[192:195], v[68:71]
	v_mfma_f32_16x16x32_bf16 v[64:67], v[208:211], v[192:195], v[64:67]
	v_mfma_f32_16x16x32_bf16 v[116:119], v[204:207], v[168:171], v[116:119]
	v_mfma_f32_16x16x32_bf16 v[108:111], v[212:215], v[168:171], v[108:111]
	v_mfma_f32_16x16x32_bf16 v[100:103], v[204:207], v[180:183], v[100:103]
	v_mfma_f32_16x16x32_bf16 v[92:95], v[212:215], v[180:183], v[92:95]
	v_mfma_f32_16x16x32_bf16 v[84:87], v[204:207], v[188:191], v[84:87]
	v_mfma_f32_16x16x32_bf16 v[76:79], v[212:215], v[188:191], v[76:79]
	v_mfma_f32_16x16x32_bf16 v[68:71], v[204:207], v[196:199], v[68:71]
	v_mfma_f32_16x16x32_bf16 v[64:67], v[212:215], v[196:199], v[64:67]
	s_mov_b32 m0, s1
	v_lshl_add_u64 v[216:217], s[24:25], 0, v[134:135]
	s_barrier
	ds_read_b128 v[164:167], v150 offset:16384
	ds_read_b128 v[168:171], v150 offset:17408
	ds_read_b128 v[172:175], v150 offset:18432
	ds_read_b128 v[180:183], v150 offset:19456
	ds_read_b128 v[184:187], v150 offset:20480
	ds_read_b128 v[188:191], v150 offset:21504
	ds_read_b128 v[192:195], v150 offset:22528
	ds_read_b128 v[196:199], v150 offset:23552
	global_load_lds_dwordx4 v[216:217], off
	v_lshl_add_u64 v[218:219], s[24:25], 0, v[130:131]
	s_mov_b32 m0, s7
	s_nop 0
	global_load_lds_dwordx4 v[218:219], off
	s_barrier
	s_waitcnt lgkmcnt(0)
	v_mfma_f32_16x16x32_bf16 v[60:63], v[140:143], v[164:167], v[60:63]
	v_mfma_f32_16x16x32_bf16 v[56:59], v[156:159], v[164:167], v[56:59]
	v_mfma_f32_16x16x32_bf16 v[48:51], v[140:143], v[172:175], v[48:51]
	v_mfma_f32_16x16x32_bf16 v[40:43], v[156:159], v[172:175], v[40:43]
	v_mfma_f32_16x16x32_bf16 v[32:35], v[140:143], v[184:187], v[32:35]
	v_mfma_f32_16x16x32_bf16 v[24:27], v[156:159], v[184:187], v[24:27]
	v_mfma_f32_16x16x32_bf16 v[16:19], v[140:143], v[192:195], v[16:19]
	v_mfma_f32_16x16x32_bf16 v[8:11], v[156:159], v[192:195], v[8:11]
	v_mfma_f32_16x16x32_bf16 v[60:63], v[152:155], v[168:171], v[60:63]
	v_mfma_f32_16x16x32_bf16 v[56:59], v[160:163], v[168:171], v[56:59]
	v_mfma_f32_16x16x32_bf16 v[48:51], v[152:155], v[180:183], v[48:51]
	v_mfma_f32_16x16x32_bf16 v[40:43], v[160:163], v[180:183], v[40:43]
	v_mfma_f32_16x16x32_bf16 v[32:35], v[152:155], v[188:191], v[32:35]
	v_mfma_f32_16x16x32_bf16 v[24:27], v[160:163], v[188:191], v[24:27]
	v_mfma_f32_16x16x32_bf16 v[16:19], v[152:155], v[196:199], v[16:19]
	v_mfma_f32_16x16x32_bf16 v[8:11], v[160:163], v[196:199], v[8:11]
	s_barrier
	s_add_u32 s46, s22, 0x20000
	s_addc_u32 s47, s23, 0
	s_add_i32 s45, s36, s27
	v_lshl_add_u64 v[140:141], s[46:47], 0, v[132:133]
	s_mov_b32 m0, s45
	s_nop 0
	global_load_lds_dwordx4 v[140:141], off
	v_lshl_add_u64 v[140:141], s[46:47], 0, v[128:129]
	s_add_i32 m0, s45, 0x2000
	s_nop 0
	global_load_lds_dwordx4 v[140:141], off
	s_waitcnt vmcnt(6)
	s_barrier
	v_mfma_f32_16x16x32_bf16 v[52:55], v[200:203], v[164:167], v[52:55]
	v_mfma_f32_16x16x32_bf16 v[44:47], v[208:211], v[164:167], v[44:47]
	v_mfma_f32_16x16x32_bf16 v[36:39], v[200:203], v[172:175], v[36:39]
	v_mfma_f32_16x16x32_bf16 v[28:31], v[208:211], v[172:175], v[28:31]
	v_mfma_f32_16x16x32_bf16 v[20:23], v[200:203], v[184:187], v[20:23]
	v_mfma_f32_16x16x32_bf16 v[12:15], v[208:211], v[184:187], v[12:15]
	v_mfma_f32_16x16x32_bf16 v[4:7], v[200:203], v[192:195], v[4:7]
	v_mfma_f32_16x16x32_bf16 v[0:3], v[208:211], v[192:195], v[0:3]
	v_mfma_f32_16x16x32_bf16 v[52:55], v[204:207], v[168:171], v[52:55]
	v_mfma_f32_16x16x32_bf16 v[44:47], v[212:215], v[168:171], v[44:47]
	v_mfma_f32_16x16x32_bf16 v[36:39], v[204:207], v[180:183], v[36:39]
	v_mfma_f32_16x16x32_bf16 v[28:31], v[212:215], v[180:183], v[28:31]
	v_mfma_f32_16x16x32_bf16 v[20:23], v[204:207], v[188:191], v[20:23]
	v_mfma_f32_16x16x32_bf16 v[12:15], v[212:215], v[188:191], v[12:15]
	v_mfma_f32_16x16x32_bf16 v[4:7], v[204:207], v[196:199], v[4:7]
	v_mfma_f32_16x16x32_bf16 v[0:3], v[212:215], v[196:199], v[0:3]
	s_add_i32 s45, 0, 0x18000
	v_add_u32_e32 v160, s45, v147
	s_barrier
	ds_read_b128 v[140:143], v160
	ds_read_b128 v[152:155], v160 offset:1024
	ds_read_b128 v[156:159], v160 offset:2048
	ds_read_b128 v[160:163], v160 offset:3072
	s_add_u32 s24, s24, 0x20000
	s_addc_u32 s25, s25, 0
	s_mov_b32 m0, s28
	v_lshl_add_u64 v[200:201], s[24:25], 0, v[134:135]
	ds_read_b128 v[164:167], v150 offset:32768
	ds_read_b128 v[168:171], v150 offset:33792
	ds_read_b128 v[172:175], v150 offset:34816
	ds_read_b128 v[180:183], v150 offset:35840
	ds_read_b128 v[184:187], v150 offset:36864
	ds_read_b128 v[188:191], v150 offset:37888
	ds_read_b128 v[192:195], v150 offset:38912
	ds_read_b128 v[196:199], v150 offset:39936
	global_load_lds_dwordx4 v[200:201], off
	v_lshl_add_u64 v[200:201], s[24:25], 0, v[130:131]
	s_mov_b32 m0, s29
	s_nop 0
	global_load_lds_dwordx4 v[200:201], off
	s_waitcnt lgkmcnt(8)
	s_barrier
	s_waitcnt lgkmcnt(0)
	v_mfma_f32_16x16x32_bf16 v[124:127], v[140:143], v[164:167], v[124:127]
	v_mfma_f32_16x16x32_bf16 v[120:123], v[156:159], v[164:167], v[120:123]
	v_mfma_f32_16x16x32_bf16 v[112:115], v[140:143], v[172:175], v[112:115]
	v_mfma_f32_16x16x32_bf16 v[104:107], v[156:159], v[172:175], v[104:107]
	v_mfma_f32_16x16x32_bf16 v[96:99], v[140:143], v[184:187], v[96:99]
	v_mfma_f32_16x16x32_bf16 v[88:91], v[156:159], v[184:187], v[88:91]
	v_mfma_f32_16x16x32_bf16 v[80:83], v[140:143], v[192:195], v[80:83]
	v_mfma_f32_16x16x32_bf16 v[72:75], v[156:159], v[192:195], v[72:75]
	v_mfma_f32_16x16x32_bf16 v[124:127], v[152:155], v[168:171], v[124:127]
	v_mfma_f32_16x16x32_bf16 v[120:123], v[160:163], v[168:171], v[120:123]
	v_mfma_f32_16x16x32_bf16 v[112:115], v[152:155], v[180:183], v[112:115]
	v_mfma_f32_16x16x32_bf16 v[104:107], v[160:163], v[180:183], v[104:107]
	v_mfma_f32_16x16x32_bf16 v[96:99], v[152:155], v[188:191], v[96:99]
	v_mfma_f32_16x16x32_bf16 v[88:91], v[160:163], v[188:191], v[88:91]
	v_mfma_f32_16x16x32_bf16 v[80:83], v[152:155], v[196:199], v[80:83]
	v_mfma_f32_16x16x32_bf16 v[72:75], v[160:163], v[196:199], v[72:75]
	s_barrier
	s_add_i32 s24, 0, 0x1c000
	s_add_i32 s25, s45, s27
	v_add_u32_e32 v179, s24, v147
	v_lshl_add_u64 v[144:145], v[144:145], 0, s[2:3]
	s_mov_b32 m0, s25
	ds_read_b128 v[200:203], v179
	ds_read_b128 v[204:207], v179 offset:1024
	ds_read_b128 v[208:211], v179 offset:2048
	ds_read_b128 v[212:215], v179 offset:3072
	global_load_lds_dwordx4 v[144:145], off
	v_lshl_add_u64 v[144:145], v[176:177], 0, s[2:3]
	s_add_i32 m0, s25, 0x2000
	s_nop 0
	global_load_lds_dwordx4 v[144:145], off
	s_barrier
	s_waitcnt lgkmcnt(0)
	v_mfma_f32_16x16x32_bf16 v[116:119], v[200:203], v[164:167], v[116:119]
	v_mfma_f32_16x16x32_bf16 v[108:111], v[208:211], v[164:167], v[108:111]
	v_mfma_f32_16x16x32_bf16 v[100:103], v[200:203], v[172:175], v[100:103]
	v_mfma_f32_16x16x32_bf16 v[92:95], v[208:211], v[172:175], v[92:95]
	v_mfma_f32_16x16x32_bf16 v[84:87], v[200:203], v[184:187], v[84:87]
	v_mfma_f32_16x16x32_bf16 v[76:79], v[208:211], v[184:187], v[76:79]
	v_mfma_f32_16x16x32_bf16 v[68:71], v[200:203], v[192:195], v[68:71]
	v_mfma_f32_16x16x32_bf16 v[64:67], v[208:211], v[192:195], v[64:67]
	v_mfma_f32_16x16x32_bf16 v[116:119], v[204:207], v[168:171], v[116:119]
	v_mfma_f32_16x16x32_bf16 v[108:111], v[212:215], v[168:171], v[108:111]
	v_mfma_f32_16x16x32_bf16 v[100:103], v[204:207], v[180:183], v[100:103]
	v_mfma_f32_16x16x32_bf16 v[92:95], v[212:215], v[180:183], v[92:95]
	v_mfma_f32_16x16x32_bf16 v[84:87], v[204:207], v[188:191], v[84:87]
	v_mfma_f32_16x16x32_bf16 v[76:79], v[212:215], v[188:191], v[76:79]
	v_mfma_f32_16x16x32_bf16 v[68:71], v[204:207], v[196:199], v[68:71]
	v_mfma_f32_16x16x32_bf16 v[64:67], v[212:215], v[196:199], v[64:67]
	s_mov_b32 m0, s31
	v_lshl_add_u64 v[144:145], v[216:217], 0, s[2:3]
	s_barrier
	ds_read_b128 v[164:167], v150 offset:49152
	ds_read_b128 v[168:171], v150 offset:50176
	ds_read_b128 v[172:175], v150 offset:51200
	ds_read_b128 v[180:183], v150 offset:52224
	ds_read_b128 v[184:187], v150 offset:53248
	ds_read_b128 v[188:191], v150 offset:54272
	ds_read_b128 v[192:195], v150 offset:55296
	ds_read_b128 v[196:199], v150 offset:56320
	global_load_lds_dwordx4 v[144:145], off
	v_lshl_add_u64 v[144:145], v[218:219], 0, s[2:3]
	s_mov_b32 m0, s33
	s_nop 0
	global_load_lds_dwordx4 v[144:145], off
	s_barrier
	s_waitcnt lgkmcnt(0)
	v_mfma_f32_16x16x32_bf16 v[60:63], v[140:143], v[164:167], v[60:63]
	v_mfma_f32_16x16x32_bf16 v[56:59], v[156:159], v[164:167], v[56:59]
	v_mfma_f32_16x16x32_bf16 v[48:51], v[140:143], v[172:175], v[48:51]
	v_mfma_f32_16x16x32_bf16 v[40:43], v[156:159], v[172:175], v[40:43]
	v_mfma_f32_16x16x32_bf16 v[32:35], v[140:143], v[184:187], v[32:35]
	v_mfma_f32_16x16x32_bf16 v[24:27], v[156:159], v[184:187], v[24:27]
	v_mfma_f32_16x16x32_bf16 v[16:19], v[140:143], v[192:195], v[16:19]
	v_mfma_f32_16x16x32_bf16 v[8:11], v[156:159], v[192:195], v[8:11]
	v_mfma_f32_16x16x32_bf16 v[60:63], v[152:155], v[168:171], v[60:63]
	v_mfma_f32_16x16x32_bf16 v[56:59], v[160:163], v[168:171], v[56:59]
	v_mfma_f32_16x16x32_bf16 v[48:51], v[152:155], v[180:183], v[48:51]
	v_mfma_f32_16x16x32_bf16 v[40:43], v[160:163], v[180:183], v[40:43]
	v_mfma_f32_16x16x32_bf16 v[32:35], v[152:155], v[188:191], v[32:35]
	v_mfma_f32_16x16x32_bf16 v[24:27], v[160:163], v[188:191], v[24:27]
	v_mfma_f32_16x16x32_bf16 v[16:19], v[152:155], v[196:199], v[16:19]
	v_mfma_f32_16x16x32_bf16 v[8:11], v[160:163], v[196:199], v[8:11]
	s_barrier
	s_add_u32 s22, s22, 0x20080
	s_addc_u32 s23, s23, 0
	s_add_i32 s24, s24, s27
	v_lshl_add_u64 v[140:141], s[22:23], 0, v[132:133]
	s_mov_b32 m0, s24
	s_nop 0
	global_load_lds_dwordx4 v[140:141], off
	v_lshl_add_u64 v[140:141], s[22:23], 0, v[128:129]
	s_add_i32 m0, s24, 0x2000
	s_nop 0
	global_load_lds_dwordx4 v[140:141], off
	s_waitcnt vmcnt(6)
	s_barrier
	v_mfma_f32_16x16x32_bf16 v[52:55], v[200:203], v[164:167], v[52:55]
	v_mfma_f32_16x16x32_bf16 v[44:47], v[208:211], v[164:167], v[44:47]
	v_mfma_f32_16x16x32_bf16 v[36:39], v[200:203], v[172:175], v[36:39]
	v_mfma_f32_16x16x32_bf16 v[28:31], v[208:211], v[172:175], v[28:31]
	v_mfma_f32_16x16x32_bf16 v[20:23], v[200:203], v[184:187], v[20:23]
	v_mfma_f32_16x16x32_bf16 v[12:15], v[208:211], v[184:187], v[12:15]
	v_mfma_f32_16x16x32_bf16 v[4:7], v[200:203], v[192:195], v[4:7]
	v_mfma_f32_16x16x32_bf16 v[0:3], v[208:211], v[192:195], v[0:3]
	v_mfma_f32_16x16x32_bf16 v[52:55], v[204:207], v[168:171], v[52:55]
	v_mfma_f32_16x16x32_bf16 v[44:47], v[212:215], v[168:171], v[44:47]
	v_mfma_f32_16x16x32_bf16 v[36:39], v[204:207], v[180:183], v[36:39]
	v_mfma_f32_16x16x32_bf16 v[28:31], v[212:215], v[180:183], v[28:31]
	v_mfma_f32_16x16x32_bf16 v[20:23], v[204:207], v[188:191], v[20:23]
	v_mfma_f32_16x16x32_bf16 v[12:15], v[212:215], v[188:191], v[12:15]
	v_mfma_f32_16x16x32_bf16 v[4:7], v[204:207], v[196:199], v[4:7]
	v_mfma_f32_16x16x32_bf16 v[0:3], v[212:215], v[196:199], v[0:3]
	s_add_i32 s44, s44, 2
	s_add_u32 s10, s10, 0x100
	s_addc_u32 s11, s11, 0
	s_add_u32 s42, s42, 0x100
	s_addc_u32 s43, s43, 0
	s_cmp_gt_u32 s44, 5
	s_barrier
	s_cbranch_scc0 .LBB0_1268
	v_lshl_add_u32 v142, s39, 8, v146
	s_nop 0
	v_lshl_or_b32 v140, s38, 8, v148
	v_ashrrev_i32_e32 v143, 31, v142
	s_nop 1
	v_readlane_b32 s46, v252, 13
	v_readlane_b32 s47, v252, 14
	v_ashrrev_i32_e32 v141, 31, v140
	v_lshlrev_b64 v[144:145], 12, v[142:143]
	s_mov_b64 s[42:43], s[46:47]
	v_lshl_add_u64 v[144:145], s[42:43], 0, v[144:145]
	v_lshlrev_b64 v[140:141], 1, v[140:141]
	v_or_b32_e32 v172, 16, v142
	v_lshl_add_u64 v[144:145], v[144:145], 0, v[140:141]
	v_ashrrev_i32_e32 v173, 31, v172
	global_load_dwordx4 v[152:155], v[144:145], off
	global_load_dwordx4 v[156:159], v[144:145], off offset:256
	v_lshlrev_b64 v[144:145], 12, v[172:173]
	v_lshl_add_u64 v[144:145], s[42:43], 0, v[144:145]
	v_lshl_add_u64 v[144:145], v[144:145], 0, v[140:141]
	global_load_dwordx4 v[160:163], v[144:145], off
	global_load_dwordx4 v[164:167], v[144:145], off offset:256
	v_or_b32_e32 v176, 32, v142
	v_ashrrev_i32_e32 v177, 31, v176
	v_lshlrev_b64 v[168:169], 12, v[176:177]
	v_lshl_add_u64 v[168:169], s[42:43], 0, v[168:169]
	v_lshl_add_u64 v[182:183], v[168:169], 0, v[140:141]
	global_load_dwordx4 v[168:171], v[182:183], off
	v_or_b32_e32 v144, 48, v142
	v_ashrrev_i32_e32 v145, 31, v144
	v_lshlrev_b64 v[180:181], 12, v[144:145]
	v_lshlrev_b64 v[174:175], 11, v[142:143]
	v_lshlrev_b64 v[172:173], 11, v[172:173]
	v_lshl_add_u64 v[180:181], s[42:43], 0, v[180:181]
	v_lshl_add_u64 v[174:175], s[82:83], 0, v[174:175]
	v_lshl_add_u64 v[172:173], s[82:83], 0, v[172:173]
	v_lshl_add_u64 v[184:185], v[180:181], 0, v[140:141]
	v_lshl_add_u64 v[188:189], v[174:175], 0, v[140:141]
	v_lshl_add_u64 v[190:191], v[172:173], 0, v[140:141]
	global_load_dwordx4 v[172:175], v[182:183], off offset:256
	s_nop 0
	global_load_dwordx4 v[180:183], v[184:185], off
	s_nop 0
	global_load_dwordx4 v[184:187], v[184:185], off offset:256
	v_add_u32_e32 v234, 0x80, v142
	v_ashrrev_i32_e32 v235, 31, v234
	v_lshlrev_b64 v[236:237], 12, v[234:235]
	v_lshl_add_u64 v[236:237], s[42:43], 0, v[236:237]
	v_lshl_add_u64 v[236:237], v[236:237], 0, v[140:141]
	global_load_dwordx4 v[200:203], v[236:237], off
	global_load_dwordx4 v[204:207], v[236:237], off offset:256
	v_add_u32_e32 v234, 0x90, v142
	v_ashrrev_i32_e32 v235, 31, v234
	v_lshlrev_b64 v[236:237], 12, v[234:235]
	v_lshl_add_u64 v[236:237], s[42:43], 0, v[236:237]
	v_lshl_add_u64 v[236:237], v[236:237], 0, v[140:141]
	global_load_dwordx4 v[208:211], v[236:237], off
	global_load_dwordx4 v[212:215], v[236:237], off offset:256
	v_add_u32_e32 v234, 0xa0, v142
	v_ashrrev_i32_e32 v235, 31, v234
	v_lshlrev_b64 v[236:237], 12, v[234:235]
	v_lshl_add_u64 v[236:237], s[42:43], 0, v[236:237]
	v_lshl_add_u64 v[236:237], v[236:237], 0, v[140:141]
	global_load_dwordx4 v[216:219], v[236:237], off
	global_load_dwordx4 v[222:225], v[236:237], off offset:256
	v_add_u32_e32 v234, 0xb0, v142
	v_ashrrev_i32_e32 v235, 31, v234
	v_lshlrev_b64 v[236:237], 12, v[234:235]
	v_lshl_add_u64 v[236:237], s[42:43], 0, v[236:237]
	v_lshl_add_u64 v[236:237], v[236:237], 0, v[140:141]
	global_load_dwordx4 v[226:229], v[236:237], off
	global_load_dwordx4 v[230:233], v[236:237], off offset:256
	s_and_b64 vcc, exec, s[18:19]
	s_mov_b32 s38, s14
	s_mov_b32 s39, s12
	s_mov_b32 s15, s14
	s_mov_b32 s18, s12
	s_mov_b64 s[22:23], s[20:21]
	s_mov_b64 s[10:11], s[16:17]
	s_mov_b32 s13, s37
	s_nop 7
	s_nop 2
	s_waitcnt vmcnt(8)
	v_lshlrev_b32_e32 v194, 16, v154
	v_and_b32_e32 v195, 0xffff0000, v154
	v_lshlrev_b32_e32 v154, 16, v155
	v_and_b32_e32 v155, 0xffff0000, v155
	v_lshlrev_b32_e32 v196, 16, v156
	v_and_b32_e32 v197, 0xffff0000, v156
	v_lshlrev_b32_e32 v156, 16, v157
	v_and_b32_e32 v157, 0xffff0000, v157
	v_lshlrev_b32_e32 v198, 16, v158
	v_and_b32_e32 v199, 0xffff0000, v158
	v_lshlrev_b32_e32 v158, 16, v159
	v_and_b32_e32 v159, 0xffff0000, v159
	v_lshlrev_b32_e32 v192, 16, v152
	v_and_b32_e32 v193, 0xffff0000, v152
	v_lshlrev_b32_e32 v152, 16, v153
	v_and_b32_e32 v153, 0xffff0000, v153
	v_pk_mul_f32 v[120:121], v[120:121], v[194:195]
	v_pk_mul_f32 v[122:123], v[122:123], v[154:155]
	v_pk_mul_f32 v[118:119], v[118:119], v[156:157]
	v_pk_mul_f32 v[154:155], v[110:111], v[158:159]
	v_lshlrev_b32_e32 v156, 16, v160
	v_and_b32_e32 v157, 0xffff0000, v160
	v_lshlrev_b32_e32 v158, 16, v161
	v_and_b32_e32 v159, 0xffff0000, v161
	v_lshlrev_b32_e32 v160, 16, v162
	v_and_b32_e32 v161, 0xffff0000, v162
	v_lshlrev_b32_e32 v162, 16, v163
	v_and_b32_e32 v163, 0xffff0000, v163
	v_pk_mul_f32 v[124:125], v[124:125], v[192:193]
	v_pk_mul_f32 v[126:127], v[126:127], v[152:153]
	v_cvt_pk_bf16_f32 v110, v120, v121
	v_cvt_pk_bf16_f32 v111, v122, v123
	v_pk_mul_f32 v[112:113], v[112:113], v[156:157]
	v_pk_mul_f32 v[114:115], v[114:115], v[158:159]
	v_pk_mul_f32 v[120:121], v[104:105], v[160:161]
	v_pk_mul_f32 v[122:123], v[106:107], v[162:163]
	v_pk_mul_f32 v[116:117], v[116:117], v[196:197]
	v_pk_mul_f32 v[152:153], v[108:109], v[198:199]
	v_cvt_pk_bf16_f32 v108, v124, v125
	v_cvt_pk_bf16_f32 v109, v126, v127
	v_cvt_pk_bf16_f32 v104, v112, v113
	v_cvt_pk_bf16_f32 v105, v114, v115
	v_cvt_pk_bf16_f32 v106, v120, v121
	v_cvt_pk_bf16_f32 v107, v122, v123
	v_cvt_pk_bf16_f32 v116, v116, v117
	v_cvt_pk_bf16_f32 v117, v118, v119
	v_cvt_pk_bf16_f32 v118, v152, v153
	v_cvt_pk_bf16_f32 v119, v154, v155
	global_store_dwordx4 v[188:189], v[108:111], off
	global_store_dwordx4 v[188:189], v[116:119], off offset:256
	global_store_dwordx4 v[190:191], v[104:107], off
	v_lshlrev_b32_e32 v192, 16, v164
	v_and_b32_e32 v193, 0xffff0000, v164
	v_lshlrev_b32_e32 v104, 16, v165
	v_and_b32_e32 v105, 0xffff0000, v165
	v_pk_mul_f32 v[102:103], v[102:103], v[104:105]
	v_lshlrev_b32_e32 v104, 16, v166
	v_and_b32_e32 v105, 0xffff0000, v166
	v_pk_mul_f32 v[104:105], v[92:93], v[104:105]
	v_lshlrev_b32_e32 v92, 16, v167
	v_and_b32_e32 v93, 0xffff0000, v167
	v_pk_mul_f32 v[100:101], v[100:101], v[192:193]
	v_pk_mul_f32 v[106:107], v[94:95], v[92:93]
	v_cvt_pk_bf16_f32 v92, v100, v101
	v_cvt_pk_bf16_f32 v93, v102, v103
	v_cvt_pk_bf16_f32 v94, v104, v105
	v_cvt_pk_bf16_f32 v95, v106, v107
	global_store_dwordx4 v[190:191], v[92:95], off offset:256
	v_add_u32_e32 v102, 0xb0, v142
	v_ashrrev_i32_e32 v103, 31, v102
	v_lshlrev_b32_e32 v94, 16, v168
	v_and_b32_e32 v95, 0xffff0000, v168
	v_pk_mul_f32 v[94:95], v[96:97], v[94:95]
	v_lshlrev_b32_e32 v96, 16, v169
	v_and_b32_e32 v97, 0xffff0000, v169
	v_pk_mul_f32 v[96:97], v[98:99], v[96:97]
	v_lshlrev_b32_e32 v98, 16, v170
	v_and_b32_e32 v99, 0xffff0000, v170
	v_lshlrev_b64 v[92:93], 11, v[176:177]
	v_pk_mul_f32 v[98:99], v[88:89], v[98:99]
	v_lshlrev_b32_e32 v88, 16, v171
	v_and_b32_e32 v89, 0xffff0000, v171
	v_pk_mul_f32 v[100:101], v[90:91], v[88:89]
	v_lshl_add_u64 v[92:93], s[82:83], 0, v[92:93]
	v_cvt_pk_bf16_f32 v88, v94, v95
	v_cvt_pk_bf16_f32 v89, v96, v97
	v_cvt_pk_bf16_f32 v90, v98, v99
	v_cvt_pk_bf16_f32 v91, v100, v101
	v_lshl_add_u64 v[92:93], v[92:93], 0, v[140:141]
	global_store_dwordx4 v[92:93], v[88:91], off
	v_add_u32_e32 v96, 0x80, v142
	v_ashrrev_i32_e32 v97, 31, v96
	v_lshlrev_b32_e32 v88, 16, v172
	v_and_b32_e32 v89, 0xffff0000, v172
	v_pk_mul_f32 v[84:85], v[84:85], v[88:89]
	v_lshlrev_b32_e32 v88, 16, v173
	v_and_b32_e32 v89, 0xffff0000, v173
	v_pk_mul_f32 v[86:87], v[86:87], v[88:89]
	v_lshlrev_b32_e32 v88, 16, v174
	v_and_b32_e32 v89, 0xffff0000, v174
	v_pk_mul_f32 v[88:89], v[76:77], v[88:89]
	v_lshlrev_b32_e32 v76, 16, v175
	v_and_b32_e32 v77, 0xffff0000, v175
	v_pk_mul_f32 v[90:91], v[78:79], v[76:77]
	v_cvt_pk_bf16_f32 v76, v84, v85
	v_cvt_pk_bf16_f32 v77, v86, v87
	v_cvt_pk_bf16_f32 v78, v88, v89
	v_cvt_pk_bf16_f32 v79, v90, v91
	global_store_dwordx4 v[92:93], v[76:79], off offset:256
	v_add_u32_e32 v98, 0x90, v142
	v_ashrrev_i32_e32 v99, 31, v98
	v_lshlrev_b32_e32 v78, 16, v180
	v_and_b32_e32 v79, 0xffff0000, v180
	v_pk_mul_f32 v[78:79], v[80:81], v[78:79]
	v_lshlrev_b32_e32 v80, 16, v181
	v_and_b32_e32 v81, 0xffff0000, v181
	v_pk_mul_f32 v[80:81], v[82:83], v[80:81]
	v_lshlrev_b32_e32 v82, 16, v182
	v_and_b32_e32 v83, 0xffff0000, v182
	v_lshlrev_b64 v[76:77], 11, v[144:145]
	v_pk_mul_f32 v[82:83], v[72:73], v[82:83]
	v_lshlrev_b32_e32 v72, 16, v183
	v_and_b32_e32 v73, 0xffff0000, v183
	v_pk_mul_f32 v[84:85], v[74:75], v[72:73]
	v_lshl_add_u64 v[76:77], s[82:83], 0, v[76:77]
	v_cvt_pk_bf16_f32 v72, v78, v79
	v_cvt_pk_bf16_f32 v73, v80, v81
	v_cvt_pk_bf16_f32 v74, v82, v83
	v_cvt_pk_bf16_f32 v75, v84, v85
	v_lshl_add_u64 v[76:77], v[76:77], 0, v[140:141]
	global_store_dwordx4 v[76:77], v[72:75], off
	v_add_u32_e32 v100, 0xa0, v142
	v_ashrrev_i32_e32 v101, 31, v100
	v_lshlrev_b32_e32 v72, 16, v184
	v_and_b32_e32 v73, 0xffff0000, v184
	v_pk_mul_f32 v[68:69], v[68:69], v[72:73]
	v_lshlrev_b32_e32 v72, 16, v185
	v_and_b32_e32 v73, 0xffff0000, v185
	v_pk_mul_f32 v[70:71], v[70:71], v[72:73]
	v_lshlrev_b32_e32 v72, 16, v186
	v_and_b32_e32 v73, 0xffff0000, v186
	v_pk_mul_f32 v[72:73], v[64:65], v[72:73]
	v_lshlrev_b32_e32 v64, 16, v187
	v_and_b32_e32 v65, 0xffff0000, v187
	v_pk_mul_f32 v[74:75], v[66:67], v[64:65]
	v_cvt_pk_bf16_f32 v64, v68, v69
	v_cvt_pk_bf16_f32 v65, v70, v71
	v_cvt_pk_bf16_f32 v66, v72, v73
	v_cvt_pk_bf16_f32 v67, v74, v75
	global_store_dwordx4 v[76:77], v[64:67], off offset:256
	s_nop 1
	v_lshlrev_b64 v[64:65], 12, v[96:97]
	v_lshl_add_u64 v[64:65], s[42:43], 0, v[64:65]
	v_lshl_add_u64 v[64:65], v[64:65], 0, v[140:141]
	v_lshlrev_b64 v[64:65], 12, v[98:99]
	v_lshl_add_u64 v[64:65], s[42:43], 0, v[64:65]
	v_lshl_add_u64 v[64:65], v[64:65], 0, v[140:141]
	v_lshlrev_b64 v[64:65], 12, v[100:101]
	v_lshl_add_u64 v[64:65], s[42:43], 0, v[64:65]
	v_lshl_add_u64 v[64:65], v[64:65], 0, v[140:141]
	v_lshlrev_b64 v[64:65], 12, v[102:103]
	v_lshl_add_u64 v[64:65], s[42:43], 0, v[64:65]
	v_lshl_add_u64 v[64:65], v[64:65], 0, v[140:141]
	s_nop 0
	v_lshlrev_b64 v[96:97], 11, v[96:97]
	s_waitcnt vmcnt(8)
	v_lshlrev_b32_e32 v104, 16, v200
	v_and_b32_e32 v105, 0xffff0000, v200
	v_lshlrev_b32_e32 v68, 16, v201
	v_and_b32_e32 v69, 0xffff0000, v201
	v_pk_mul_f32 v[62:63], v[62:63], v[68:69]
	v_lshlrev_b32_e32 v68, 16, v202
	v_and_b32_e32 v69, 0xffff0000, v202
	v_pk_mul_f32 v[60:61], v[60:61], v[104:105]
	v_pk_mul_f32 v[68:69], v[56:57], v[68:69]
	v_lshlrev_b32_e32 v56, 16, v203
	v_and_b32_e32 v57, 0xffff0000, v203
	v_pk_mul_f32 v[70:71], v[58:59], v[56:57]
	v_cvt_pk_bf16_f32 v56, v60, v61
	v_lshl_add_u64 v[60:61], s[82:83], 0, v[96:97]
	v_cvt_pk_bf16_f32 v57, v62, v63
	v_cvt_pk_bf16_f32 v58, v68, v69
	v_cvt_pk_bf16_f32 v59, v70, v71
	v_lshl_add_u64 v[60:61], v[60:61], 0, v[140:141]
	global_store_dwordx4 v[60:61], v[56:59], off
	s_nop 1
	v_lshlrev_b32_e32 v56, 16, v204
	v_and_b32_e32 v57, 0xffff0000, v204
	v_pk_mul_f32 v[52:53], v[52:53], v[56:57]
	v_lshlrev_b32_e32 v56, 16, v205
	v_and_b32_e32 v57, 0xffff0000, v205
	v_pk_mul_f32 v[54:55], v[54:55], v[56:57]
	v_lshlrev_b32_e32 v56, 16, v206
	v_and_b32_e32 v57, 0xffff0000, v206
	v_pk_mul_f32 v[56:57], v[44:45], v[56:57]
	v_lshlrev_b32_e32 v44, 16, v207
	v_and_b32_e32 v45, 0xffff0000, v207
	v_pk_mul_f32 v[58:59], v[46:47], v[44:45]
	v_cvt_pk_bf16_f32 v44, v52, v53
	v_cvt_pk_bf16_f32 v45, v54, v55
	v_cvt_pk_bf16_f32 v46, v56, v57
	v_cvt_pk_bf16_f32 v47, v58, v59
	global_store_dwordx4 v[60:61], v[44:47], off offset:256
	s_nop 1
	v_lshlrev_b32_e32 v46, 16, v208
	v_and_b32_e32 v47, 0xffff0000, v208
	v_pk_mul_f32 v[46:47], v[48:49], v[46:47]
	v_lshlrev_b32_e32 v48, 16, v209
	v_and_b32_e32 v49, 0xffff0000, v209
	v_pk_mul_f32 v[48:49], v[50:51], v[48:49]
	v_lshlrev_b32_e32 v50, 16, v210
	v_and_b32_e32 v51, 0xffff0000, v210
	v_lshlrev_b64 v[44:45], 11, v[98:99]
	v_pk_mul_f32 v[50:51], v[40:41], v[50:51]
	v_lshlrev_b32_e32 v40, 16, v211
	v_and_b32_e32 v41, 0xffff0000, v211
	v_pk_mul_f32 v[52:53], v[42:43], v[40:41]
	v_lshl_add_u64 v[44:45], s[82:83], 0, v[44:45]
	v_cvt_pk_bf16_f32 v40, v46, v47
	v_cvt_pk_bf16_f32 v41, v48, v49
	v_cvt_pk_bf16_f32 v42, v50, v51
	v_cvt_pk_bf16_f32 v43, v52, v53
	v_lshl_add_u64 v[44:45], v[44:45], 0, v[140:141]
	global_store_dwordx4 v[44:45], v[40:43], off
	s_nop 1
	v_lshlrev_b32_e32 v40, 16, v212
	v_and_b32_e32 v41, 0xffff0000, v212
	v_pk_mul_f32 v[36:37], v[36:37], v[40:41]
	v_lshlrev_b32_e32 v40, 16, v213
	v_and_b32_e32 v41, 0xffff0000, v213
	v_pk_mul_f32 v[38:39], v[38:39], v[40:41]
	v_lshlrev_b32_e32 v40, 16, v214
	v_and_b32_e32 v41, 0xffff0000, v214
	v_pk_mul_f32 v[40:41], v[28:29], v[40:41]
	v_lshlrev_b32_e32 v28, 16, v215
	v_and_b32_e32 v29, 0xffff0000, v215
	v_pk_mul_f32 v[42:43], v[30:31], v[28:29]
	v_cvt_pk_bf16_f32 v28, v36, v37
	v_cvt_pk_bf16_f32 v29, v38, v39
	v_cvt_pk_bf16_f32 v30, v40, v41
	v_cvt_pk_bf16_f32 v31, v42, v43
	global_store_dwordx4 v[44:45], v[28:31], off offset:256
	s_nop 1
	v_lshlrev_b32_e32 v30, 16, v216
	v_and_b32_e32 v31, 0xffff0000, v216
	v_pk_mul_f32 v[30:31], v[32:33], v[30:31]
	v_lshlrev_b32_e32 v32, 16, v217
	v_and_b32_e32 v33, 0xffff0000, v217
	v_pk_mul_f32 v[32:33], v[34:35], v[32:33]
	v_lshlrev_b32_e32 v34, 16, v218
	v_and_b32_e32 v35, 0xffff0000, v218
	v_lshlrev_b64 v[28:29], 11, v[100:101]
	v_pk_mul_f32 v[34:35], v[24:25], v[34:35]
	v_lshlrev_b32_e32 v24, 16, v219
	v_and_b32_e32 v25, 0xffff0000, v219
	v_pk_mul_f32 v[36:37], v[26:27], v[24:25]
	v_lshl_add_u64 v[28:29], s[82:83], 0, v[28:29]
	v_cvt_pk_bf16_f32 v24, v30, v31
	v_cvt_pk_bf16_f32 v25, v32, v33
	v_cvt_pk_bf16_f32 v26, v34, v35
	v_cvt_pk_bf16_f32 v27, v36, v37
	v_lshl_add_u64 v[28:29], v[28:29], 0, v[140:141]
	global_store_dwordx4 v[28:29], v[24:27], off
	s_nop 1
	v_lshlrev_b32_e32 v24, 16, v222
	v_and_b32_e32 v25, 0xffff0000, v222
	v_pk_mul_f32 v[20:21], v[20:21], v[24:25]
	v_lshlrev_b32_e32 v24, 16, v223
	v_and_b32_e32 v25, 0xffff0000, v223
	v_pk_mul_f32 v[22:23], v[22:23], v[24:25]
	v_lshlrev_b32_e32 v24, 16, v224
	v_and_b32_e32 v25, 0xffff0000, v224
	v_pk_mul_f32 v[24:25], v[12:13], v[24:25]
	v_lshlrev_b32_e32 v12, 16, v225
	v_and_b32_e32 v13, 0xffff0000, v225
	v_pk_mul_f32 v[26:27], v[14:15], v[12:13]
	v_cvt_pk_bf16_f32 v12, v20, v21
	v_cvt_pk_bf16_f32 v13, v22, v23
	v_cvt_pk_bf16_f32 v14, v24, v25
	v_cvt_pk_bf16_f32 v15, v26, v27
	global_store_dwordx4 v[28:29], v[12:15], off offset:256
	s_nop 1
	v_lshlrev_b32_e32 v14, 16, v226
	v_and_b32_e32 v15, 0xffff0000, v226
	v_pk_mul_f32 v[14:15], v[16:17], v[14:15]
	v_lshlrev_b32_e32 v16, 16, v227
	v_and_b32_e32 v17, 0xffff0000, v227
	v_pk_mul_f32 v[16:17], v[18:19], v[16:17]
	v_lshlrev_b32_e32 v18, 16, v228
	v_and_b32_e32 v19, 0xffff0000, v228
	v_lshlrev_b64 v[12:13], 11, v[102:103]
	v_pk_mul_f32 v[18:19], v[8:9], v[18:19]
	v_lshlrev_b32_e32 v8, 16, v229
	v_and_b32_e32 v9, 0xffff0000, v229
	v_pk_mul_f32 v[20:21], v[10:11], v[8:9]
	v_lshl_add_u64 v[12:13], s[82:83], 0, v[12:13]
	v_cvt_pk_bf16_f32 v8, v14, v15
	v_cvt_pk_bf16_f32 v9, v16, v17
	v_cvt_pk_bf16_f32 v10, v18, v19
	v_cvt_pk_bf16_f32 v11, v20, v21
	v_lshl_add_u64 v[12:13], v[12:13], 0, v[140:141]
	global_store_dwordx4 v[12:13], v[8:11], off
	s_nop 1
	v_lshlrev_b32_e32 v8, 16, v230
	v_and_b32_e32 v9, 0xffff0000, v230
	v_pk_mul_f32 v[4:5], v[4:5], v[8:9]
	v_lshlrev_b32_e32 v8, 16, v231
	v_and_b32_e32 v9, 0xffff0000, v231
	v_pk_mul_f32 v[6:7], v[6:7], v[8:9]
	v_lshlrev_b32_e32 v8, 16, v232
	v_and_b32_e32 v9, 0xffff0000, v232
	v_pk_mul_f32 v[8:9], v[0:1], v[8:9]
	v_lshlrev_b32_e32 v0, 16, v233
	v_and_b32_e32 v1, 0xffff0000, v233
	v_pk_mul_f32 v[10:11], v[2:3], v[0:1]
	v_cvt_pk_bf16_f32 v0, v4, v5
	v_cvt_pk_bf16_f32 v1, v6, v7
	v_cvt_pk_bf16_f32 v2, v8, v9
	v_cvt_pk_bf16_f32 v3, v10, v11
	global_store_dwordx4 v[12:13], v[0:3], off offset:256
	s_cbranch_vccz .LBB0_1260
	s_waitcnt vmcnt(0)
	s_cmpk_gt_u32 s26, 0xff
	s_cbranch_scc1 .LBB0_1272
	s_barrier

.LBB0_1285:
	ds_read_b128 v[128:131], v175
	ds_read_b128 v[132:135], v175 offset:1024
	ds_read_b128 v[136:139], v175 offset:2048
	ds_read_b128 v[140:143], v175 offset:3072
	s_add_u32 s22, s10, 0xfffe0080
	s_addc_u32 s23, s11, -1
	s_cmp_eq_u32 s43, 4
	s_cselect_b32 s25, s13, s23
	s_cselect_b32 s24, s39, s22
	s_cselect_b32 s23, s15, s42
	s_cselect_b32 s22, s40, s41
	v_lshl_add_u64 v[196:197], s[10:11], 0, v[160:161]
	s_add_i32 m0, s1, 0xc000
	ds_read_b128 v[144:147], v176
	ds_read_b128 v[148:151], v176 offset:1024
	ds_read_b128 v[164:167], v176 offset:2048
	ds_read_b128 v[168:171], v176 offset:3072
	ds_read_b128 v[180:183], v176 offset:4096
	ds_read_b128 v[184:187], v176 offset:5120
	ds_read_b128 v[188:191], v176 offset:6144
	ds_read_b128 v[192:195], v176 offset:7168
	global_load_lds_dwordx4 v[196:197], off
	v_lshl_add_u64 v[196:197], s[10:11], 0, v[162:163]
	s_add_i32 m0, s1, 0xe000
	s_nop 0
	global_load_lds_dwordx4 v[196:197], off
	s_waitcnt lgkmcnt(8)
	s_barrier
	s_waitcnt lgkmcnt(0)
	v_mfma_f32_16x16x32_bf16 v[124:127], v[128:131], v[144:147], v[124:127]
	v_mfma_f32_16x16x32_bf16 v[120:123], v[136:139], v[144:147], v[120:123]
	v_mfma_f32_16x16x32_bf16 v[108:111], v[128:131], v[164:167], v[108:111]
	v_mfma_f32_16x16x32_bf16 v[104:107], v[136:139], v[164:167], v[104:107]
	v_mfma_f32_16x16x32_bf16 v[92:95], v[128:131], v[180:183], v[92:95]
	v_mfma_f32_16x16x32_bf16 v[88:91], v[136:139], v[180:183], v[88:91]
	v_mfma_f32_16x16x32_bf16 v[76:79], v[128:131], v[188:191], v[76:79]
	v_mfma_f32_16x16x32_bf16 v[72:75], v[136:139], v[188:191], v[72:75]
	v_mfma_f32_16x16x32_bf16 v[124:127], v[132:135], v[148:151], v[124:127]
	v_mfma_f32_16x16x32_bf16 v[120:123], v[140:143], v[148:151], v[120:123]
	v_mfma_f32_16x16x32_bf16 v[108:111], v[132:135], v[168:171], v[108:111]
	v_mfma_f32_16x16x32_bf16 v[104:107], v[140:143], v[168:171], v[104:107]
	v_mfma_f32_16x16x32_bf16 v[92:95], v[132:135], v[184:187], v[92:95]
	v_mfma_f32_16x16x32_bf16 v[88:91], v[140:143], v[184:187], v[88:91]
	v_mfma_f32_16x16x32_bf16 v[76:79], v[132:135], v[192:195], v[76:79]
	v_mfma_f32_16x16x32_bf16 v[72:75], v[140:143], v[192:195], v[72:75]
	s_barrier
	s_add_i32 s44, s35, s27
	v_lshl_add_u64 v[212:213], s[22:23], 0, v[156:157]
	s_mov_b32 m0, s44
	ds_read_b128 v[196:199], v177
	ds_read_b128 v[200:203], v177 offset:1024
	ds_read_b128 v[204:207], v177 offset:2048
	ds_read_b128 v[208:211], v177 offset:3072
	global_load_lds_dwordx4 v[212:213], off
	v_lshl_add_u64 v[214:215], s[22:23], 0, v[152:153]
	s_add_i32 m0, s44, 0x2000
	s_nop 0
	global_load_lds_dwordx4 v[214:215], off
	s_barrier
	s_waitcnt lgkmcnt(0)
	v_mfma_f32_16x16x32_bf16 v[116:119], v[196:199], v[144:147], v[116:119]
	v_mfma_f32_16x16x32_bf16 v[112:115], v[204:207], v[144:147], v[112:115]
	v_mfma_f32_16x16x32_bf16 v[100:103], v[196:199], v[164:167], v[100:103]
	v_mfma_f32_16x16x32_bf16 v[96:99], v[204:207], v[164:167], v[96:99]
	v_mfma_f32_16x16x32_bf16 v[84:87], v[196:199], v[180:183], v[84:87]
	v_mfma_f32_16x16x32_bf16 v[80:83], v[204:207], v[180:183], v[80:83]
	v_mfma_f32_16x16x32_bf16 v[68:71], v[196:199], v[188:191], v[68:71]
	v_mfma_f32_16x16x32_bf16 v[64:67], v[204:207], v[188:191], v[64:67]
	v_mfma_f32_16x16x32_bf16 v[116:119], v[200:203], v[148:151], v[116:119]
	v_mfma_f32_16x16x32_bf16 v[112:115], v[208:211], v[148:151], v[112:115]
	v_mfma_f32_16x16x32_bf16 v[100:103], v[200:203], v[168:171], v[100:103]
	v_mfma_f32_16x16x32_bf16 v[96:99], v[208:211], v[168:171], v[96:99]
	v_mfma_f32_16x16x32_bf16 v[84:87], v[200:203], v[184:187], v[84:87]
	v_mfma_f32_16x16x32_bf16 v[80:83], v[208:211], v[184:187], v[80:83]
	v_mfma_f32_16x16x32_bf16 v[68:71], v[200:203], v[192:195], v[68:71]
	v_mfma_f32_16x16x32_bf16 v[64:67], v[208:211], v[192:195], v[64:67]
	s_mov_b32 m0, s1
	v_lshl_add_u64 v[216:217], s[24:25], 0, v[158:159]
	s_barrier
	ds_read_b128 v[144:147], v176 offset:16384
	ds_read_b128 v[148:151], v176 offset:17408
	ds_read_b128 v[164:167], v176 offset:18432
	ds_read_b128 v[168:171], v176 offset:19456
	ds_read_b128 v[180:183], v176 offset:20480
	ds_read_b128 v[184:187], v176 offset:21504
	ds_read_b128 v[188:191], v176 offset:22528
	ds_read_b128 v[192:195], v176 offset:23552
	global_load_lds_dwordx4 v[216:217], off
	v_lshl_add_u64 v[218:219], s[24:25], 0, v[154:155]
	s_mov_b32 m0, s7
	s_nop 0
	global_load_lds_dwordx4 v[218:219], off
	s_barrier
	s_waitcnt lgkmcnt(0)
	v_mfma_f32_16x16x32_bf16 v[60:63], v[128:131], v[144:147], v[60:63]
	v_mfma_f32_16x16x32_bf16 v[56:59], v[136:139], v[144:147], v[56:59]
	v_mfma_f32_16x16x32_bf16 v[44:47], v[128:131], v[164:167], v[44:47]
	v_mfma_f32_16x16x32_bf16 v[40:43], v[136:139], v[164:167], v[40:43]
	v_mfma_f32_16x16x32_bf16 v[28:31], v[128:131], v[180:183], v[28:31]
	v_mfma_f32_16x16x32_bf16 v[24:27], v[136:139], v[180:183], v[24:27]
	v_mfma_f32_16x16x32_bf16 v[12:15], v[128:131], v[188:191], v[12:15]
	v_mfma_f32_16x16x32_bf16 v[8:11], v[136:139], v[188:191], v[8:11]
	v_mfma_f32_16x16x32_bf16 v[60:63], v[132:135], v[148:151], v[60:63]
	v_mfma_f32_16x16x32_bf16 v[56:59], v[140:143], v[148:151], v[56:59]
	v_mfma_f32_16x16x32_bf16 v[44:47], v[132:135], v[168:171], v[44:47]
	v_mfma_f32_16x16x32_bf16 v[40:43], v[140:143], v[168:171], v[40:43]
	v_mfma_f32_16x16x32_bf16 v[28:31], v[132:135], v[184:187], v[28:31]
	v_mfma_f32_16x16x32_bf16 v[24:27], v[140:143], v[184:187], v[24:27]
	v_mfma_f32_16x16x32_bf16 v[12:15], v[132:135], v[192:195], v[12:15]
	v_mfma_f32_16x16x32_bf16 v[8:11], v[140:143], v[192:195], v[8:11]
	s_barrier
	s_add_u32 s44, s22, 0x20000
	s_addc_u32 s45, s23, 0
	s_add_i32 s46, s36, s27
	v_lshl_add_u64 v[128:129], s[44:45], 0, v[156:157]
	s_mov_b32 m0, s46
	s_nop 0
	global_load_lds_dwordx4 v[128:129], off
	v_lshl_add_u64 v[128:129], s[44:45], 0, v[152:153]
	s_add_i32 m0, s46, 0x2000
	s_nop 0
	global_load_lds_dwordx4 v[128:129], off
	s_waitcnt vmcnt(6)
	s_barrier
	v_mfma_f32_16x16x32_bf16 v[52:55], v[196:199], v[144:147], v[52:55]
	v_mfma_f32_16x16x32_bf16 v[48:51], v[204:207], v[144:147], v[48:51]
	v_mfma_f32_16x16x32_bf16 v[36:39], v[196:199], v[164:167], v[36:39]
	v_mfma_f32_16x16x32_bf16 v[32:35], v[204:207], v[164:167], v[32:35]
	v_mfma_f32_16x16x32_bf16 v[20:23], v[196:199], v[180:183], v[20:23]
	v_mfma_f32_16x16x32_bf16 v[16:19], v[204:207], v[180:183], v[16:19]
	v_mfma_f32_16x16x32_bf16 v[4:7], v[196:199], v[188:191], v[4:7]
	v_mfma_f32_16x16x32_bf16 v[0:3], v[204:207], v[188:191], v[0:3]
	v_mfma_f32_16x16x32_bf16 v[52:55], v[200:203], v[148:151], v[52:55]
	v_mfma_f32_16x16x32_bf16 v[48:51], v[208:211], v[148:151], v[48:51]
	v_mfma_f32_16x16x32_bf16 v[36:39], v[200:203], v[168:171], v[36:39]
	v_mfma_f32_16x16x32_bf16 v[32:35], v[208:211], v[168:171], v[32:35]
	v_mfma_f32_16x16x32_bf16 v[20:23], v[200:203], v[184:187], v[20:23]
	v_mfma_f32_16x16x32_bf16 v[16:19], v[208:211], v[184:187], v[16:19]
	v_mfma_f32_16x16x32_bf16 v[4:7], v[200:203], v[192:195], v[4:7]
	v_mfma_f32_16x16x32_bf16 v[0:3], v[208:211], v[192:195], v[0:3]
	s_add_i32 s44, 0, 0x18000
	v_add_u32_e32 v140, s44, v173
	s_barrier
	ds_read_b128 v[128:131], v140
	ds_read_b128 v[132:135], v140 offset:1024
	ds_read_b128 v[136:139], v140 offset:2048
	ds_read_b128 v[140:143], v140 offset:3072
	s_add_u32 s24, s24, 0x20000
	s_addc_u32 s25, s25, 0
	s_mov_b32 m0, s28
	v_lshl_add_u64 v[196:197], s[24:25], 0, v[158:159]
	ds_read_b128 v[144:147], v176 offset:32768
	ds_read_b128 v[148:151], v176 offset:33792
	ds_read_b128 v[164:167], v176 offset:34816
	ds_read_b128 v[168:171], v176 offset:35840
	ds_read_b128 v[180:183], v176 offset:36864
	ds_read_b128 v[184:187], v176 offset:37888
	ds_read_b128 v[188:191], v176 offset:38912
	ds_read_b128 v[192:195], v176 offset:39936
	global_load_lds_dwordx4 v[196:197], off
	v_lshl_add_u64 v[196:197], s[24:25], 0, v[154:155]
	s_mov_b32 m0, s29
	s_nop 0
	global_load_lds_dwordx4 v[196:197], off
	s_waitcnt lgkmcnt(8)
	s_barrier
	s_waitcnt lgkmcnt(0)
	v_mfma_f32_16x16x32_bf16 v[124:127], v[128:131], v[144:147], v[124:127]
	v_mfma_f32_16x16x32_bf16 v[120:123], v[136:139], v[144:147], v[120:123]
	v_mfma_f32_16x16x32_bf16 v[108:111], v[128:131], v[164:167], v[108:111]
	v_mfma_f32_16x16x32_bf16 v[104:107], v[136:139], v[164:167], v[104:107]
	v_mfma_f32_16x16x32_bf16 v[92:95], v[128:131], v[180:183], v[92:95]
	v_mfma_f32_16x16x32_bf16 v[88:91], v[136:139], v[180:183], v[88:91]
	v_mfma_f32_16x16x32_bf16 v[76:79], v[128:131], v[188:191], v[76:79]
	v_mfma_f32_16x16x32_bf16 v[72:75], v[136:139], v[188:191], v[72:75]
	v_mfma_f32_16x16x32_bf16 v[124:127], v[132:135], v[148:151], v[124:127]
	v_mfma_f32_16x16x32_bf16 v[120:123], v[140:143], v[148:151], v[120:123]
	v_mfma_f32_16x16x32_bf16 v[108:111], v[132:135], v[168:171], v[108:111]
	v_mfma_f32_16x16x32_bf16 v[104:107], v[140:143], v[168:171], v[104:107]
	v_mfma_f32_16x16x32_bf16 v[92:95], v[132:135], v[184:187], v[92:95]
	v_mfma_f32_16x16x32_bf16 v[88:91], v[140:143], v[184:187], v[88:91]
	v_mfma_f32_16x16x32_bf16 v[76:79], v[132:135], v[192:195], v[76:79]
	v_mfma_f32_16x16x32_bf16 v[72:75], v[140:143], v[192:195], v[72:75]
	s_barrier
	s_add_i32 s24, 0, 0x1c000
	s_add_i32 s25, s44, s27
	v_add_u32_e32 v179, s24, v173
	v_lshl_add_u64 v[212:213], v[212:213], 0, s[4:5]
	s_mov_b32 m0, s25
	ds_read_b128 v[196:199], v179
	ds_read_b128 v[200:203], v179 offset:1024
	ds_read_b128 v[204:207], v179 offset:2048
	ds_read_b128 v[208:211], v179 offset:3072
	global_load_lds_dwordx4 v[212:213], off
	v_lshl_add_u64 v[212:213], v[214:215], 0, s[4:5]
	s_add_i32 m0, s25, 0x2000
	s_nop 0
	global_load_lds_dwordx4 v[212:213], off
	s_barrier
	s_waitcnt lgkmcnt(0)
	v_mfma_f32_16x16x32_bf16 v[116:119], v[196:199], v[144:147], v[116:119]
	v_mfma_f32_16x16x32_bf16 v[112:115], v[204:207], v[144:147], v[112:115]
	v_mfma_f32_16x16x32_bf16 v[100:103], v[196:199], v[164:167], v[100:103]
	v_mfma_f32_16x16x32_bf16 v[96:99], v[204:207], v[164:167], v[96:99]
	v_mfma_f32_16x16x32_bf16 v[84:87], v[196:199], v[180:183], v[84:87]
	v_mfma_f32_16x16x32_bf16 v[80:83], v[204:207], v[180:183], v[80:83]
	v_mfma_f32_16x16x32_bf16 v[68:71], v[196:199], v[188:191], v[68:71]
	v_mfma_f32_16x16x32_bf16 v[64:67], v[204:207], v[188:191], v[64:67]
	v_mfma_f32_16x16x32_bf16 v[116:119], v[200:203], v[148:151], v[116:119]
	v_mfma_f32_16x16x32_bf16 v[112:115], v[208:211], v[148:151], v[112:115]
	v_mfma_f32_16x16x32_bf16 v[100:103], v[200:203], v[168:171], v[100:103]
	v_mfma_f32_16x16x32_bf16 v[96:99], v[208:211], v[168:171], v[96:99]
	v_mfma_f32_16x16x32_bf16 v[84:87], v[200:203], v[184:187], v[84:87]
	v_mfma_f32_16x16x32_bf16 v[80:83], v[208:211], v[184:187], v[80:83]
	v_mfma_f32_16x16x32_bf16 v[68:71], v[200:203], v[192:195], v[68:71]
	v_mfma_f32_16x16x32_bf16 v[64:67], v[208:211], v[192:195], v[64:67]
	s_mov_b32 m0, s31
	v_lshl_add_u64 v[212:213], v[216:217], 0, s[4:5]
	s_barrier
	ds_read_b128 v[144:147], v176 offset:49152
	ds_read_b128 v[148:151], v176 offset:50176
	ds_read_b128 v[164:167], v176 offset:51200
	ds_read_b128 v[168:171], v176 offset:52224
	ds_read_b128 v[180:183], v176 offset:53248
	ds_read_b128 v[184:187], v176 offset:54272
	ds_read_b128 v[188:191], v176 offset:55296
	ds_read_b128 v[192:195], v176 offset:56320
	global_load_lds_dwordx4 v[212:213], off
	v_lshl_add_u64 v[212:213], v[218:219], 0, s[4:5]
	s_mov_b32 m0, s33
	s_nop 0
	global_load_lds_dwordx4 v[212:213], off
	s_barrier
	s_waitcnt lgkmcnt(0)
	v_mfma_f32_16x16x32_bf16 v[60:63], v[128:131], v[144:147], v[60:63]
	v_mfma_f32_16x16x32_bf16 v[56:59], v[136:139], v[144:147], v[56:59]
	v_mfma_f32_16x16x32_bf16 v[44:47], v[128:131], v[164:167], v[44:47]
	v_mfma_f32_16x16x32_bf16 v[40:43], v[136:139], v[164:167], v[40:43]
	v_mfma_f32_16x16x32_bf16 v[28:31], v[128:131], v[180:183], v[28:31]
	v_mfma_f32_16x16x32_bf16 v[24:27], v[136:139], v[180:183], v[24:27]
	v_mfma_f32_16x16x32_bf16 v[12:15], v[128:131], v[188:191], v[12:15]
	v_mfma_f32_16x16x32_bf16 v[8:11], v[136:139], v[188:191], v[8:11]
	v_mfma_f32_16x16x32_bf16 v[60:63], v[132:135], v[148:151], v[60:63]
	v_mfma_f32_16x16x32_bf16 v[56:59], v[140:143], v[148:151], v[56:59]
	v_mfma_f32_16x16x32_bf16 v[44:47], v[132:135], v[168:171], v[44:47]
	v_mfma_f32_16x16x32_bf16 v[40:43], v[140:143], v[168:171], v[40:43]
	v_mfma_f32_16x16x32_bf16 v[28:31], v[132:135], v[184:187], v[28:31]
	v_mfma_f32_16x16x32_bf16 v[24:27], v[140:143], v[184:187], v[24:27]
	v_mfma_f32_16x16x32_bf16 v[12:15], v[132:135], v[192:195], v[12:15]
	v_mfma_f32_16x16x32_bf16 v[8:11], v[140:143], v[192:195], v[8:11]
	s_barrier
	s_add_u32 s22, s22, 0x20080
	s_addc_u32 s23, s23, 0
	s_add_i32 s24, s24, s27
	v_lshl_add_u64 v[128:129], s[22:23], 0, v[156:157]
	s_mov_b32 m0, s24
	s_nop 0
	global_load_lds_dwordx4 v[128:129], off
	v_lshl_add_u64 v[128:129], s[22:23], 0, v[152:153]
	s_add_i32 m0, s24, 0x2000
	s_nop 0
	global_load_lds_dwordx4 v[128:129], off
	s_waitcnt vmcnt(6)
	s_barrier
	v_mfma_f32_16x16x32_bf16 v[52:55], v[196:199], v[144:147], v[52:55]
	v_mfma_f32_16x16x32_bf16 v[48:51], v[204:207], v[144:147], v[48:51]
	v_mfma_f32_16x16x32_bf16 v[36:39], v[196:199], v[164:167], v[36:39]
	v_mfma_f32_16x16x32_bf16 v[32:35], v[204:207], v[164:167], v[32:35]
	v_mfma_f32_16x16x32_bf16 v[20:23], v[196:199], v[180:183], v[20:23]
	v_mfma_f32_16x16x32_bf16 v[16:19], v[204:207], v[180:183], v[16:19]
	v_mfma_f32_16x16x32_bf16 v[4:7], v[196:199], v[188:191], v[4:7]
	v_mfma_f32_16x16x32_bf16 v[0:3], v[204:207], v[188:191], v[0:3]
	v_mfma_f32_16x16x32_bf16 v[52:55], v[200:203], v[148:151], v[52:55]
	v_mfma_f32_16x16x32_bf16 v[48:51], v[208:211], v[148:151], v[48:51]
	v_mfma_f32_16x16x32_bf16 v[36:39], v[200:203], v[168:171], v[36:39]
	v_mfma_f32_16x16x32_bf16 v[32:35], v[208:211], v[168:171], v[32:35]
	v_mfma_f32_16x16x32_bf16 v[20:23], v[200:203], v[184:187], v[20:23]
	v_mfma_f32_16x16x32_bf16 v[16:19], v[208:211], v[184:187], v[16:19]
	v_mfma_f32_16x16x32_bf16 v[4:7], v[200:203], v[192:195], v[4:7]
	v_mfma_f32_16x16x32_bf16 v[0:3], v[208:211], v[192:195], v[0:3]
	s_add_i32 s43, s43, 2
	s_add_u32 s10, s10, 0x100
	s_addc_u32 s11, s11, 0
	s_add_u32 s41, s41, 0x100
	s_addc_u32 s42, s42, 0
	s_cmp_gt_u32 s43, 5
	s_barrier
	s_cbranch_scc0 .LBB0_1285
	v_lshl_add_u32 v164, s38, 8, v172
	s_nop 0
	v_lshl_or_b32 v128, s0, 8, v174
	v_ashrrev_i32_e32 v165, 31, v164
	s_nop 1
	v_readlane_b32 s46, v252, 13
	v_readlane_b32 s47, v252, 14
	v_ashrrev_i32_e32 v129, 31, v128
	v_lshlrev_b64 v[130:131], 12, v[164:165]
	s_mov_b64 s[42:43], s[46:47]
	v_lshl_add_u64 v[130:131], s[42:43], 0, v[130:131]
	v_lshlrev_b64 v[132:133], 11, v[164:165]
	v_lshlrev_b64 v[166:167], 1, v[128:129]
	v_lshl_add_u64 v[132:133], s[82:83], 0, v[132:133]
	v_lshl_add_u64 v[128:129], v[130:131], 0, v[166:167]
	global_load_dwordx4 v[180:183], v[128:129], off offset:2048
	v_lshl_add_u64 v[222:223], v[132:133], 0, v[166:167]
	global_load_dwordx4 v[184:187], v[222:223], off
	global_load_dwordx4 v[188:191], v[128:129], off offset:2304
	global_load_dwordx4 v[192:195], v[222:223], off offset:256
	v_or_b32_e32 v128, 16, v164
	v_ashrrev_i32_e32 v129, 31, v128
	v_lshlrev_b64 v[130:131], 12, v[128:129]
	v_lshlrev_b64 v[128:129], 11, v[128:129]
	v_lshl_add_u64 v[130:131], s[42:43], 0, v[130:131]
	v_lshl_add_u64 v[128:129], s[82:83], 0, v[128:129]
	v_lshl_add_u64 v[130:131], v[130:131], 0, v[166:167]
	v_lshl_add_u64 v[224:225], v[128:129], 0, v[166:167]
	global_load_dwordx4 v[196:199], v[130:131], off offset:2048
	global_load_dwordx4 v[200:203], v[224:225], off
	v_or_b32_e32 v128, 32, v164
	v_or_b32_e32 v132, 48, v164
	v_ashrrev_i32_e32 v129, 31, v128
	v_ashrrev_i32_e32 v133, 31, v132
	v_lshlrev_b64 v[134:135], 12, v[128:129]
	v_lshlrev_b64 v[128:129], 11, v[128:129]
	v_lshlrev_b64 v[136:137], 12, v[132:133]
	v_lshlrev_b64 v[132:133], 11, v[132:133]
	v_lshl_add_u64 v[134:135], s[42:43], 0, v[134:135]
	v_lshl_add_u64 v[128:129], s[82:83], 0, v[128:129]
	v_lshl_add_u64 v[136:137], s[42:43], 0, v[136:137]
	v_lshl_add_u64 v[132:133], s[82:83], 0, v[132:133]
	v_lshl_add_u64 v[134:135], v[134:135], 0, v[166:167]
	v_lshl_add_u64 v[170:171], v[128:129], 0, v[166:167]
	v_lshl_add_u64 v[128:129], v[136:137], 0, v[166:167]
	v_lshl_add_u64 v[168:169], v[132:133], 0, v[166:167]
	global_load_dwordx4 v[204:207], v[130:131], off offset:2304
	global_load_dwordx4 v[208:211], v[224:225], off offset:256
	global_load_dwordx4 v[212:215], v[134:135], off offset:2048
	global_load_dwordx4 v[148:151], v[134:135], off offset:2304
	global_load_dwordx4 v[216:219], v[170:171], off
	global_load_dwordx4 v[144:147], v[170:171], off offset:256
	global_load_dwordx4 v[140:143], v[128:129], off offset:2048
	s_nop 0
	global_load_dwordx4 v[132:135], v[128:129], off offset:2304
	global_load_dwordx4 v[136:139], v[168:169], off
	s_nop 0
	global_load_dwordx4 v[128:131], v[168:169], off offset:256
	s_and_b64 vcc, exec, s[18:19]
	s_mov_b32 s0, s14
	s_mov_b32 s38, s12
	s_mov_b32 s15, s14
	s_mov_b32 s18, s12
	s_mov_b64 s[22:23], s[20:21]
	s_mov_b64 s[10:11], s[16:17]
	s_mov_b32 s13, s37
	s_nop 7
	s_nop 2
	s_waitcnt vmcnt(0)
	v_lshlrev_b32_e32 v228, 16, v184
	v_lshlrev_b32_e32 v226, 16, v180
	v_and_b32_e32 v227, 0xffff0000, v180
	v_and_b32_e32 v229, 0xffff0000, v184
	v_lshlrev_b32_e32 v180, 16, v181
	v_and_b32_e32 v181, 0xffff0000, v181
	v_lshlrev_b32_e32 v184, 16, v185
	v_and_b32_e32 v185, 0xffff0000, v185
	v_lshlrev_b32_e32 v230, 16, v182
	v_and_b32_e32 v231, 0xffff0000, v182
	v_lshlrev_b32_e32 v232, 16, v186
	v_and_b32_e32 v233, 0xffff0000, v186
	v_lshlrev_b32_e32 v182, 16, v183
	v_and_b32_e32 v183, 0xffff0000, v183
	v_lshlrev_b32_e32 v186, 16, v187
	v_and_b32_e32 v187, 0xffff0000, v187
	v_lshlrev_b32_e32 v234, 16, v188
	v_and_b32_e32 v235, 0xffff0000, v188
	v_lshlrev_b32_e32 v236, 16, v192
	v_and_b32_e32 v237, 0xffff0000, v192
	v_lshlrev_b32_e32 v188, 16, v189
	v_and_b32_e32 v189, 0xffff0000, v189
	v_lshlrev_b32_e32 v192, 16, v193
	v_and_b32_e32 v193, 0xffff0000, v193
	v_pk_fma_f32 v[124:125], v[124:125], v[226:227], v[228:229]
	v_pk_fma_f32 v[126:127], v[126:127], v[180:181], v[184:185]
	v_pk_fma_f32 v[120:121], v[120:121], v[230:231], v[232:233]
	v_pk_fma_f32 v[122:123], v[122:123], v[182:183], v[186:187]
	v_lshlrev_b32_e32 v238, 16, v190
	v_and_b32_e32 v239, 0xffff0000, v190
	v_lshlrev_b32_e32 v240, 16, v194
	v_pk_fma_f32 v[180:181], v[116:117], v[234:235], v[236:237]
	v_pk_fma_f32 v[182:183], v[118:119], v[188:189], v[192:193]
	v_cvt_pk_bf16_f32 v116, v124, v125
	v_cvt_pk_bf16_f32 v117, v126, v127
	v_cvt_pk_bf16_f32 v118, v120, v121
	v_cvt_pk_bf16_f32 v119, v122, v123
	v_and_b32_e32 v241, 0xffff0000, v194
	global_store_dwordx4 v[222:223], v[116:119], off
	s_nop 1
	v_pk_fma_f32 v[116:117], v[112:113], v[238:239], v[240:241]
	v_lshlrev_b32_e32 v112, 16, v191
	v_and_b32_e32 v113, 0xffff0000, v191
	v_lshlrev_b32_e32 v118, 16, v195
	v_and_b32_e32 v119, 0xffff0000, v195
	v_pk_fma_f32 v[118:119], v[114:115], v[112:113], v[118:119]
	v_cvt_pk_bf16_f32 v112, v180, v181
	v_cvt_pk_bf16_f32 v113, v182, v183
	v_cvt_pk_bf16_f32 v114, v116, v117
	v_cvt_pk_bf16_f32 v115, v118, v119
	global_store_dwordx4 v[222:223], v[112:115], off offset:256
	s_nop 1
	v_lshlrev_b32_e32 v112, 16, v196
	v_and_b32_e32 v113, 0xffff0000, v196
	v_lshlrev_b32_e32 v114, 16, v200
	v_and_b32_e32 v115, 0xffff0000, v200
	v_pk_fma_f32 v[108:109], v[108:109], v[112:113], v[114:115]
	v_lshlrev_b32_e32 v112, 16, v197
	v_and_b32_e32 v113, 0xffff0000, v197
	v_lshlrev_b32_e32 v114, 16, v201
	v_and_b32_e32 v115, 0xffff0000, v201
	v_pk_fma_f32 v[110:111], v[110:111], v[112:113], v[114:115]
	v_lshlrev_b32_e32 v112, 16, v198
	v_and_b32_e32 v113, 0xffff0000, v198
	v_lshlrev_b32_e32 v114, 16, v202
	v_and_b32_e32 v115, 0xffff0000, v202
	v_pk_fma_f32 v[112:113], v[104:105], v[112:113], v[114:115]
	v_lshlrev_b32_e32 v104, 16, v199
	v_and_b32_e32 v105, 0xffff0000, v199
	v_lshlrev_b32_e32 v114, 16, v203
	v_and_b32_e32 v115, 0xffff0000, v203
	v_pk_fma_f32 v[114:115], v[106:107], v[104:105], v[114:115]
	v_cvt_pk_bf16_f32 v104, v108, v109
	v_cvt_pk_bf16_f32 v105, v110, v111
	v_cvt_pk_bf16_f32 v106, v112, v113
	v_cvt_pk_bf16_f32 v107, v114, v115
	global_store_dwordx4 v[224:225], v[104:107], off
	s_nop 1
	v_lshlrev_b32_e32 v104, 16, v204
	v_and_b32_e32 v105, 0xffff0000, v204
	v_lshlrev_b32_e32 v106, 16, v208
	v_and_b32_e32 v107, 0xffff0000, v208
	v_pk_fma_f32 v[100:101], v[100:101], v[104:105], v[106:107]
	v_lshlrev_b32_e32 v104, 16, v205
	v_and_b32_e32 v105, 0xffff0000, v205
	v_lshlrev_b32_e32 v106, 16, v209
	v_and_b32_e32 v107, 0xffff0000, v209
	v_pk_fma_f32 v[102:103], v[102:103], v[104:105], v[106:107]
	v_lshlrev_b32_e32 v104, 16, v206
	v_and_b32_e32 v105, 0xffff0000, v206
	v_lshlrev_b32_e32 v106, 16, v210
	v_and_b32_e32 v107, 0xffff0000, v210
	v_pk_fma_f32 v[104:105], v[96:97], v[104:105], v[106:107]
	v_lshlrev_b32_e32 v96, 16, v207
	v_and_b32_e32 v97, 0xffff0000, v207
	v_lshlrev_b32_e32 v106, 16, v211
	v_and_b32_e32 v107, 0xffff0000, v211
	v_pk_fma_f32 v[106:107], v[98:99], v[96:97], v[106:107]
	v_cvt_pk_bf16_f32 v96, v100, v101
	v_cvt_pk_bf16_f32 v97, v102, v103
	v_cvt_pk_bf16_f32 v98, v104, v105
	v_cvt_pk_bf16_f32 v99, v106, v107
	global_store_dwordx4 v[224:225], v[96:99], off offset:256
	s_nop 1
	v_lshlrev_b32_e32 v96, 16, v212
	v_and_b32_e32 v97, 0xffff0000, v212
	v_lshlrev_b32_e32 v98, 16, v216
	v_and_b32_e32 v99, 0xffff0000, v216
	v_pk_fma_f32 v[92:93], v[92:93], v[96:97], v[98:99]
	v_lshlrev_b32_e32 v96, 16, v213
	v_and_b32_e32 v97, 0xffff0000, v213
	v_lshlrev_b32_e32 v98, 16, v217
	v_and_b32_e32 v99, 0xffff0000, v217
	v_pk_fma_f32 v[94:95], v[94:95], v[96:97], v[98:99]
	v_lshlrev_b32_e32 v96, 16, v214
	v_and_b32_e32 v97, 0xffff0000, v214
	v_lshlrev_b32_e32 v98, 16, v218
	v_and_b32_e32 v99, 0xffff0000, v218
	v_pk_fma_f32 v[96:97], v[88:89], v[96:97], v[98:99]
	v_lshlrev_b32_e32 v88, 16, v215
	v_and_b32_e32 v89, 0xffff0000, v215
	v_lshlrev_b32_e32 v98, 16, v219
	v_and_b32_e32 v99, 0xffff0000, v219
	v_pk_fma_f32 v[98:99], v[90:91], v[88:89], v[98:99]
	v_cvt_pk_bf16_f32 v88, v92, v93
	v_cvt_pk_bf16_f32 v89, v94, v95
	v_cvt_pk_bf16_f32 v90, v96, v97
	v_cvt_pk_bf16_f32 v91, v98, v99
	global_store_dwordx4 v[170:171], v[88:91], off
	s_nop 1
	v_lshlrev_b32_e32 v88, 16, v148
	v_and_b32_e32 v89, 0xffff0000, v148
	v_lshlrev_b32_e32 v90, 16, v144
	v_and_b32_e32 v91, 0xffff0000, v144
	v_pk_fma_f32 v[84:85], v[84:85], v[88:89], v[90:91]
	v_lshlrev_b32_e32 v88, 16, v149
	v_and_b32_e32 v89, 0xffff0000, v149
	v_lshlrev_b32_e32 v90, 16, v145
	v_and_b32_e32 v91, 0xffff0000, v145
	v_pk_fma_f32 v[86:87], v[86:87], v[88:89], v[90:91]
	v_lshlrev_b32_e32 v88, 16, v150
	v_and_b32_e32 v89, 0xffff0000, v150
	v_lshlrev_b32_e32 v90, 16, v146
	v_and_b32_e32 v91, 0xffff0000, v146
	v_pk_fma_f32 v[88:89], v[80:81], v[88:89], v[90:91]
	v_lshlrev_b32_e32 v80, 16, v151
	v_and_b32_e32 v81, 0xffff0000, v151
	v_lshlrev_b32_e32 v90, 16, v147
	v_and_b32_e32 v91, 0xffff0000, v147
	v_pk_fma_f32 v[90:91], v[82:83], v[80:81], v[90:91]
	v_cvt_pk_bf16_f32 v80, v84, v85
	v_cvt_pk_bf16_f32 v81, v86, v87
	v_cvt_pk_bf16_f32 v82, v88, v89
	v_cvt_pk_bf16_f32 v83, v90, v91
	global_store_dwordx4 v[170:171], v[80:83], off offset:256
	s_nop 1
	v_lshlrev_b32_e32 v80, 16, v140
	v_and_b32_e32 v81, 0xffff0000, v140
	v_lshlrev_b32_e32 v82, 16, v136
	v_and_b32_e32 v83, 0xffff0000, v136
	v_pk_fma_f32 v[76:77], v[76:77], v[80:81], v[82:83]
	v_lshlrev_b32_e32 v80, 16, v141
	v_and_b32_e32 v81, 0xffff0000, v141
	v_lshlrev_b32_e32 v82, 16, v137
	v_and_b32_e32 v83, 0xffff0000, v137
	v_pk_fma_f32 v[78:79], v[78:79], v[80:81], v[82:83]
	v_lshlrev_b32_e32 v80, 16, v142
	v_and_b32_e32 v81, 0xffff0000, v142
	v_lshlrev_b32_e32 v82, 16, v138
	v_and_b32_e32 v83, 0xffff0000, v138
	v_pk_fma_f32 v[80:81], v[72:73], v[80:81], v[82:83]
	v_lshlrev_b32_e32 v72, 16, v143
	v_and_b32_e32 v73, 0xffff0000, v143
	v_lshlrev_b32_e32 v82, 16, v139
	v_and_b32_e32 v83, 0xffff0000, v139
	v_pk_fma_f32 v[82:83], v[74:75], v[72:73], v[82:83]
	v_cvt_pk_bf16_f32 v72, v76, v77
	v_cvt_pk_bf16_f32 v73, v78, v79
	v_cvt_pk_bf16_f32 v74, v80, v81
	v_cvt_pk_bf16_f32 v75, v82, v83
	global_store_dwordx4 v[168:169], v[72:75], off
	s_nop 1
	v_lshlrev_b32_e32 v72, 16, v132
	v_and_b32_e32 v73, 0xffff0000, v132
	v_lshlrev_b32_e32 v74, 16, v128
	v_and_b32_e32 v75, 0xffff0000, v128
	v_pk_fma_f32 v[68:69], v[68:69], v[72:73], v[74:75]
	v_lshlrev_b32_e32 v72, 16, v133
	v_and_b32_e32 v73, 0xffff0000, v133
	v_lshlrev_b32_e32 v74, 16, v129
	v_and_b32_e32 v75, 0xffff0000, v129
	v_pk_fma_f32 v[70:71], v[70:71], v[72:73], v[74:75]
	v_lshlrev_b32_e32 v72, 16, v134
	v_and_b32_e32 v73, 0xffff0000, v134
	v_lshlrev_b32_e32 v74, 16, v130
	v_and_b32_e32 v75, 0xffff0000, v130
	v_pk_fma_f32 v[72:73], v[64:65], v[72:73], v[74:75]
	v_lshlrev_b32_e32 v64, 16, v135
	v_and_b32_e32 v65, 0xffff0000, v135
	v_lshlrev_b32_e32 v74, 16, v131
	v_and_b32_e32 v75, 0xffff0000, v131
	v_pk_fma_f32 v[74:75], v[66:67], v[64:65], v[74:75]
	v_cvt_pk_bf16_f32 v64, v68, v69
	v_cvt_pk_bf16_f32 v65, v70, v71
	v_cvt_pk_bf16_f32 v66, v72, v73
	v_cvt_pk_bf16_f32 v67, v74, v75
	global_store_dwordx4 v[168:169], v[64:67], off offset:256
	s_nop 1
	v_add_u32_e32 v64, 0x80, v164
	v_ashrrev_i32_e32 v65, 31, v64
	v_lshlrev_b64 v[66:67], 12, v[64:65]
	v_lshl_add_u64 v[66:67], s[42:43], 0, v[66:67]
	v_lshlrev_b64 v[64:65], 11, v[64:65]
	v_lshl_add_u64 v[66:67], v[66:67], 0, v[166:167]
	v_lshl_add_u64 v[64:65], s[82:83], 0, v[64:65]
	global_load_dwordx4 v[92:95], v[66:67], off offset:2048
	v_lshl_add_u64 v[132:133], v[64:65], 0, v[166:167]
	global_load_dwordx4 v[96:99], v[132:133], off
	global_load_dwordx4 v[100:103], v[66:67], off offset:2304
	global_load_dwordx4 v[104:107], v[132:133], off offset:256
	v_add_u32_e32 v64, 0x90, v164
	v_ashrrev_i32_e32 v65, 31, v64
	v_lshlrev_b64 v[66:67], 12, v[64:65]
	v_lshl_add_u64 v[66:67], s[42:43], 0, v[66:67]
	v_lshlrev_b64 v[64:65], 11, v[64:65]
	v_lshl_add_u64 v[66:67], v[66:67], 0, v[166:167]
	v_lshl_add_u64 v[64:65], s[82:83], 0, v[64:65]
	global_load_dwordx4 v[108:111], v[66:67], off offset:2048
	v_lshl_add_u64 v[134:135], v[64:65], 0, v[166:167]
	global_load_dwordx4 v[112:115], v[134:135], off
	global_load_dwordx4 v[116:119], v[66:67], off offset:2304
	global_load_dwordx4 v[120:123], v[134:135], off offset:256
	v_add_u32_e32 v64, 0xa0, v164
	v_ashrrev_i32_e32 v65, 31, v64
	v_lshlrev_b64 v[66:67], 12, v[64:65]
	v_lshl_add_u64 v[66:67], s[42:43], 0, v[66:67]
	v_lshlrev_b64 v[64:65], 11, v[64:65]
	v_lshl_add_u64 v[64:65], s[82:83], 0, v[64:65]
	v_lshl_add_u64 v[66:67], v[66:67], 0, v[166:167]
	v_lshl_add_u64 v[90:91], v[64:65], 0, v[166:167]
	global_load_dwordx4 v[124:127], v[66:67], off offset:2048
	global_load_dwordx4 v[84:87], v[66:67], off offset:2304
	global_load_dwordx4 v[128:131], v[90:91], off
	global_load_dwordx4 v[80:83], v[90:91], off offset:256
	v_add_u32_e32 v64, 0xb0, v164
	v_ashrrev_i32_e32 v65, 31, v64
	v_lshlrev_b64 v[66:67], 12, v[64:65]
	v_lshl_add_u64 v[66:67], s[42:43], 0, v[66:67]
	v_lshlrev_b64 v[64:65], 11, v[64:65]
	v_lshl_add_u64 v[64:65], s[82:83], 0, v[64:65]
	v_lshl_add_u64 v[66:67], v[66:67], 0, v[166:167]
	v_lshl_add_u64 v[88:89], v[64:65], 0, v[166:167]
	global_load_dwordx4 v[76:79], v[66:67], off offset:2048
	global_load_dwordx4 v[68:71], v[66:67], off offset:2304
	global_load_dwordx4 v[72:75], v[88:89], off
	s_nop 0
	global_load_dwordx4 v[64:67], v[88:89], off offset:256
	s_waitcnt vmcnt(0)
	v_lshlrev_b32_e32 v136, 16, v92
	v_and_b32_e32 v137, 0xffff0000, v92
	v_lshlrev_b32_e32 v138, 16, v96
	v_and_b32_e32 v139, 0xffff0000, v96
	v_lshlrev_b32_e32 v92, 16, v93
	v_and_b32_e32 v93, 0xffff0000, v93
	v_lshlrev_b32_e32 v96, 16, v97
	v_and_b32_e32 v97, 0xffff0000, v97
	v_pk_fma_f32 v[62:63], v[62:63], v[92:93], v[96:97]
	v_lshlrev_b32_e32 v92, 16, v94
	v_and_b32_e32 v93, 0xffff0000, v94
	v_lshlrev_b32_e32 v96, 16, v98
	v_and_b32_e32 v97, 0xffff0000, v98
	v_pk_fma_f32 v[92:93], v[56:57], v[92:93], v[96:97]
	v_lshlrev_b32_e32 v56, 16, v95
	v_and_b32_e32 v57, 0xffff0000, v95
	v_lshlrev_b32_e32 v94, 16, v99
	v_and_b32_e32 v95, 0xffff0000, v99
	v_pk_fma_f32 v[60:61], v[60:61], v[136:137], v[138:139]
	v_pk_fma_f32 v[94:95], v[58:59], v[56:57], v[94:95]
	v_cvt_pk_bf16_f32 v56, v60, v61
	v_cvt_pk_bf16_f32 v57, v62, v63
	v_cvt_pk_bf16_f32 v58, v92, v93
	v_cvt_pk_bf16_f32 v59, v94, v95
	global_store_dwordx4 v[132:133], v[56:59], off
	s_nop 1
	v_lshlrev_b32_e32 v56, 16, v100
	v_and_b32_e32 v57, 0xffff0000, v100
	v_lshlrev_b32_e32 v58, 16, v104
	v_and_b32_e32 v59, 0xffff0000, v104
	v_pk_fma_f32 v[52:53], v[52:53], v[56:57], v[58:59]
	v_lshlrev_b32_e32 v56, 16, v101
	v_and_b32_e32 v57, 0xffff0000, v101
	v_lshlrev_b32_e32 v58, 16, v105
	v_and_b32_e32 v59, 0xffff0000, v105
	v_pk_fma_f32 v[54:55], v[54:55], v[56:57], v[58:59]
	v_lshlrev_b32_e32 v56, 16, v102
	v_and_b32_e32 v57, 0xffff0000, v102
	v_lshlrev_b32_e32 v58, 16, v106
	v_and_b32_e32 v59, 0xffff0000, v106
	v_pk_fma_f32 v[56:57], v[48:49], v[56:57], v[58:59]
	v_lshlrev_b32_e32 v48, 16, v103
	v_and_b32_e32 v49, 0xffff0000, v103
	v_lshlrev_b32_e32 v58, 16, v107
	v_and_b32_e32 v59, 0xffff0000, v107
	v_pk_fma_f32 v[58:59], v[50:51], v[48:49], v[58:59]
	v_cvt_pk_bf16_f32 v48, v52, v53
	v_cvt_pk_bf16_f32 v49, v54, v55
	v_cvt_pk_bf16_f32 v50, v56, v57
	v_cvt_pk_bf16_f32 v51, v58, v59
	global_store_dwordx4 v[132:133], v[48:51], off offset:256
	s_nop 1
	v_lshlrev_b32_e32 v48, 16, v108
	v_and_b32_e32 v49, 0xffff0000, v108
	v_lshlrev_b32_e32 v50, 16, v112
	v_and_b32_e32 v51, 0xffff0000, v112
	v_pk_fma_f32 v[44:45], v[44:45], v[48:49], v[50:51]
	v_lshlrev_b32_e32 v48, 16, v109
	v_and_b32_e32 v49, 0xffff0000, v109
	v_lshlrev_b32_e32 v50, 16, v113
	v_and_b32_e32 v51, 0xffff0000, v113
	v_pk_fma_f32 v[46:47], v[46:47], v[48:49], v[50:51]
	v_lshlrev_b32_e32 v48, 16, v110
	v_and_b32_e32 v49, 0xffff0000, v110
	v_lshlrev_b32_e32 v50, 16, v114
	v_and_b32_e32 v51, 0xffff0000, v114
	v_pk_fma_f32 v[48:49], v[40:41], v[48:49], v[50:51]
	v_lshlrev_b32_e32 v40, 16, v111
	v_and_b32_e32 v41, 0xffff0000, v111
	v_lshlrev_b32_e32 v50, 16, v115
	v_and_b32_e32 v51, 0xffff0000, v115
	v_pk_fma_f32 v[50:51], v[42:43], v[40:41], v[50:51]
	v_cvt_pk_bf16_f32 v40, v44, v45
	v_cvt_pk_bf16_f32 v41, v46, v47
	v_cvt_pk_bf16_f32 v42, v48, v49
	v_cvt_pk_bf16_f32 v43, v50, v51
	global_store_dwordx4 v[134:135], v[40:43], off
	s_nop 1
	v_lshlrev_b32_e32 v40, 16, v116
	v_and_b32_e32 v41, 0xffff0000, v116
	v_lshlrev_b32_e32 v42, 16, v120
	v_and_b32_e32 v43, 0xffff0000, v120
	v_pk_fma_f32 v[36:37], v[36:37], v[40:41], v[42:43]
	v_lshlrev_b32_e32 v40, 16, v117
	v_and_b32_e32 v41, 0xffff0000, v117
	v_lshlrev_b32_e32 v42, 16, v121
	v_and_b32_e32 v43, 0xffff0000, v121
	v_pk_fma_f32 v[38:39], v[38:39], v[40:41], v[42:43]
	v_lshlrev_b32_e32 v40, 16, v118
	v_and_b32_e32 v41, 0xffff0000, v118
	v_lshlrev_b32_e32 v42, 16, v122
	v_and_b32_e32 v43, 0xffff0000, v122
	v_pk_fma_f32 v[40:41], v[32:33], v[40:41], v[42:43]
	v_lshlrev_b32_e32 v32, 16, v119
	v_and_b32_e32 v33, 0xffff0000, v119
	v_lshlrev_b32_e32 v42, 16, v123
	v_and_b32_e32 v43, 0xffff0000, v123
	v_pk_fma_f32 v[42:43], v[34:35], v[32:33], v[42:43]
	v_cvt_pk_bf16_f32 v32, v36, v37
	v_cvt_pk_bf16_f32 v33, v38, v39
	v_cvt_pk_bf16_f32 v34, v40, v41
	v_cvt_pk_bf16_f32 v35, v42, v43
	global_store_dwordx4 v[134:135], v[32:35], off offset:256
	s_nop 1
	v_lshlrev_b32_e32 v32, 16, v124
	v_and_b32_e32 v33, 0xffff0000, v124
	v_lshlrev_b32_e32 v34, 16, v128
	v_and_b32_e32 v35, 0xffff0000, v128
	v_pk_fma_f32 v[28:29], v[28:29], v[32:33], v[34:35]
	v_lshlrev_b32_e32 v32, 16, v125
	v_and_b32_e32 v33, 0xffff0000, v125
	v_lshlrev_b32_e32 v34, 16, v129
	v_and_b32_e32 v35, 0xffff0000, v129
	v_pk_fma_f32 v[30:31], v[30:31], v[32:33], v[34:35]
	v_lshlrev_b32_e32 v32, 16, v126
	v_and_b32_e32 v33, 0xffff0000, v126
	v_lshlrev_b32_e32 v34, 16, v130
	v_and_b32_e32 v35, 0xffff0000, v130
	v_pk_fma_f32 v[32:33], v[24:25], v[32:33], v[34:35]
	v_lshlrev_b32_e32 v24, 16, v127
	v_and_b32_e32 v25, 0xffff0000, v127
	v_lshlrev_b32_e32 v34, 16, v131
	v_and_b32_e32 v35, 0xffff0000, v131
	v_pk_fma_f32 v[34:35], v[26:27], v[24:25], v[34:35]
	v_cvt_pk_bf16_f32 v24, v28, v29
	v_cvt_pk_bf16_f32 v25, v30, v31
	v_cvt_pk_bf16_f32 v26, v32, v33
	v_cvt_pk_bf16_f32 v27, v34, v35
	global_store_dwordx4 v[90:91], v[24:27], off
	s_nop 1
	v_lshlrev_b32_e32 v24, 16, v84
	v_and_b32_e32 v25, 0xffff0000, v84
	v_lshlrev_b32_e32 v26, 16, v80
	v_and_b32_e32 v27, 0xffff0000, v80
	v_pk_fma_f32 v[20:21], v[20:21], v[24:25], v[26:27]
	v_lshlrev_b32_e32 v24, 16, v85
	v_and_b32_e32 v25, 0xffff0000, v85
	v_lshlrev_b32_e32 v26, 16, v81
	v_and_b32_e32 v27, 0xffff0000, v81
	v_pk_fma_f32 v[22:23], v[22:23], v[24:25], v[26:27]
	v_lshlrev_b32_e32 v24, 16, v86
	v_and_b32_e32 v25, 0xffff0000, v86
	v_lshlrev_b32_e32 v26, 16, v82
	v_and_b32_e32 v27, 0xffff0000, v82
	v_pk_fma_f32 v[24:25], v[16:17], v[24:25], v[26:27]
	v_lshlrev_b32_e32 v16, 16, v87
	v_and_b32_e32 v17, 0xffff0000, v87
	v_lshlrev_b32_e32 v26, 16, v83
	v_and_b32_e32 v27, 0xffff0000, v83
	v_pk_fma_f32 v[26:27], v[18:19], v[16:17], v[26:27]
	v_cvt_pk_bf16_f32 v16, v20, v21
	v_cvt_pk_bf16_f32 v17, v22, v23
	v_cvt_pk_bf16_f32 v18, v24, v25
	v_cvt_pk_bf16_f32 v19, v26, v27
	global_store_dwordx4 v[90:91], v[16:19], off offset:256
	s_nop 1
	v_lshlrev_b32_e32 v16, 16, v76
	v_and_b32_e32 v17, 0xffff0000, v76
	v_lshlrev_b32_e32 v18, 16, v72
	v_and_b32_e32 v19, 0xffff0000, v72
	v_pk_fma_f32 v[12:13], v[12:13], v[16:17], v[18:19]
	v_lshlrev_b32_e32 v16, 16, v77
	v_and_b32_e32 v17, 0xffff0000, v77
	v_lshlrev_b32_e32 v18, 16, v73
	v_and_b32_e32 v19, 0xffff0000, v73
	v_pk_fma_f32 v[14:15], v[14:15], v[16:17], v[18:19]
	v_lshlrev_b32_e32 v16, 16, v78
	v_and_b32_e32 v17, 0xffff0000, v78
	v_lshlrev_b32_e32 v18, 16, v74
	v_and_b32_e32 v19, 0xffff0000, v74
	v_pk_fma_f32 v[16:17], v[8:9], v[16:17], v[18:19]
	v_lshlrev_b32_e32 v8, 16, v79
	v_and_b32_e32 v9, 0xffff0000, v79
	v_lshlrev_b32_e32 v18, 16, v75
	v_and_b32_e32 v19, 0xffff0000, v75
	v_pk_fma_f32 v[18:19], v[10:11], v[8:9], v[18:19]
	v_cvt_pk_bf16_f32 v8, v12, v13
	v_cvt_pk_bf16_f32 v9, v14, v15
	v_cvt_pk_bf16_f32 v10, v16, v17
	v_cvt_pk_bf16_f32 v11, v18, v19
	global_store_dwordx4 v[88:89], v[8:11], off
	s_nop 1
	v_lshlrev_b32_e32 v8, 16, v68
	v_and_b32_e32 v9, 0xffff0000, v68
	v_lshlrev_b32_e32 v10, 16, v64
	v_and_b32_e32 v11, 0xffff0000, v64
	v_pk_fma_f32 v[4:5], v[4:5], v[8:9], v[10:11]
	v_lshlrev_b32_e32 v8, 16, v69
	v_and_b32_e32 v9, 0xffff0000, v69
	v_lshlrev_b32_e32 v10, 16, v65
	v_and_b32_e32 v11, 0xffff0000, v65
	v_pk_fma_f32 v[6:7], v[6:7], v[8:9], v[10:11]
	v_lshlrev_b32_e32 v8, 16, v70
	v_and_b32_e32 v9, 0xffff0000, v70
	v_lshlrev_b32_e32 v10, 16, v66
	v_and_b32_e32 v11, 0xffff0000, v66
	v_pk_fma_f32 v[8:9], v[0:1], v[8:9], v[10:11]
	v_lshlrev_b32_e32 v0, 16, v71
	v_and_b32_e32 v1, 0xffff0000, v71
	v_lshlrev_b32_e32 v10, 16, v67
	v_and_b32_e32 v11, 0xffff0000, v67
	v_pk_fma_f32 v[10:11], v[2:3], v[0:1], v[10:11]
	v_cvt_pk_bf16_f32 v0, v4, v5
	v_cvt_pk_bf16_f32 v1, v6, v7
	v_cvt_pk_bf16_f32 v2, v8, v9
	v_cvt_pk_bf16_f32 v3, v10, v11
	global_store_dwordx4 v[88:89], v[0:3], off offset:256
	s_cbranch_vccz .LBB0_1277
	s_waitcnt vmcnt(0)
	s_cmpk_gt_u32 s26, 0xff
	s_cbranch_scc1 .LBB0_1289
	s_barrier

.LBB0_1356:
	ds_read_b128 v[128:131], v189
	ds_read_b128 v[132:135], v189 offset:1024
	ds_read_b128 v[136:139], v189 offset:2048
	ds_read_b128 v[140:143], v189 offset:3072
	s_add_u32 s24, s10, 0xfffc0080
	s_addc_u32 s25, s11, -1
	s_cmp_eq_u32 s47, 12
	s_cselect_b32 s27, s15, s25
	s_cselect_b32 s26, s29, s24
	s_cselect_b32 s25, s17, s46
	s_cselect_b32 s24, s44, s45
	v_lshl_add_u64 v[198:199], s[10:11], 0, v[162:163]
	s_add_i32 m0, s7, 0xc000
	ds_read_b128 v[144:147], v190
	ds_read_b128 v[148:151], v190 offset:1024
	ds_read_b128 v[166:169], v190 offset:2048
	ds_read_b128 v[170:173], v190 offset:3072
	ds_read_b128 v[174:177], v190 offset:4096
	ds_read_b128 v[180:183], v190 offset:5120
	ds_read_b128 v[184:187], v190 offset:6144
	ds_read_b128 v[194:197], v190 offset:7168
	global_load_lds_dwordx4 v[198:199], off
	v_lshl_add_u64 v[198:199], s[10:11], 0, v[164:165]
	s_add_i32 m0, s7, 0xe000
	s_nop 0
	global_load_lds_dwordx4 v[198:199], off
	s_waitcnt lgkmcnt(8)
	s_barrier
	s_waitcnt lgkmcnt(0)
	v_mfma_f32_16x16x32_bf16 v[124:127], v[128:131], v[144:147], v[124:127]
	v_mfma_f32_16x16x32_bf16 v[120:123], v[136:139], v[144:147], v[120:123]
	v_mfma_f32_16x16x32_bf16 v[108:111], v[128:131], v[166:169], v[108:111]
	v_mfma_f32_16x16x32_bf16 v[104:107], v[136:139], v[166:169], v[104:107]
	v_mfma_f32_16x16x32_bf16 v[92:95], v[128:131], v[174:177], v[92:95]
	v_mfma_f32_16x16x32_bf16 v[88:91], v[136:139], v[174:177], v[88:91]
	v_mfma_f32_16x16x32_bf16 v[76:79], v[128:131], v[184:187], v[76:79]
	v_mfma_f32_16x16x32_bf16 v[72:75], v[136:139], v[184:187], v[72:75]
	v_mfma_f32_16x16x32_bf16 v[124:127], v[132:135], v[148:151], v[124:127]
	v_mfma_f32_16x16x32_bf16 v[120:123], v[140:143], v[148:151], v[120:123]
	v_mfma_f32_16x16x32_bf16 v[108:111], v[132:135], v[170:173], v[108:111]
	v_mfma_f32_16x16x32_bf16 v[104:107], v[140:143], v[170:173], v[104:107]
	v_mfma_f32_16x16x32_bf16 v[92:95], v[132:135], v[180:183], v[92:95]
	v_mfma_f32_16x16x32_bf16 v[88:91], v[140:143], v[180:183], v[88:91]
	v_mfma_f32_16x16x32_bf16 v[76:79], v[132:135], v[194:197], v[76:79]
	v_mfma_f32_16x16x32_bf16 v[72:75], v[140:143], v[194:197], v[72:75]
	s_barrier
	s_add_i32 s48, s41, s33
	v_lshl_add_u64 v[214:215], s[24:25], 0, v[156:157]
	s_mov_b32 m0, s48
	ds_read_b128 v[198:201], v191
	ds_read_b128 v[202:205], v191 offset:1024
	ds_read_b128 v[206:209], v191 offset:2048
	ds_read_b128 v[210:213], v191 offset:3072
	global_load_lds_dwordx4 v[214:215], off
	v_lshl_add_u64 v[216:217], s[24:25], 0, v[152:153]
	s_add_i32 m0, s48, 0x2000
	s_nop 0
	global_load_lds_dwordx4 v[216:217], off
	s_barrier
	s_waitcnt lgkmcnt(0)
	v_mfma_f32_16x16x32_bf16 v[116:119], v[198:201], v[144:147], v[116:119]
	v_mfma_f32_16x16x32_bf16 v[112:115], v[206:209], v[144:147], v[112:115]
	v_mfma_f32_16x16x32_bf16 v[100:103], v[198:201], v[166:169], v[100:103]
	v_mfma_f32_16x16x32_bf16 v[96:99], v[206:209], v[166:169], v[96:99]
	v_mfma_f32_16x16x32_bf16 v[84:87], v[198:201], v[174:177], v[84:87]
	v_mfma_f32_16x16x32_bf16 v[80:83], v[206:209], v[174:177], v[80:83]
	v_mfma_f32_16x16x32_bf16 v[68:71], v[198:201], v[184:187], v[68:71]
	v_mfma_f32_16x16x32_bf16 v[64:67], v[206:209], v[184:187], v[64:67]
	v_mfma_f32_16x16x32_bf16 v[116:119], v[202:205], v[148:151], v[116:119]
	v_mfma_f32_16x16x32_bf16 v[112:115], v[210:213], v[148:151], v[112:115]
	v_mfma_f32_16x16x32_bf16 v[100:103], v[202:205], v[170:173], v[100:103]
	v_mfma_f32_16x16x32_bf16 v[96:99], v[210:213], v[170:173], v[96:99]
	v_mfma_f32_16x16x32_bf16 v[84:87], v[202:205], v[180:183], v[84:87]
	v_mfma_f32_16x16x32_bf16 v[80:83], v[210:213], v[180:183], v[80:83]
	v_mfma_f32_16x16x32_bf16 v[68:71], v[202:205], v[194:197], v[68:71]
	v_mfma_f32_16x16x32_bf16 v[64:67], v[210:213], v[194:197], v[64:67]
	s_mov_b32 m0, s7
	v_lshl_add_u64 v[218:219], s[26:27], 0, v[158:159]
	s_barrier
	ds_read_b128 v[144:147], v190 offset:16384
	ds_read_b128 v[148:151], v190 offset:17408
	ds_read_b128 v[166:169], v190 offset:18432
	ds_read_b128 v[170:173], v190 offset:19456
	ds_read_b128 v[174:177], v190 offset:20480
	ds_read_b128 v[180:183], v190 offset:21504
	ds_read_b128 v[184:187], v190 offset:22528
	ds_read_b128 v[194:197], v190 offset:23552
	global_load_lds_dwordx4 v[218:219], off
	v_lshl_add_u64 v[222:223], s[26:27], 0, v[154:155]
	s_mov_b32 m0, s35
	s_nop 0
	global_load_lds_dwordx4 v[222:223], off
	s_barrier
	s_waitcnt lgkmcnt(0)
	v_mfma_f32_16x16x32_bf16 v[60:63], v[128:131], v[144:147], v[60:63]
	v_mfma_f32_16x16x32_bf16 v[56:59], v[136:139], v[144:147], v[56:59]
	v_mfma_f32_16x16x32_bf16 v[44:47], v[128:131], v[166:169], v[44:47]
	v_mfma_f32_16x16x32_bf16 v[40:43], v[136:139], v[166:169], v[40:43]
	v_mfma_f32_16x16x32_bf16 v[28:31], v[128:131], v[174:177], v[28:31]
	v_mfma_f32_16x16x32_bf16 v[24:27], v[136:139], v[174:177], v[24:27]
	v_mfma_f32_16x16x32_bf16 v[12:15], v[128:131], v[184:187], v[12:15]
	v_mfma_f32_16x16x32_bf16 v[8:11], v[136:139], v[184:187], v[8:11]
	v_mfma_f32_16x16x32_bf16 v[60:63], v[132:135], v[148:151], v[60:63]
	v_mfma_f32_16x16x32_bf16 v[56:59], v[140:143], v[148:151], v[56:59]
	v_mfma_f32_16x16x32_bf16 v[44:47], v[132:135], v[170:173], v[44:47]
	v_mfma_f32_16x16x32_bf16 v[40:43], v[140:143], v[170:173], v[40:43]
	v_mfma_f32_16x16x32_bf16 v[28:31], v[132:135], v[180:183], v[28:31]
	v_mfma_f32_16x16x32_bf16 v[24:27], v[140:143], v[180:183], v[24:27]
	v_mfma_f32_16x16x32_bf16 v[12:15], v[132:135], v[194:197], v[12:15]
	v_mfma_f32_16x16x32_bf16 v[8:11], v[140:143], v[194:197], v[8:11]
	s_barrier
	s_add_u32 s48, s24, 0x40000
	s_addc_u32 s49, s25, 0
	s_add_i32 s50, s42, s33
	v_lshl_add_u64 v[128:129], s[48:49], 0, v[156:157]
	s_mov_b32 m0, s50
	s_nop 0
	global_load_lds_dwordx4 v[128:129], off
	v_lshl_add_u64 v[128:129], s[48:49], 0, v[152:153]
	s_add_i32 m0, s50, 0x2000
	s_nop 0
	global_load_lds_dwordx4 v[128:129], off
	s_waitcnt vmcnt(6)
	s_barrier
	v_mfma_f32_16x16x32_bf16 v[52:55], v[198:201], v[144:147], v[52:55]
	v_mfma_f32_16x16x32_bf16 v[48:51], v[206:209], v[144:147], v[48:51]
	v_mfma_f32_16x16x32_bf16 v[36:39], v[198:201], v[166:169], v[36:39]
	v_mfma_f32_16x16x32_bf16 v[32:35], v[206:209], v[166:169], v[32:35]
	v_mfma_f32_16x16x32_bf16 v[20:23], v[198:201], v[174:177], v[20:23]
	v_mfma_f32_16x16x32_bf16 v[16:19], v[206:209], v[174:177], v[16:19]
	v_mfma_f32_16x16x32_bf16 v[4:7], v[198:201], v[184:187], v[4:7]
	v_mfma_f32_16x16x32_bf16 v[0:3], v[206:209], v[184:187], v[0:3]
	v_mfma_f32_16x16x32_bf16 v[52:55], v[202:205], v[148:151], v[52:55]
	v_mfma_f32_16x16x32_bf16 v[48:51], v[210:213], v[148:151], v[48:51]
	v_mfma_f32_16x16x32_bf16 v[36:39], v[202:205], v[170:173], v[36:39]
	v_mfma_f32_16x16x32_bf16 v[32:35], v[210:213], v[170:173], v[32:35]
	v_mfma_f32_16x16x32_bf16 v[20:23], v[202:205], v[180:183], v[20:23]
	v_mfma_f32_16x16x32_bf16 v[16:19], v[210:213], v[180:183], v[16:19]
	v_mfma_f32_16x16x32_bf16 v[4:7], v[202:205], v[194:197], v[4:7]
	v_mfma_f32_16x16x32_bf16 v[0:3], v[210:213], v[194:197], v[0:3]
	s_add_i32 s48, 0, 0x18000
	v_add_u32_e32 v140, s48, v188
	s_barrier
	ds_read_b128 v[128:131], v140
	ds_read_b128 v[132:135], v140 offset:1024
	ds_read_b128 v[136:139], v140 offset:2048
	ds_read_b128 v[140:143], v140 offset:3072
	s_add_u32 s26, s26, 0x40000
	s_addc_u32 s27, s27, 0
	s_mov_b32 m0, s36
	v_lshl_add_u64 v[198:199], s[26:27], 0, v[158:159]
	ds_read_b128 v[144:147], v190 offset:32768
	ds_read_b128 v[148:151], v190 offset:33792
	ds_read_b128 v[166:169], v190 offset:34816
	ds_read_b128 v[170:173], v190 offset:35840
	ds_read_b128 v[174:177], v190 offset:36864
	ds_read_b128 v[180:183], v190 offset:37888
	ds_read_b128 v[184:187], v190 offset:38912
	ds_read_b128 v[194:197], v190 offset:39936
	global_load_lds_dwordx4 v[198:199], off
	v_lshl_add_u64 v[198:199], s[26:27], 0, v[154:155]
	s_mov_b32 m0, s37
	s_nop 0
	global_load_lds_dwordx4 v[198:199], off
	s_waitcnt lgkmcnt(8)
	s_barrier
	s_waitcnt lgkmcnt(0)
	v_mfma_f32_16x16x32_bf16 v[124:127], v[128:131], v[144:147], v[124:127]
	v_mfma_f32_16x16x32_bf16 v[120:123], v[136:139], v[144:147], v[120:123]
	v_mfma_f32_16x16x32_bf16 v[108:111], v[128:131], v[166:169], v[108:111]
	v_mfma_f32_16x16x32_bf16 v[104:107], v[136:139], v[166:169], v[104:107]
	v_mfma_f32_16x16x32_bf16 v[92:95], v[128:131], v[174:177], v[92:95]
	v_mfma_f32_16x16x32_bf16 v[88:91], v[136:139], v[174:177], v[88:91]
	v_mfma_f32_16x16x32_bf16 v[76:79], v[128:131], v[184:187], v[76:79]
	v_mfma_f32_16x16x32_bf16 v[72:75], v[136:139], v[184:187], v[72:75]
	v_mfma_f32_16x16x32_bf16 v[124:127], v[132:135], v[148:151], v[124:127]
	v_mfma_f32_16x16x32_bf16 v[120:123], v[140:143], v[148:151], v[120:123]
	v_mfma_f32_16x16x32_bf16 v[108:111], v[132:135], v[170:173], v[108:111]
	v_mfma_f32_16x16x32_bf16 v[104:107], v[140:143], v[170:173], v[104:107]
	v_mfma_f32_16x16x32_bf16 v[92:95], v[132:135], v[180:183], v[92:95]
	v_mfma_f32_16x16x32_bf16 v[88:91], v[140:143], v[180:183], v[88:91]
	v_mfma_f32_16x16x32_bf16 v[76:79], v[132:135], v[194:197], v[76:79]
	v_mfma_f32_16x16x32_bf16 v[72:75], v[140:143], v[194:197], v[72:75]
	s_barrier
	s_add_i32 s26, 0, 0x1c000
	s_add_i32 s27, s48, s33
	v_add_u32_e32 v193, s26, v188
	v_lshl_add_u64 v[214:215], v[214:215], 0, s[12:13]
	s_mov_b32 m0, s27
	ds_read_b128 v[198:201], v193
	ds_read_b128 v[202:205], v193 offset:1024
	ds_read_b128 v[206:209], v193 offset:2048
	ds_read_b128 v[210:213], v193 offset:3072
	global_load_lds_dwordx4 v[214:215], off
	v_lshl_add_u64 v[214:215], v[216:217], 0, s[12:13]
	s_add_i32 m0, s27, 0x2000
	s_nop 0
	global_load_lds_dwordx4 v[214:215], off
	s_barrier
	s_waitcnt lgkmcnt(0)
	v_mfma_f32_16x16x32_bf16 v[116:119], v[198:201], v[144:147], v[116:119]
	v_mfma_f32_16x16x32_bf16 v[112:115], v[206:209], v[144:147], v[112:115]
	v_mfma_f32_16x16x32_bf16 v[100:103], v[198:201], v[166:169], v[100:103]
	v_mfma_f32_16x16x32_bf16 v[96:99], v[206:209], v[166:169], v[96:99]
	v_mfma_f32_16x16x32_bf16 v[84:87], v[198:201], v[174:177], v[84:87]
	v_mfma_f32_16x16x32_bf16 v[80:83], v[206:209], v[174:177], v[80:83]
	v_mfma_f32_16x16x32_bf16 v[68:71], v[198:201], v[184:187], v[68:71]
	v_mfma_f32_16x16x32_bf16 v[64:67], v[206:209], v[184:187], v[64:67]
	v_mfma_f32_16x16x32_bf16 v[116:119], v[202:205], v[148:151], v[116:119]
	v_mfma_f32_16x16x32_bf16 v[112:115], v[210:213], v[148:151], v[112:115]
	v_mfma_f32_16x16x32_bf16 v[100:103], v[202:205], v[170:173], v[100:103]
	v_mfma_f32_16x16x32_bf16 v[96:99], v[210:213], v[170:173], v[96:99]
	v_mfma_f32_16x16x32_bf16 v[84:87], v[202:205], v[180:183], v[84:87]
	v_mfma_f32_16x16x32_bf16 v[80:83], v[210:213], v[180:183], v[80:83]
	v_mfma_f32_16x16x32_bf16 v[68:71], v[202:205], v[194:197], v[68:71]
	v_mfma_f32_16x16x32_bf16 v[64:67], v[210:213], v[194:197], v[64:67]
	s_mov_b32 m0, s39
	v_lshl_add_u64 v[214:215], v[218:219], 0, s[12:13]
	s_barrier
	ds_read_b128 v[144:147], v190 offset:49152
	ds_read_b128 v[148:151], v190 offset:50176
	ds_read_b128 v[166:169], v190 offset:51200
	ds_read_b128 v[170:173], v190 offset:52224
	ds_read_b128 v[174:177], v190 offset:53248
	ds_read_b128 v[180:183], v190 offset:54272
	ds_read_b128 v[184:187], v190 offset:55296
	ds_read_b128 v[194:197], v190 offset:56320
	global_load_lds_dwordx4 v[214:215], off
	v_lshl_add_u64 v[214:215], v[222:223], 0, s[12:13]
	s_mov_b32 m0, s40
	s_nop 0
	global_load_lds_dwordx4 v[214:215], off
	s_barrier
	s_waitcnt lgkmcnt(0)
	v_mfma_f32_16x16x32_bf16 v[60:63], v[128:131], v[144:147], v[60:63]
	v_mfma_f32_16x16x32_bf16 v[56:59], v[136:139], v[144:147], v[56:59]
	v_mfma_f32_16x16x32_bf16 v[44:47], v[128:131], v[166:169], v[44:47]
	v_mfma_f32_16x16x32_bf16 v[40:43], v[136:139], v[166:169], v[40:43]
	v_mfma_f32_16x16x32_bf16 v[28:31], v[128:131], v[174:177], v[28:31]
	v_mfma_f32_16x16x32_bf16 v[24:27], v[136:139], v[174:177], v[24:27]
	v_mfma_f32_16x16x32_bf16 v[12:15], v[128:131], v[184:187], v[12:15]
	v_mfma_f32_16x16x32_bf16 v[8:11], v[136:139], v[184:187], v[8:11]
	v_mfma_f32_16x16x32_bf16 v[60:63], v[132:135], v[148:151], v[60:63]
	v_mfma_f32_16x16x32_bf16 v[56:59], v[140:143], v[148:151], v[56:59]
	v_mfma_f32_16x16x32_bf16 v[44:47], v[132:135], v[170:173], v[44:47]
	v_mfma_f32_16x16x32_bf16 v[40:43], v[140:143], v[170:173], v[40:43]
	v_mfma_f32_16x16x32_bf16 v[28:31], v[132:135], v[180:183], v[28:31]
	v_mfma_f32_16x16x32_bf16 v[24:27], v[140:143], v[180:183], v[24:27]
	v_mfma_f32_16x16x32_bf16 v[12:15], v[132:135], v[194:197], v[12:15]
	v_mfma_f32_16x16x32_bf16 v[8:11], v[140:143], v[194:197], v[8:11]
	s_barrier
	s_add_u32 s24, s24, 0x40080
	s_addc_u32 s25, s25, 0
	s_add_i32 s26, s26, s33
	v_lshl_add_u64 v[128:129], s[24:25], 0, v[156:157]
	s_mov_b32 m0, s26
	s_nop 0
	global_load_lds_dwordx4 v[128:129], off
	v_lshl_add_u64 v[128:129], s[24:25], 0, v[152:153]
	s_add_i32 m0, s26, 0x2000
	s_nop 0
	global_load_lds_dwordx4 v[128:129], off
	s_waitcnt vmcnt(6)
	s_barrier
	v_mfma_f32_16x16x32_bf16 v[52:55], v[198:201], v[144:147], v[52:55]
	v_mfma_f32_16x16x32_bf16 v[48:51], v[206:209], v[144:147], v[48:51]
	v_mfma_f32_16x16x32_bf16 v[36:39], v[198:201], v[166:169], v[36:39]
	v_mfma_f32_16x16x32_bf16 v[32:35], v[206:209], v[166:169], v[32:35]
	v_mfma_f32_16x16x32_bf16 v[20:23], v[198:201], v[174:177], v[20:23]
	v_mfma_f32_16x16x32_bf16 v[16:19], v[206:209], v[174:177], v[16:19]
	v_mfma_f32_16x16x32_bf16 v[4:7], v[198:201], v[184:187], v[4:7]
	v_mfma_f32_16x16x32_bf16 v[0:3], v[206:209], v[184:187], v[0:3]
	v_mfma_f32_16x16x32_bf16 v[52:55], v[202:205], v[148:151], v[52:55]
	v_mfma_f32_16x16x32_bf16 v[48:51], v[210:213], v[148:151], v[48:51]
	v_mfma_f32_16x16x32_bf16 v[36:39], v[202:205], v[170:173], v[36:39]
	v_mfma_f32_16x16x32_bf16 v[32:35], v[210:213], v[170:173], v[32:35]
	v_mfma_f32_16x16x32_bf16 v[20:23], v[202:205], v[180:183], v[20:23]
	v_mfma_f32_16x16x32_bf16 v[16:19], v[210:213], v[180:183], v[16:19]
	v_mfma_f32_16x16x32_bf16 v[4:7], v[202:205], v[194:197], v[4:7]
	v_mfma_f32_16x16x32_bf16 v[0:3], v[210:213], v[194:197], v[0:3]
	s_add_i32 s47, s47, 2
	s_add_u32 s10, s10, 0x100
	s_addc_u32 s11, s11, 0
	s_add_u32 s45, s45, 0x100
	s_addc_u32 s46, s46, 0
	s_cmp_gt_u32 s47, 13
	s_barrier
	s_cbranch_scc0 .LBB0_1356
	s_lshl_b32 s24, s4, 8
	s_ashr_i32 s25, s24, 31
	s_lshl_b32 s10, s4, 2
	s_nop 0
	v_lshl_add_u32 v166, s28, 8, v179
	s_ashr_i32 s11, s10, 31
	s_lshl_b64 s[28:29], s[24:25], 1
	v_readlane_b32 s50, v253, 40
	v_readlane_b32 s51, v253, 41
	s_add_u32 s26, s50, s28
	v_ashrrev_i32_e32 v167, 31, v166
	s_addc_u32 s27, s51, s29
	v_lshlrev_b64 v[204:205], 11, v[166:167]
	v_lshl_add_u64 v[128:129], s[26:27], 0, v[204:205]
	v_lshl_add_u64 v[206:207], v[128:129], 0, v[160:161]
	global_load_dwordx4 v[196:199], v[206:207], off
	global_load_dwordx4 v[200:203], v[206:207], off offset:256
	v_or_b32_e32 v182, 16, v166
	v_or_b32_e32 v174, 32, v166
	v_or_b32_e32 v168, 48, v166
	v_ashrrev_i32_e32 v183, 31, v182
	v_ashrrev_i32_e32 v175, 31, v174
	v_ashrrev_i32_e32 v169, 31, v168
	v_lshlrev_b64 v[186:187], 11, v[182:183]
	v_lshlrev_b64 v[180:181], 11, v[174:175]
	v_lshlrev_b64 v[172:173], 11, v[168:169]
	v_lshl_add_u64 v[128:129], s[26:27], 0, v[186:187]
	v_lshl_add_u64 v[130:131], s[26:27], 0, v[180:181]
	v_lshl_add_u64 v[132:133], s[26:27], 0, v[172:173]
	v_lshl_add_u64 v[184:185], v[128:129], 0, v[160:161]
	v_lshl_add_u64 v[176:177], v[130:131], 0, v[160:161]
	v_lshl_add_u64 v[170:171], v[132:133], 0, v[160:161]
	global_load_dwordx4 v[148:151], v[184:185], off
	global_load_dwordx4 v[144:147], v[184:185], off offset:256
	global_load_dwordx4 v[140:143], v[176:177], off
	global_load_dwordx4 v[136:139], v[176:177], off offset:256
	global_load_dwordx4 v[132:135], v[170:171], off
	global_load_dwordx4 v[128:131], v[170:171], off offset:256
	v_and_b32_e32 v194, 64, v192
	v_xor_b32_e32 v193, 16, v192
	v_add_u32_e32 v194, 64, v194
	v_cmp_lt_i32_e32 vcc, v193, v194
	v_xor_b32_e32 v195, 32, v192
	v_lshl_add_u64 v[204:205], s[50:51], 0, v[204:205]
	v_cndmask_b32_e32 v193, v192, v193, vcc
	v_cmp_lt_i32_e32 vcc, v195, v194
	v_lshlrev_b32_e32 v194, 2, v193
	s_nop 0
	v_cndmask_b32_e32 v195, v192, v195, vcc
	v_lshlrev_b32_e32 v193, 2, v195
	s_nop 7
	s_nop 3
	s_waitcnt vmcnt(0)
	v_lshlrev_b32_e32 v210, 16, v198
	v_and_b32_e32 v211, 0xffff0000, v198
	v_lshlrev_b32_e32 v208, 16, v196
	v_and_b32_e32 v209, 0xffff0000, v196
	v_lshlrev_b32_e32 v198, 16, v199
	v_and_b32_e32 v199, 0xffff0000, v199
	v_lshlrev_b32_e32 v214, 16, v202
	v_and_b32_e32 v215, 0xffff0000, v202
	v_lshlrev_b32_e32 v202, 16, v203
	v_and_b32_e32 v203, 0xffff0000, v203
	v_pk_add_f32 v[120:121], v[120:121], v[210:211]
	v_lshlrev_b32_e32 v196, 16, v197
	v_and_b32_e32 v197, 0xffff0000, v197
	v_pk_add_f32 v[124:125], v[124:125], v[208:209]
	v_pk_add_f32 v[122:123], v[122:123], v[198:199]
	v_pk_add_f32 v[198:199], v[114:115], v[202:203]
	v_cvt_pk_bf16_f32 v114, v120, v121
	v_pk_mul_f32 v[120:121], v[120:121], v[120:121]
	v_pk_add_f32 v[126:127], v[126:127], v[196:197]
	v_cvt_pk_bf16_f32 v115, v122, v123
	v_pk_mul_f32 v[122:123], v[122:123], v[122:123]
	v_pk_fma_f32 v[120:121], v[124:125], v[124:125], v[120:121]
	v_lshlrev_b32_e32 v212, 16, v200
	v_and_b32_e32 v213, 0xffff0000, v200
	v_lshlrev_b32_e32 v200, 16, v201
	v_and_b32_e32 v201, 0xffff0000, v201
	v_pk_add_f32 v[196:197], v[112:113], v[214:215]
	v_pk_fma_f32 v[122:123], v[126:127], v[126:127], v[122:123]
	v_add_f32_e32 v120, v120, v121
	v_pk_add_f32 v[116:117], v[116:117], v[212:213]
	v_pk_add_f32 v[118:119], v[118:119], v[200:201]
	v_pk_mul_f32 v[200:201], v[196:197], v[196:197]
	v_add_f32_e32 v120, v122, v120
	v_cvt_pk_bf16_f32 v112, v124, v125
	v_pk_fma_f32 v[124:125], v[116:117], v[116:117], v[200:201]
	v_add_f32_e32 v120, v123, v120
	v_pk_mul_f32 v[202:203], v[198:199], v[198:199]
	v_add_f32_e32 v120, v124, v120
	v_cvt_pk_bf16_f32 v113, v126, v127
	v_pk_fma_f32 v[126:127], v[118:119], v[118:119], v[202:203]
	v_add_f32_e32 v120, v125, v120
	v_add_f32_e32 v120, v126, v120
	v_add_f32_e32 v122, v127, v120
	ds_bpermute_b32 v123, v194, v122
	global_store_dwordx4 v[206:207], v[112:115], off
	v_lshl_add_u64 v[120:121], v[204:205], 0, s[28:29]
	s_nop 0
	v_cvt_pk_bf16_f32 v114, v116, v117
	s_waitcnt lgkmcnt(0)
	v_add_f32_e32 v112, v122, v123
	ds_bpermute_b32 v113, v193, v112
	v_cvt_pk_bf16_f32 v115, v118, v119
	v_cvt_pk_bf16_f32 v116, v196, v197
	v_cvt_pk_bf16_f32 v117, v198, v199
	v_lshl_add_u64 v[118:119], v[120:121], 0, v[160:161]
	global_store_dwordx4 v[118:119], v[114:117], off offset:256
	s_and_saveexec_b64 s[28:29], s[0:1]
	s_cbranch_execz .LBB0_1359
	s_waitcnt lgkmcnt(0)
	v_add_f32_e32 v114, v112, v113
	v_lshlrev_b64 v[112:113], 6, v[166:167]
	v_lshl_add_u64 v[112:113], s[86:87], 0, v[112:113]
	v_lshl_add_u64 v[112:113], s[10:11], 2, v[112:113]
	s_lshl_b32 s4, s38, 2
	v_lshl_add_u64 v[112:113], v[112:113], 0, s[4:5]
	global_store_dword v[112:113], v114, off

.LBB0_1441:
	ds_read_b128 v[144:147], v161
	ds_read_b128 v[148:151], v161 offset:1024
	ds_read_b128 v[172:175], v161 offset:2048
	ds_read_b128 v[180:183], v161 offset:3072
	s_add_u32 s4, s0, 0xfffc0080
	s_addc_u32 s5, s1, -1
	s_cmp_eq_u32 s45, 12
	s_cselect_b32 s11, s19, s5
	s_cselect_b32 s10, s41, s4
	s_cselect_b32 s5, s21, s44
	s_cselect_b32 s4, s42, s43
	v_lshl_add_u64 v[154:155], s[0:1], 0, v[140:141]
	s_add_i32 m0, s17, 0xc000
	ds_read_b128 v[184:187], v165
	ds_read_b128 v[188:191], v165 offset:1024
	ds_read_b128 v[192:195], v165 offset:2048
	ds_read_b128 v[196:199], v165 offset:3072
	ds_read_b128 v[200:203], v165 offset:4096
	ds_read_b128 v[204:207], v165 offset:5120
	ds_read_b128 v[208:211], v165 offset:6144
	ds_read_b128 v[212:215], v165 offset:7168
	global_load_lds_dwordx4 v[154:155], off
	v_lshl_add_u64 v[154:155], s[0:1], 0, v[142:143]
	s_add_i32 m0, s17, 0xe000
	s_nop 0
	global_load_lds_dwordx4 v[154:155], off
	s_waitcnt lgkmcnt(8)
	s_barrier
	s_waitcnt lgkmcnt(0)
	v_mfma_f32_16x16x32_bf16 v[124:127], v[144:147], v[184:187], v[124:127]
	v_mfma_f32_16x16x32_bf16 v[120:123], v[172:175], v[184:187], v[120:123]
	v_mfma_f32_16x16x32_bf16 v[108:111], v[144:147], v[192:195], v[108:111]
	v_mfma_f32_16x16x32_bf16 v[104:107], v[172:175], v[192:195], v[104:107]
	v_mfma_f32_16x16x32_bf16 v[92:95], v[144:147], v[200:203], v[92:95]
	v_mfma_f32_16x16x32_bf16 v[88:91], v[172:175], v[200:203], v[88:91]
	v_mfma_f32_16x16x32_bf16 v[76:79], v[144:147], v[208:211], v[76:79]
	v_mfma_f32_16x16x32_bf16 v[72:75], v[172:175], v[208:211], v[72:75]
	v_mfma_f32_16x16x32_bf16 v[124:127], v[148:151], v[188:191], v[124:127]
	v_mfma_f32_16x16x32_bf16 v[120:123], v[180:183], v[188:191], v[120:123]
	v_mfma_f32_16x16x32_bf16 v[108:111], v[148:151], v[196:199], v[108:111]
	v_mfma_f32_16x16x32_bf16 v[104:107], v[180:183], v[196:199], v[104:107]
	v_mfma_f32_16x16x32_bf16 v[92:95], v[148:151], v[204:207], v[92:95]
	v_mfma_f32_16x16x32_bf16 v[88:91], v[180:183], v[204:207], v[88:91]
	v_mfma_f32_16x16x32_bf16 v[76:79], v[148:151], v[212:215], v[76:79]
	v_mfma_f32_16x16x32_bf16 v[72:75], v[180:183], v[212:215], v[72:75]
	s_barrier
	s_add_i32 s46, s37, s15
	v_lshl_add_u64 v[154:155], s[4:5], 0, v[132:133]
	s_mov_b32 m0, s46
	ds_read_b128 v[216:219], v167
	ds_read_b128 v[222:225], v167 offset:1024
	ds_read_b128 v[226:229], v167 offset:2048
	ds_read_b128 v[230:233], v167 offset:3072
	global_load_lds_dwordx4 v[154:155], off
	v_lshl_add_u64 v[158:159], s[4:5], 0, v[128:129]
	s_add_i32 m0, s46, 0x2000
	s_nop 0
	global_load_lds_dwordx4 v[158:159], off
	s_barrier
	s_waitcnt lgkmcnt(0)
	v_mfma_f32_16x16x32_bf16 v[116:119], v[216:219], v[184:187], v[116:119]
	v_mfma_f32_16x16x32_bf16 v[112:115], v[226:229], v[184:187], v[112:115]
	v_mfma_f32_16x16x32_bf16 v[100:103], v[216:219], v[192:195], v[100:103]
	v_mfma_f32_16x16x32_bf16 v[96:99], v[226:229], v[192:195], v[96:99]
	v_mfma_f32_16x16x32_bf16 v[84:87], v[216:219], v[200:203], v[84:87]
	v_mfma_f32_16x16x32_bf16 v[80:83], v[226:229], v[200:203], v[80:83]
	v_mfma_f32_16x16x32_bf16 v[68:71], v[216:219], v[208:211], v[68:71]
	v_mfma_f32_16x16x32_bf16 v[64:67], v[226:229], v[208:211], v[64:67]
	v_mfma_f32_16x16x32_bf16 v[116:119], v[222:225], v[188:191], v[116:119]
	v_mfma_f32_16x16x32_bf16 v[112:115], v[230:233], v[188:191], v[112:115]
	v_mfma_f32_16x16x32_bf16 v[100:103], v[222:225], v[196:199], v[100:103]
	v_mfma_f32_16x16x32_bf16 v[96:99], v[230:233], v[196:199], v[96:99]
	v_mfma_f32_16x16x32_bf16 v[84:87], v[222:225], v[204:207], v[84:87]
	v_mfma_f32_16x16x32_bf16 v[80:83], v[230:233], v[204:207], v[80:83]
	v_mfma_f32_16x16x32_bf16 v[68:71], v[222:225], v[212:215], v[68:71]
	v_mfma_f32_16x16x32_bf16 v[64:67], v[230:233], v[212:215], v[64:67]
	s_mov_b32 m0, s17
	v_lshl_add_u64 v[162:163], s[10:11], 0, v[134:135]
	s_barrier
	ds_read_b128 v[184:187], v165 offset:16384
	ds_read_b128 v[188:191], v165 offset:17408
	ds_read_b128 v[192:195], v165 offset:18432
	ds_read_b128 v[196:199], v165 offset:19456
	ds_read_b128 v[200:203], v165 offset:20480
	ds_read_b128 v[204:207], v165 offset:21504
	ds_read_b128 v[208:211], v165 offset:22528
	ds_read_b128 v[212:215], v165 offset:23552
	global_load_lds_dwordx4 v[162:163], off
	v_lshl_add_u64 v[168:169], s[10:11], 0, v[130:131]
	s_mov_b32 m0, s28
	s_nop 0
	global_load_lds_dwordx4 v[168:169], off
	s_barrier
	s_waitcnt lgkmcnt(0)
	v_mfma_f32_16x16x32_bf16 v[60:63], v[144:147], v[184:187], v[60:63]
	v_mfma_f32_16x16x32_bf16 v[56:59], v[172:175], v[184:187], v[56:59]
	v_mfma_f32_16x16x32_bf16 v[44:47], v[144:147], v[192:195], v[44:47]
	v_mfma_f32_16x16x32_bf16 v[40:43], v[172:175], v[192:195], v[40:43]
	v_mfma_f32_16x16x32_bf16 v[28:31], v[144:147], v[200:203], v[28:31]
	v_mfma_f32_16x16x32_bf16 v[24:27], v[172:175], v[200:203], v[24:27]
	v_mfma_f32_16x16x32_bf16 v[12:15], v[144:147], v[208:211], v[12:15]
	v_mfma_f32_16x16x32_bf16 v[8:11], v[172:175], v[208:211], v[8:11]
	v_mfma_f32_16x16x32_bf16 v[60:63], v[148:151], v[188:191], v[60:63]
	v_mfma_f32_16x16x32_bf16 v[56:59], v[180:183], v[188:191], v[56:59]
	v_mfma_f32_16x16x32_bf16 v[44:47], v[148:151], v[196:199], v[44:47]
	v_mfma_f32_16x16x32_bf16 v[40:43], v[180:183], v[196:199], v[40:43]
	v_mfma_f32_16x16x32_bf16 v[28:31], v[148:151], v[204:207], v[28:31]
	v_mfma_f32_16x16x32_bf16 v[24:27], v[180:183], v[204:207], v[24:27]
	v_mfma_f32_16x16x32_bf16 v[12:15], v[148:151], v[212:215], v[12:15]
	v_mfma_f32_16x16x32_bf16 v[8:11], v[180:183], v[212:215], v[8:11]
	s_barrier
	s_add_u32 s46, s4, 0x40000
	s_addc_u32 s47, s5, 0
	s_add_i32 s48, s38, s15
	v_lshl_add_u64 v[144:145], s[46:47], 0, v[132:133]
	s_mov_b32 m0, s48
	s_nop 0
	global_load_lds_dwordx4 v[144:145], off
	v_lshl_add_u64 v[144:145], s[46:47], 0, v[128:129]
	s_add_i32 m0, s48, 0x2000
	s_nop 0
	global_load_lds_dwordx4 v[144:145], off
	s_waitcnt vmcnt(6)
	s_barrier
	v_mfma_f32_16x16x32_bf16 v[52:55], v[216:219], v[184:187], v[52:55]
	v_mfma_f32_16x16x32_bf16 v[48:51], v[226:229], v[184:187], v[48:51]
	v_mfma_f32_16x16x32_bf16 v[36:39], v[216:219], v[192:195], v[36:39]
	v_mfma_f32_16x16x32_bf16 v[32:35], v[226:229], v[192:195], v[32:35]
	v_mfma_f32_16x16x32_bf16 v[20:23], v[216:219], v[200:203], v[20:23]
	v_mfma_f32_16x16x32_bf16 v[16:19], v[226:229], v[200:203], v[16:19]
	v_mfma_f32_16x16x32_bf16 v[4:7], v[216:219], v[208:211], v[4:7]
	v_mfma_f32_16x16x32_bf16 v[0:3], v[226:229], v[208:211], v[0:3]
	v_mfma_f32_16x16x32_bf16 v[52:55], v[222:225], v[188:191], v[52:55]
	v_mfma_f32_16x16x32_bf16 v[48:51], v[230:233], v[188:191], v[48:51]
	v_mfma_f32_16x16x32_bf16 v[36:39], v[222:225], v[196:199], v[36:39]
	v_mfma_f32_16x16x32_bf16 v[32:35], v[230:233], v[196:199], v[32:35]
	v_mfma_f32_16x16x32_bf16 v[20:23], v[222:225], v[204:207], v[20:23]
	v_mfma_f32_16x16x32_bf16 v[16:19], v[230:233], v[204:207], v[16:19]
	v_mfma_f32_16x16x32_bf16 v[4:7], v[222:225], v[212:215], v[4:7]
	v_mfma_f32_16x16x32_bf16 v[0:3], v[230:233], v[212:215], v[0:3]
	s_add_i32 s46, 0, 0x18000
	v_add_u32_e32 v152, s46, v157
	s_barrier
	ds_read_b128 v[144:147], v152
	ds_read_b128 v[148:151], v152 offset:1024
	ds_read_b128 v[172:175], v152 offset:2048
	ds_read_b128 v[180:183], v152 offset:3072
	s_add_u32 s10, s10, 0x40000
	s_addc_u32 s11, s11, 0
	s_mov_b32 m0, s29
	v_lshl_add_u64 v[176:177], s[10:11], 0, v[134:135]
	ds_read_b128 v[184:187], v165 offset:32768
	ds_read_b128 v[188:191], v165 offset:33792
	ds_read_b128 v[192:195], v165 offset:34816
	ds_read_b128 v[196:199], v165 offset:35840
	ds_read_b128 v[200:203], v165 offset:36864
	ds_read_b128 v[204:207], v165 offset:37888
	ds_read_b128 v[208:211], v165 offset:38912
	ds_read_b128 v[212:215], v165 offset:39936
	global_load_lds_dwordx4 v[176:177], off
	v_lshl_add_u64 v[176:177], s[10:11], 0, v[130:131]
	s_mov_b32 m0, s31
	s_nop 0
	global_load_lds_dwordx4 v[176:177], off
	s_waitcnt lgkmcnt(8)
	s_barrier
	s_waitcnt lgkmcnt(0)
	v_mfma_f32_16x16x32_bf16 v[124:127], v[144:147], v[184:187], v[124:127]
	v_mfma_f32_16x16x32_bf16 v[120:123], v[172:175], v[184:187], v[120:123]
	v_mfma_f32_16x16x32_bf16 v[108:111], v[144:147], v[192:195], v[108:111]
	v_mfma_f32_16x16x32_bf16 v[104:107], v[172:175], v[192:195], v[104:107]
	v_mfma_f32_16x16x32_bf16 v[92:95], v[144:147], v[200:203], v[92:95]
	v_mfma_f32_16x16x32_bf16 v[88:91], v[172:175], v[200:203], v[88:91]
	v_mfma_f32_16x16x32_bf16 v[76:79], v[144:147], v[208:211], v[76:79]
	v_mfma_f32_16x16x32_bf16 v[72:75], v[172:175], v[208:211], v[72:75]
	v_mfma_f32_16x16x32_bf16 v[124:127], v[148:151], v[188:191], v[124:127]
	v_mfma_f32_16x16x32_bf16 v[120:123], v[180:183], v[188:191], v[120:123]
	v_mfma_f32_16x16x32_bf16 v[108:111], v[148:151], v[196:199], v[108:111]
	v_mfma_f32_16x16x32_bf16 v[104:107], v[180:183], v[196:199], v[104:107]
	v_mfma_f32_16x16x32_bf16 v[92:95], v[148:151], v[204:207], v[92:95]
	v_mfma_f32_16x16x32_bf16 v[88:91], v[180:183], v[204:207], v[88:91]
	v_mfma_f32_16x16x32_bf16 v[76:79], v[148:151], v[212:215], v[76:79]
	v_mfma_f32_16x16x32_bf16 v[72:75], v[180:183], v[212:215], v[72:75]
	s_barrier
	s_add_i32 s10, 0, 0x1c000
	s_add_i32 s11, s46, s15
	v_add_u32_e32 v152, s10, v157
	v_lshl_add_u64 v[154:155], v[154:155], 0, s[12:13]
	s_mov_b32 m0, s11
	ds_read_b128 v[216:219], v152
	ds_read_b128 v[222:225], v152 offset:1024
	ds_read_b128 v[226:229], v152 offset:2048
	ds_read_b128 v[230:233], v152 offset:3072
	global_load_lds_dwordx4 v[154:155], off
	v_lshl_add_u64 v[154:155], v[158:159], 0, s[12:13]
	s_add_i32 m0, s11, 0x2000
	s_nop 0
	global_load_lds_dwordx4 v[154:155], off
	s_barrier
	s_waitcnt lgkmcnt(0)
	v_mfma_f32_16x16x32_bf16 v[116:119], v[216:219], v[184:187], v[116:119]
	v_mfma_f32_16x16x32_bf16 v[112:115], v[226:229], v[184:187], v[112:115]
	v_mfma_f32_16x16x32_bf16 v[100:103], v[216:219], v[192:195], v[100:103]
	v_mfma_f32_16x16x32_bf16 v[96:99], v[226:229], v[192:195], v[96:99]
	v_mfma_f32_16x16x32_bf16 v[84:87], v[216:219], v[200:203], v[84:87]
	v_mfma_f32_16x16x32_bf16 v[80:83], v[226:229], v[200:203], v[80:83]
	v_mfma_f32_16x16x32_bf16 v[68:71], v[216:219], v[208:211], v[68:71]
	v_mfma_f32_16x16x32_bf16 v[64:67], v[226:229], v[208:211], v[64:67]
	v_mfma_f32_16x16x32_bf16 v[116:119], v[222:225], v[188:191], v[116:119]
	v_mfma_f32_16x16x32_bf16 v[112:115], v[230:233], v[188:191], v[112:115]
	v_mfma_f32_16x16x32_bf16 v[100:103], v[222:225], v[196:199], v[100:103]
	v_mfma_f32_16x16x32_bf16 v[96:99], v[230:233], v[196:199], v[96:99]
	v_mfma_f32_16x16x32_bf16 v[84:87], v[222:225], v[204:207], v[84:87]
	v_mfma_f32_16x16x32_bf16 v[80:83], v[230:233], v[204:207], v[80:83]
	v_mfma_f32_16x16x32_bf16 v[68:71], v[222:225], v[212:215], v[68:71]
	v_mfma_f32_16x16x32_bf16 v[64:67], v[230:233], v[212:215], v[64:67]
	s_mov_b32 m0, s35
	v_lshl_add_u64 v[154:155], v[162:163], 0, s[12:13]
	s_barrier
	ds_read_b128 v[184:187], v165 offset:49152
	ds_read_b128 v[188:191], v165 offset:50176
	ds_read_b128 v[192:195], v165 offset:51200
	ds_read_b128 v[196:199], v165 offset:52224
	ds_read_b128 v[200:203], v165 offset:53248
	ds_read_b128 v[204:207], v165 offset:54272
	ds_read_b128 v[208:211], v165 offset:55296
	ds_read_b128 v[212:215], v165 offset:56320
	global_load_lds_dwordx4 v[154:155], off
	v_lshl_add_u64 v[154:155], v[168:169], 0, s[12:13]
	s_mov_b32 m0, s36
	s_nop 0
	global_load_lds_dwordx4 v[154:155], off
	s_barrier
	s_waitcnt lgkmcnt(0)
	v_mfma_f32_16x16x32_bf16 v[60:63], v[144:147], v[184:187], v[60:63]
	v_mfma_f32_16x16x32_bf16 v[56:59], v[172:175], v[184:187], v[56:59]
	v_mfma_f32_16x16x32_bf16 v[44:47], v[144:147], v[192:195], v[44:47]
	v_mfma_f32_16x16x32_bf16 v[40:43], v[172:175], v[192:195], v[40:43]
	v_mfma_f32_16x16x32_bf16 v[28:31], v[144:147], v[200:203], v[28:31]
	v_mfma_f32_16x16x32_bf16 v[24:27], v[172:175], v[200:203], v[24:27]
	v_mfma_f32_16x16x32_bf16 v[12:15], v[144:147], v[208:211], v[12:15]
	v_mfma_f32_16x16x32_bf16 v[8:11], v[172:175], v[208:211], v[8:11]
	v_mfma_f32_16x16x32_bf16 v[60:63], v[148:151], v[188:191], v[60:63]
	v_mfma_f32_16x16x32_bf16 v[56:59], v[180:183], v[188:191], v[56:59]
	v_mfma_f32_16x16x32_bf16 v[44:47], v[148:151], v[196:199], v[44:47]
	v_mfma_f32_16x16x32_bf16 v[40:43], v[180:183], v[196:199], v[40:43]
	v_mfma_f32_16x16x32_bf16 v[28:31], v[148:151], v[204:207], v[28:31]
	v_mfma_f32_16x16x32_bf16 v[24:27], v[180:183], v[204:207], v[24:27]
	v_mfma_f32_16x16x32_bf16 v[12:15], v[148:151], v[212:215], v[12:15]
	v_mfma_f32_16x16x32_bf16 v[8:11], v[180:183], v[212:215], v[8:11]
	s_barrier
	s_add_u32 s4, s4, 0x40080
	s_addc_u32 s5, s5, 0
	s_add_i32 s10, s10, s15
	v_lshl_add_u64 v[144:145], s[4:5], 0, v[132:133]
	s_mov_b32 m0, s10
	s_nop 0
	global_load_lds_dwordx4 v[144:145], off
	v_lshl_add_u64 v[144:145], s[4:5], 0, v[128:129]
	s_add_i32 m0, s10, 0x2000
	s_nop 0
	global_load_lds_dwordx4 v[144:145], off
	s_waitcnt vmcnt(6)
	s_barrier
	v_mfma_f32_16x16x32_bf16 v[52:55], v[216:219], v[184:187], v[52:55]
	v_mfma_f32_16x16x32_bf16 v[48:51], v[226:229], v[184:187], v[48:51]
	v_mfma_f32_16x16x32_bf16 v[36:39], v[216:219], v[192:195], v[36:39]
	v_mfma_f32_16x16x32_bf16 v[32:35], v[226:229], v[192:195], v[32:35]
	v_mfma_f32_16x16x32_bf16 v[20:23], v[216:219], v[200:203], v[20:23]
	v_mfma_f32_16x16x32_bf16 v[16:19], v[226:229], v[200:203], v[16:19]
	v_mfma_f32_16x16x32_bf16 v[4:7], v[216:219], v[208:211], v[4:7]
	v_mfma_f32_16x16x32_bf16 v[0:3], v[226:229], v[208:211], v[0:3]
	v_mfma_f32_16x16x32_bf16 v[52:55], v[222:225], v[188:191], v[52:55]
	v_mfma_f32_16x16x32_bf16 v[48:51], v[230:233], v[188:191], v[48:51]
	v_mfma_f32_16x16x32_bf16 v[36:39], v[222:225], v[196:199], v[36:39]
	v_mfma_f32_16x16x32_bf16 v[32:35], v[230:233], v[196:199], v[32:35]
	v_mfma_f32_16x16x32_bf16 v[20:23], v[222:225], v[204:207], v[20:23]
	v_mfma_f32_16x16x32_bf16 v[16:19], v[230:233], v[204:207], v[16:19]
	v_mfma_f32_16x16x32_bf16 v[4:7], v[222:225], v[212:215], v[4:7]
	v_mfma_f32_16x16x32_bf16 v[0:3], v[230:233], v[212:215], v[0:3]
	s_add_i32 s45, s45, 2
	s_add_u32 s0, s0, 0x100
	s_addc_u32 s1, s1, 0
	s_add_u32 s43, s43, 0x100
	s_addc_u32 s44, s44, 0
	s_cmp_gt_u32 s45, 13
	s_barrier
	s_cbranch_scc0 .LBB0_1441
	v_lshl_add_u32 v168, s72, 8, v153
	v_ashrrev_i32_e32 v169, 31, v168
	v_or_b32_e32 v162, 16, v168
	v_lshlrev_b64 v[144:145], 6, v[168:169]
	v_ashrrev_i32_e32 v163, 31, v162
	v_or_b32_e32 v158, 32, v168
	v_lshl_add_u64 v[144:145], v[138:139], 0, v[144:145]
	v_lshlrev_b64 v[146:147], 6, v[162:163]
	v_ashrrev_i32_e32 v159, 31, v158
	v_lshl_add_u64 v[146:147], v[138:139], 0, v[146:147]
	global_load_dwordx4 v[172:175], v[144:145], off
	global_load_dwordx4 v[180:183], v[146:147], off
	v_lshlrev_b64 v[144:145], 6, v[158:159]
	v_or_b32_e32 v154, 48, v168
	v_lshl_add_u64 v[144:145], v[138:139], 0, v[144:145]
	v_ashrrev_i32_e32 v155, 31, v154
	global_load_dwordx4 v[184:187], v[144:145], off
	v_lshlrev_b64 v[144:145], 6, v[154:155]
	v_lshl_add_u64 v[144:145], v[138:139], 0, v[144:145]
	global_load_dwordx4 v[188:191], v[144:145], off
	v_add_u32_e32 v150, 0x80, v168
	v_ashrrev_i32_e32 v151, 31, v150
	v_lshlrev_b64 v[144:145], 6, v[150:151]
	v_add_u32_e32 v148, 0x90, v168
	v_lshl_add_u64 v[144:145], v[138:139], 0, v[144:145]
	v_ashrrev_i32_e32 v149, 31, v148
	global_load_dwordx4 v[192:195], v[144:145], off
	v_lshlrev_b64 v[144:145], 6, v[148:149]
	v_lshl_add_u64 v[144:145], v[138:139], 0, v[144:145]
	global_load_dwordx4 v[196:199], v[144:145], off
	v_and_b32_e32 v145, 64, v171
	v_add_u32_e32 v146, 0xa0, v168
	v_add_u32_e32 v144, 0xb0, v168
	v_add_u32_e32 v160, 64, v145
	v_ashrrev_i32_e32 v147, 31, v146
	v_ashrrev_i32_e32 v145, 31, v144
	v_lshlrev_b64 v[200:201], 6, v[146:147]
	v_lshlrev_b64 v[202:203], 6, v[144:145]
	v_lshl_add_u64 v[200:201], v[138:139], 0, v[200:201]
	v_lshl_add_u64 v[204:205], v[138:139], 0, v[202:203]
	global_load_dwordx4 v[200:203], v[200:201], off
	s_nop 0
	global_load_dwordx4 v[204:207], v[204:205], off
	v_xor_b32_e32 v152, 16, v171
	v_cmp_lt_i32_e32 vcc, v152, v160
	v_xor_b32_e32 v156, 32, v171
	v_mov_b64_e32 v[176:177], s[16:17]
	v_cndmask_b32_e32 v152, v171, v152, vcc
	v_lshlrev_b32_e32 v152, 2, v152
	v_cmp_lt_i32_e32 vcc, v156, v160
	v_lshlrev_b64 v[168:169], 7, v[168:169]
	s_mov_b32 s72, s18
	v_cndmask_b32_e32 v156, v171, v156, vcc
	v_lshlrev_b32_e32 v156, 2, v156
	s_mov_b32 s21, s18
	s_mov_b32 s19, s40
	s_waitcnt vmcnt(0)
	v_mov_b32_e32 v208, v173
	v_mov_b32_e32 v209, v174
	v_mov_b32_e32 v173, v175
	v_mov_b32_e32 v174, v181
	v_mov_b32_e32 v175, v182
	v_mov_b32_e32 v181, v183
	v_pk_add_f32 v[172:173], v[208:209], v[172:173]
	v_pk_add_f32 v[174:175], v[174:175], v[180:181]
	v_mov_b32_e32 v181, v172
	v_mov_b32_e32 v180, v174
	v_mov_b32_e32 v172, v175
	v_mov_b32_e32 v182, v185
	v_mov_b32_e32 v183, v186
	v_mov_b32_e32 v185, v187
	v_mov_b32_e32 v186, v189
	v_mov_b32_e32 v187, v190
	v_mov_b32_e32 v189, v191
	v_pk_add_f32 v[172:173], v[180:181], v[172:173]
	v_pk_add_f32 v[182:183], v[182:183], v[184:185]
	v_pk_add_f32 v[184:185], v[186:187], v[188:189]
	ds_bpermute_b32 v181, v152, v173
	ds_bpermute_b32 v180, v152, v172
	v_mov_b32_e32 v174, v184
	v_mov_b32_e32 v175, v182
	v_mov_b32_e32 v182, v185
	v_pk_add_f32 v[174:175], v[174:175], v[182:183]
	ds_bpermute_b32 v183, v152, v175
	ds_bpermute_b32 v182, v152, v174
	s_waitcnt lgkmcnt(0)
	v_pk_add_f32 v[172:173], v[172:173], v[180:181]
	ds_bpermute_b32 v181, v156, v173
	ds_bpermute_b32 v180, v156, v172
	v_mov_b32_e32 v184, v193
	v_pk_add_f32 v[174:175], v[174:175], v[182:183]
	ds_bpermute_b32 v183, v156, v175
	ds_bpermute_b32 v182, v156, v174
	s_waitcnt lgkmcnt(2)
	v_pk_add_f32 v[172:173], v[172:173], v[180:181]
	v_mov_b32_e32 v185, v194
	v_mov_b32_e32 v193, v195
	v_mov_b32_e32 v186, v197
	v_mov_b32_e32 v187, v198
	v_pk_fma_f32 v[172:173], v[172:173], s[14:15], v[176:177] op_sel_hi:[1,0,0]
	v_mov_b32_e32 v197, v199
	v_pk_add_f32 v[184:185], v[184:185], v[192:193]
	v_mul_f32_e32 v160, 0x4b800000, v173
	v_cmp_gt_f32_e32 vcc, s39, v173
	v_pk_add_f32 v[180:181], v[186:187], v[196:197]
	s_waitcnt lgkmcnt(0)
	v_pk_add_f32 v[174:175], v[174:175], v[182:183]
	v_cndmask_b32_e32 v160, v173, v160, vcc
	v_mov_b32_e32 v182, v180
	v_mov_b32_e32 v183, v184
	v_mov_b32_e32 v184, v181
	v_rsq_f32_e32 v160, v160
	v_pk_add_f32 v[180:181], v[182:183], v[184:185]
	ds_bpermute_b32 v183, v152, v181
	ds_bpermute_b32 v182, v152, v180
	v_pk_fma_f32 v[174:175], v[174:175], s[14:15], v[176:177] op_sel_hi:[1,0,0]
	v_mul_f32_e32 v164, 0x4b800000, v172
	v_cmp_gt_f32_e64 s[0:1], s39, v172
	v_mul_f32_e32 v170, 0x45800000, v160
	v_mul_f32_e32 v166, 0x4b800000, v175
	v_cndmask_b32_e64 v164, v172, v164, s[0:1]
	v_cmp_gt_f32_e64 s[4:5], s39, v175
	v_cndmask_b32_e32 v172, v160, v170, vcc
	v_mul_f32_e32 v160, 0x4b800000, v174
	v_cmp_gt_f32_e32 vcc, s39, v174
	v_cndmask_b32_e64 v166, v175, v166, s[4:5]
	v_mov_b32_e32 v184, v205
	v_cndmask_b32_e32 v160, v174, v160, vcc
	s_waitcnt lgkmcnt(0)
	v_pk_add_f32 v[174:175], v[180:181], v[182:183]
	ds_bpermute_b32 v181, v156, v175
	ds_bpermute_b32 v180, v156, v174
	v_mov_b32_e32 v185, v206
	v_mov_b32_e32 v205, v207
	v_pk_add_f32 v[184:185], v[184:185], v[204:205]
	v_rsq_f32_e32 v164, v164
	s_waitcnt lgkmcnt(0)
	v_pk_add_f32 v[174:175], v[174:175], v[180:181]
	v_mov_b32_e32 v180, v201
	v_mov_b32_e32 v181, v202
	v_mov_b32_e32 v201, v203
	v_pk_add_f32 v[180:181], v[180:181], v[200:201]
	v_mov_b32_e32 v186, v184
	v_mov_b32_e32 v187, v180
	v_mov_b32_e32 v180, v185
	v_rsq_f32_e32 v166, v166
	v_pk_add_f32 v[180:181], v[186:187], v[180:181]
	ds_bpermute_b32 v185, v152, v181
	ds_bpermute_b32 v184, v152, v180
	v_mul_f32_e32 v173, 0x45800000, v164
	v_cndmask_b32_e64 v182, v164, v173, s[0:1]
	v_mul_f32_e32 v164, 0x45800000, v166
	v_pk_fma_f32 v[174:175], v[174:175], s[14:15], v[176:177] op_sel_hi:[1,0,0]
	v_cndmask_b32_e64 v170, v166, v164, s[4:5]
	v_mul_f32_e32 v166, 0x4b800000, v175
	v_cmp_gt_f32_e64 s[0:1], s39, v175
	v_mul_f32_e32 v152, 0x4b800000, v174
	v_cmp_gt_f32_e64 s[4:5], s39, v174
	v_cndmask_b32_e64 v166, v175, v166, s[0:1]
	v_rsq_f32_e32 v160, v160
	v_cndmask_b32_e64 v152, v174, v152, s[4:5]
	s_waitcnt lgkmcnt(0)
	v_pk_add_f32 v[174:175], v[180:181], v[184:185]
	ds_bpermute_b32 v181, v156, v175
	ds_bpermute_b32 v180, v156, v174
	v_rsq_f32_e32 v173, v166
	v_mul_f32_e32 v164, 0x45800000, v160
	v_cndmask_b32_e32 v166, v160, v164, vcc
	v_rsq_f32_e32 v152, v152
	s_waitcnt lgkmcnt(0)
	v_pk_add_f32 v[174:175], v[174:175], v[180:181]
	v_mul_f32_e32 v156, 0x45800000, v173
	v_pk_fma_f32 v[174:175], v[174:175], s[14:15], v[176:177] op_sel_hi:[1,0,0]
	v_cndmask_b32_e64 v164, v173, v156, s[0:1]
	v_mul_f32_e32 v160, 0x4b800000, v175
	v_cmp_gt_f32_e32 vcc, s39, v175
	v_cmp_gt_f32_e64 s[0:1], s39, v174
	v_mul_f32_e32 v156, 0x45800000, v152
	v_cndmask_b32_e32 v160, v175, v160, vcc
	v_rsq_f32_e32 v173, v160
	v_mul_f32_e32 v160, 0x4b800000, v174
	v_cndmask_b32_e64 v160, v174, v160, s[0:1]
	v_rsq_f32_e32 v174, v160
	v_cndmask_b32_e64 v160, v152, v156, s[4:5]
	v_mul_f32_e32 v152, 0x45800000, v173
	v_cndmask_b32_e32 v156, v173, v152, vcc
	v_mul_f32_e32 v152, 0x45800000, v174
	v_cndmask_b32_e64 v152, v174, v152, s[0:1]
	s_lshl_b32 s0, s70, 8
	s_or_b32 s0, s0, s33
	s_ashr_i32 s4, s0, 6
	s_ashr_i32 s5, s4, 31
	s_lshl_b64 s[0:1], s[4:5], 22
	v_pk_mul_f32 v[124:125], v[124:125], v[172:173] op_sel_hi:[1,0]
	v_pk_mul_f32 v[120:121], v[120:121], v[172:173] op_sel_hi:[1,0]
	s_add_u32 s0, s84, s0
	v_pk_mul_f32 v[126:127], v[126:127], v[172:173] op_sel_hi:[1,0]
	v_pk_mul_f32 v[122:123], v[122:123], v[172:173] op_sel_hi:[1,0]
	v_max_f32_e32 v124, 0, v124
	v_max_f32_e32 v120, 0, v120
	v_max_f32_e32 v125, 0, v125
	v_max_f32_e32 v121, 0, v121
	s_addc_u32 s1, s85, s1
	s_or_b32 s4, s4, 2
	v_pk_mul_f32 v[124:125], v[124:125], v[124:125]
	v_pk_mul_f32 v[174:175], v[120:121], v[120:121]
	v_max_f32_e32 v120, 0, v126
	v_max_f32_e32 v122, 0, v122
	v_max_f32_e32 v121, 0, v127
	v_max_f32_e32 v123, 0, v123
	s_ashr_i32 s5, s4, 31
	v_pk_mul_f32 v[126:127], v[120:121], v[120:121]
	v_pk_mul_f32 v[176:177], v[122:123], v[122:123]
	v_cvt_pk_bf16_f32 v120, v124, v125
	v_lshl_add_u64 v[124:125], s[0:1], 0, v[168:169]
	v_pk_mul_f32 v[116:117], v[116:117], v[172:173] op_sel_hi:[1,0]
	v_pk_mul_f32 v[112:113], v[112:113], v[172:173] op_sel_hi:[1,0]
	s_lshl_b64 s[4:5], s[4:5], 22
	v_cvt_pk_bf16_f32 v121, v126, v127
	v_cvt_pk_bf16_f32 v122, v174, v175
	v_cvt_pk_bf16_f32 v123, v176, v177
	v_lshl_add_u64 v[124:125], v[124:125], 0, v[136:137]
	v_pk_mul_f32 v[118:119], v[118:119], v[172:173] op_sel_hi:[1,0]
	v_pk_mul_f32 v[114:115], v[114:115], v[172:173] op_sel_hi:[1,0]
	v_max_f32_e32 v116, 0, v116
	v_max_f32_e32 v112, 0, v112
	v_max_f32_e32 v117, 0, v117
	v_max_f32_e32 v113, 0, v113
	s_add_u32 s4, s84, s4
	global_store_dwordx4 v[124:125], v[120:123], off nt
	v_pk_mul_f32 v[116:117], v[116:117], v[116:117]
	v_max_f32_e32 v114, 0, v114
	v_pk_mul_f32 v[120:121], v[112:113], v[112:113]
	v_max_f32_e32 v112, 0, v118
	v_max_f32_e32 v113, 0, v119
	v_max_f32_e32 v115, 0, v115
	s_addc_u32 s5, s85, s5
	v_pk_mul_f32 v[118:119], v[112:113], v[112:113]
	v_pk_mul_f32 v[122:123], v[114:115], v[114:115]
	v_cvt_pk_bf16_f32 v112, v116, v117
	v_lshl_add_u64 v[116:117], s[4:5], 0, v[168:169]
	v_pk_mul_f32 v[108:109], v[108:109], v[182:183] op_sel_hi:[1,0]
	v_pk_mul_f32 v[104:105], v[104:105], v[182:183] op_sel_hi:[1,0]
	v_cvt_pk_bf16_f32 v113, v118, v119
	v_cvt_pk_bf16_f32 v114, v120, v121
	v_cvt_pk_bf16_f32 v115, v122, v123
	v_lshl_add_u64 v[116:117], v[116:117], 0, v[136:137]
	v_pk_mul_f32 v[110:111], v[110:111], v[182:183] op_sel_hi:[1,0]
	v_pk_mul_f32 v[106:107], v[106:107], v[182:183] op_sel_hi:[1,0]
	v_max_f32_e32 v108, 0, v108
	v_max_f32_e32 v104, 0, v104
	v_max_f32_e32 v109, 0, v109
	v_max_f32_e32 v105, 0, v105
	global_store_dwordx4 v[116:117], v[112:115], off nt
	v_pk_mul_f32 v[108:109], v[108:109], v[108:109]
	v_max_f32_e32 v106, 0, v106
	v_lshlrev_b64 v[112:113], 7, v[162:163]
	v_pk_mul_f32 v[114:115], v[104:105], v[104:105]
	v_max_f32_e32 v104, 0, v110
	v_max_f32_e32 v105, 0, v111
	v_max_f32_e32 v107, 0, v107
	v_pk_mul_f32 v[110:111], v[104:105], v[104:105]
	v_pk_mul_f32 v[116:117], v[106:107], v[106:107]
	v_cvt_pk_bf16_f32 v104, v108, v109
	v_lshl_add_u64 v[108:109], s[0:1], 0, v[112:113]
	v_pk_mul_f32 v[100:101], v[100:101], v[182:183] op_sel_hi:[1,0]
	v_pk_mul_f32 v[96:97], v[96:97], v[182:183] op_sel_hi:[1,0]
	v_cvt_pk_bf16_f32 v105, v110, v111
	v_cvt_pk_bf16_f32 v106, v114, v115
	v_cvt_pk_bf16_f32 v107, v116, v117
	v_lshl_add_u64 v[108:109], v[108:109], 0, v[136:137]
	v_pk_mul_f32 v[102:103], v[102:103], v[182:183] op_sel_hi:[1,0]
	v_pk_mul_f32 v[98:99], v[98:99], v[182:183] op_sel_hi:[1,0]
	v_max_f32_e32 v100, 0, v100
	v_max_f32_e32 v96, 0, v96
	v_max_f32_e32 v101, 0, v101
	v_max_f32_e32 v97, 0, v97
	global_store_dwordx4 v[108:109], v[104:107], off nt
	v_pk_mul_f32 v[100:101], v[100:101], v[100:101]
	v_max_f32_e32 v98, 0, v98
	v_pk_mul_f32 v[104:105], v[96:97], v[96:97]
	v_max_f32_e32 v96, 0, v102
	v_max_f32_e32 v97, 0, v103
	v_max_f32_e32 v99, 0, v99
	v_pk_mul_f32 v[102:103], v[96:97], v[96:97]
	v_pk_mul_f32 v[106:107], v[98:99], v[98:99]
	v_cvt_pk_bf16_f32 v96, v100, v101
	v_lshl_add_u64 v[100:101], s[4:5], 0, v[112:113]
	v_pk_mul_f32 v[92:93], v[92:93], v[170:171] op_sel_hi:[1,0]
	v_pk_mul_f32 v[88:89], v[88:89], v[170:171] op_sel_hi:[1,0]
	v_cvt_pk_bf16_f32 v97, v102, v103
	v_cvt_pk_bf16_f32 v98, v104, v105
	v_cvt_pk_bf16_f32 v99, v106, v107
	v_lshl_add_u64 v[100:101], v[100:101], 0, v[136:137]
	v_pk_mul_f32 v[94:95], v[94:95], v[170:171] op_sel_hi:[1,0]
	v_pk_mul_f32 v[90:91], v[90:91], v[170:171] op_sel_hi:[1,0]
	v_max_f32_e32 v92, 0, v92
	v_max_f32_e32 v88, 0, v88
	v_max_f32_e32 v93, 0, v93
	v_max_f32_e32 v89, 0, v89
	global_store_dwordx4 v[100:101], v[96:99], off nt
	v_pk_mul_f32 v[92:93], v[92:93], v[92:93]
	v_max_f32_e32 v90, 0, v90
	v_lshlrev_b64 v[96:97], 7, v[158:159]
	v_pk_mul_f32 v[98:99], v[88:89], v[88:89]
	v_max_f32_e32 v88, 0, v94
	v_max_f32_e32 v89, 0, v95
	v_max_f32_e32 v91, 0, v91
	v_pk_mul_f32 v[94:95], v[88:89], v[88:89]
	v_pk_mul_f32 v[100:101], v[90:91], v[90:91]
	v_cvt_pk_bf16_f32 v88, v92, v93
	v_lshl_add_u64 v[92:93], s[0:1], 0, v[96:97]
	v_pk_mul_f32 v[84:85], v[84:85], v[170:171] op_sel_hi:[1,0]
	v_pk_mul_f32 v[80:81], v[80:81], v[170:171] op_sel_hi:[1,0]
	v_cvt_pk_bf16_f32 v89, v94, v95
	v_cvt_pk_bf16_f32 v90, v98, v99
	v_cvt_pk_bf16_f32 v91, v100, v101
	v_lshl_add_u64 v[92:93], v[92:93], 0, v[136:137]
	v_pk_mul_f32 v[86:87], v[86:87], v[170:171] op_sel_hi:[1,0]
	v_pk_mul_f32 v[82:83], v[82:83], v[170:171] op_sel_hi:[1,0]
	v_max_f32_e32 v84, 0, v84
	v_max_f32_e32 v80, 0, v80
	v_max_f32_e32 v85, 0, v85
	v_max_f32_e32 v81, 0, v81
	global_store_dwordx4 v[92:93], v[88:91], off nt
	v_pk_mul_f32 v[84:85], v[84:85], v[84:85]
	v_max_f32_e32 v82, 0, v82
	v_pk_mul_f32 v[88:89], v[80:81], v[80:81]
	v_max_f32_e32 v80, 0, v86
	v_max_f32_e32 v81, 0, v87
	v_max_f32_e32 v83, 0, v83
	v_pk_mul_f32 v[86:87], v[80:81], v[80:81]
	v_pk_mul_f32 v[90:91], v[82:83], v[82:83]
	v_cvt_pk_bf16_f32 v80, v84, v85
	v_lshl_add_u64 v[84:85], s[4:5], 0, v[96:97]
	v_pk_mul_f32 v[76:77], v[76:77], v[166:167] op_sel_hi:[1,0]
	v_pk_mul_f32 v[72:73], v[72:73], v[166:167] op_sel_hi:[1,0]
	v_cvt_pk_bf16_f32 v81, v86, v87
	v_cvt_pk_bf16_f32 v82, v88, v89
	v_cvt_pk_bf16_f32 v83, v90, v91
	v_lshl_add_u64 v[84:85], v[84:85], 0, v[136:137]
	v_pk_mul_f32 v[78:79], v[78:79], v[166:167] op_sel_hi:[1,0]
	v_pk_mul_f32 v[74:75], v[74:75], v[166:167] op_sel_hi:[1,0]
	v_max_f32_e32 v76, 0, v76
	v_max_f32_e32 v72, 0, v72
	v_max_f32_e32 v77, 0, v77
	v_max_f32_e32 v73, 0, v73
	global_store_dwordx4 v[84:85], v[80:83], off nt
	v_pk_mul_f32 v[76:77], v[76:77], v[76:77]
	v_max_f32_e32 v74, 0, v74
	v_lshlrev_b64 v[80:81], 7, v[154:155]
	v_pk_mul_f32 v[82:83], v[72:73], v[72:73]
	v_max_f32_e32 v72, 0, v78
	v_max_f32_e32 v73, 0, v79
	v_max_f32_e32 v75, 0, v75
	v_pk_mul_f32 v[78:79], v[72:73], v[72:73]
	v_pk_mul_f32 v[84:85], v[74:75], v[74:75]
	v_cvt_pk_bf16_f32 v72, v76, v77
	v_lshl_add_u64 v[76:77], s[0:1], 0, v[80:81]
	v_pk_mul_f32 v[68:69], v[68:69], v[166:167] op_sel_hi:[1,0]
	v_pk_mul_f32 v[64:65], v[64:65], v[166:167] op_sel_hi:[1,0]
	v_cvt_pk_bf16_f32 v73, v78, v79
	v_cvt_pk_bf16_f32 v74, v82, v83
	v_cvt_pk_bf16_f32 v75, v84, v85
	v_lshl_add_u64 v[76:77], v[76:77], 0, v[136:137]
	v_pk_mul_f32 v[70:71], v[70:71], v[166:167] op_sel_hi:[1,0]
	v_pk_mul_f32 v[66:67], v[66:67], v[166:167] op_sel_hi:[1,0]
	v_max_f32_e32 v68, 0, v68
	v_max_f32_e32 v64, 0, v64
	v_max_f32_e32 v69, 0, v69
	v_max_f32_e32 v65, 0, v65
	global_store_dwordx4 v[76:77], v[72:75], off nt
	v_pk_mul_f32 v[68:69], v[68:69], v[68:69]
	v_max_f32_e32 v66, 0, v66
	v_pk_mul_f32 v[72:73], v[64:65], v[64:65]
	v_max_f32_e32 v64, 0, v70
	v_max_f32_e32 v65, 0, v71
	v_max_f32_e32 v67, 0, v67
	v_pk_mul_f32 v[70:71], v[64:65], v[64:65]
	v_pk_mul_f32 v[74:75], v[66:67], v[66:67]
	v_cvt_pk_bf16_f32 v64, v68, v69
	v_lshl_add_u64 v[68:69], s[4:5], 0, v[80:81]
	v_pk_mul_f32 v[60:61], v[60:61], v[164:165] op_sel_hi:[1,0]
	v_pk_mul_f32 v[56:57], v[56:57], v[164:165] op_sel_hi:[1,0]
	v_cvt_pk_bf16_f32 v65, v70, v71
	v_cvt_pk_bf16_f32 v66, v72, v73
	v_cvt_pk_bf16_f32 v67, v74, v75
	v_lshl_add_u64 v[68:69], v[68:69], 0, v[136:137]
	v_pk_mul_f32 v[62:63], v[62:63], v[164:165] op_sel_hi:[1,0]
	v_pk_mul_f32 v[58:59], v[58:59], v[164:165] op_sel_hi:[1,0]
	v_max_f32_e32 v60, 0, v60
	v_max_f32_e32 v56, 0, v56
	v_max_f32_e32 v61, 0, v61
	v_max_f32_e32 v57, 0, v57
	global_store_dwordx4 v[68:69], v[64:67], off nt
	v_pk_mul_f32 v[60:61], v[60:61], v[60:61]
	v_max_f32_e32 v58, 0, v58
	v_lshlrev_b64 v[64:65], 7, v[150:151]
	v_pk_mul_f32 v[66:67], v[56:57], v[56:57]
	v_max_f32_e32 v56, 0, v62
	v_max_f32_e32 v57, 0, v63
	v_max_f32_e32 v59, 0, v59
	v_pk_mul_f32 v[62:63], v[56:57], v[56:57]
	v_pk_mul_f32 v[68:69], v[58:59], v[58:59]
	v_cvt_pk_bf16_f32 v56, v60, v61
	v_lshl_add_u64 v[60:61], s[0:1], 0, v[64:65]
	v_pk_mul_f32 v[52:53], v[52:53], v[164:165] op_sel_hi:[1,0]
	v_pk_mul_f32 v[48:49], v[48:49], v[164:165] op_sel_hi:[1,0]
	v_cvt_pk_bf16_f32 v57, v62, v63
	v_cvt_pk_bf16_f32 v58, v66, v67
	v_cvt_pk_bf16_f32 v59, v68, v69
	v_lshl_add_u64 v[60:61], v[60:61], 0, v[136:137]
	v_pk_mul_f32 v[54:55], v[54:55], v[164:165] op_sel_hi:[1,0]
	v_pk_mul_f32 v[50:51], v[50:51], v[164:165] op_sel_hi:[1,0]
	v_max_f32_e32 v52, 0, v52
	v_max_f32_e32 v48, 0, v48
	v_max_f32_e32 v53, 0, v53
	v_max_f32_e32 v49, 0, v49
	global_store_dwordx4 v[60:61], v[56:59], off nt
	v_pk_mul_f32 v[52:53], v[52:53], v[52:53]
	v_max_f32_e32 v50, 0, v50
	v_pk_mul_f32 v[56:57], v[48:49], v[48:49]
	v_max_f32_e32 v48, 0, v54
	v_max_f32_e32 v49, 0, v55
	v_max_f32_e32 v51, 0, v51
	v_pk_mul_f32 v[54:55], v[48:49], v[48:49]
	v_pk_mul_f32 v[58:59], v[50:51], v[50:51]
	v_cvt_pk_bf16_f32 v48, v52, v53
	v_lshl_add_u64 v[52:53], s[4:5], 0, v[64:65]
	v_pk_mul_f32 v[44:45], v[44:45], v[160:161] op_sel_hi:[1,0]
	v_pk_mul_f32 v[40:41], v[40:41], v[160:161] op_sel_hi:[1,0]
	v_cvt_pk_bf16_f32 v49, v54, v55
	v_cvt_pk_bf16_f32 v50, v56, v57
	v_cvt_pk_bf16_f32 v51, v58, v59
	v_lshl_add_u64 v[52:53], v[52:53], 0, v[136:137]
	v_pk_mul_f32 v[46:47], v[46:47], v[160:161] op_sel_hi:[1,0]
	v_pk_mul_f32 v[42:43], v[42:43], v[160:161] op_sel_hi:[1,0]
	v_max_f32_e32 v44, 0, v44
	v_max_f32_e32 v40, 0, v40
	v_max_f32_e32 v45, 0, v45
	v_max_f32_e32 v41, 0, v41
	global_store_dwordx4 v[52:53], v[48:51], off nt
	v_pk_mul_f32 v[44:45], v[44:45], v[44:45]
	v_max_f32_e32 v42, 0, v42
	v_lshlrev_b64 v[48:49], 7, v[148:149]
	v_pk_mul_f32 v[50:51], v[40:41], v[40:41]
	v_max_f32_e32 v40, 0, v46
	v_max_f32_e32 v41, 0, v47
	v_max_f32_e32 v43, 0, v43
	v_pk_mul_f32 v[46:47], v[40:41], v[40:41]
	v_pk_mul_f32 v[52:53], v[42:43], v[42:43]
	v_cvt_pk_bf16_f32 v40, v44, v45
	v_lshl_add_u64 v[44:45], s[0:1], 0, v[48:49]
	v_pk_mul_f32 v[36:37], v[36:37], v[160:161] op_sel_hi:[1,0]
	v_pk_mul_f32 v[32:33], v[32:33], v[160:161] op_sel_hi:[1,0]
	v_cvt_pk_bf16_f32 v41, v46, v47
	v_cvt_pk_bf16_f32 v42, v50, v51
	v_cvt_pk_bf16_f32 v43, v52, v53
	v_lshl_add_u64 v[44:45], v[44:45], 0, v[136:137]
	v_pk_mul_f32 v[38:39], v[38:39], v[160:161] op_sel_hi:[1,0]
	v_pk_mul_f32 v[34:35], v[34:35], v[160:161] op_sel_hi:[1,0]
	v_max_f32_e32 v36, 0, v36
	v_max_f32_e32 v32, 0, v32
	v_max_f32_e32 v37, 0, v37
	v_max_f32_e32 v33, 0, v33
	global_store_dwordx4 v[44:45], v[40:43], off nt
	v_pk_mul_f32 v[36:37], v[36:37], v[36:37]
	v_max_f32_e32 v34, 0, v34
	v_pk_mul_f32 v[40:41], v[32:33], v[32:33]
	v_max_f32_e32 v32, 0, v38
	v_max_f32_e32 v33, 0, v39
	v_max_f32_e32 v35, 0, v35
	v_pk_mul_f32 v[38:39], v[32:33], v[32:33]
	v_pk_mul_f32 v[42:43], v[34:35], v[34:35]
	v_cvt_pk_bf16_f32 v32, v36, v37
	v_lshl_add_u64 v[36:37], s[4:5], 0, v[48:49]
	v_pk_mul_f32 v[28:29], v[28:29], v[156:157] op_sel_hi:[1,0]
	v_pk_mul_f32 v[24:25], v[24:25], v[156:157] op_sel_hi:[1,0]
	v_cvt_pk_bf16_f32 v33, v38, v39
	v_cvt_pk_bf16_f32 v34, v40, v41
	v_cvt_pk_bf16_f32 v35, v42, v43
	v_lshl_add_u64 v[36:37], v[36:37], 0, v[136:137]
	v_pk_mul_f32 v[30:31], v[30:31], v[156:157] op_sel_hi:[1,0]
	v_pk_mul_f32 v[26:27], v[26:27], v[156:157] op_sel_hi:[1,0]
	v_max_f32_e32 v28, 0, v28
	v_max_f32_e32 v24, 0, v24
	v_max_f32_e32 v29, 0, v29
	v_max_f32_e32 v25, 0, v25
	global_store_dwordx4 v[36:37], v[32:35], off nt
	v_pk_mul_f32 v[28:29], v[28:29], v[28:29]
	v_max_f32_e32 v26, 0, v26
	v_lshlrev_b64 v[32:33], 7, v[146:147]
	v_pk_mul_f32 v[34:35], v[24:25], v[24:25]
	v_max_f32_e32 v24, 0, v30
	v_max_f32_e32 v25, 0, v31
	v_max_f32_e32 v27, 0, v27
	v_pk_mul_f32 v[30:31], v[24:25], v[24:25]
	v_pk_mul_f32 v[36:37], v[26:27], v[26:27]
	v_cvt_pk_bf16_f32 v24, v28, v29
	v_lshl_add_u64 v[28:29], s[0:1], 0, v[32:33]
	v_pk_mul_f32 v[20:21], v[20:21], v[156:157] op_sel_hi:[1,0]
	v_pk_mul_f32 v[16:17], v[16:17], v[156:157] op_sel_hi:[1,0]
	v_cvt_pk_bf16_f32 v25, v30, v31
	v_cvt_pk_bf16_f32 v26, v34, v35
	v_cvt_pk_bf16_f32 v27, v36, v37
	v_lshl_add_u64 v[28:29], v[28:29], 0, v[136:137]
	v_pk_mul_f32 v[22:23], v[22:23], v[156:157] op_sel_hi:[1,0]
	v_pk_mul_f32 v[18:19], v[18:19], v[156:157] op_sel_hi:[1,0]
	v_max_f32_e32 v20, 0, v20
	v_max_f32_e32 v16, 0, v16
	v_max_f32_e32 v21, 0, v21
	v_max_f32_e32 v17, 0, v17
	global_store_dwordx4 v[28:29], v[24:27], off nt
	v_pk_mul_f32 v[20:21], v[20:21], v[20:21]
	v_max_f32_e32 v18, 0, v18
	v_pk_mul_f32 v[24:25], v[16:17], v[16:17]
	v_max_f32_e32 v16, 0, v22
	v_max_f32_e32 v17, 0, v23
	v_max_f32_e32 v19, 0, v19
	v_pk_mul_f32 v[22:23], v[16:17], v[16:17]
	v_pk_mul_f32 v[26:27], v[18:19], v[18:19]
	v_cvt_pk_bf16_f32 v16, v20, v21
	v_lshl_add_u64 v[20:21], s[4:5], 0, v[32:33]
	v_pk_mul_f32 v[12:13], v[12:13], v[152:153] op_sel_hi:[1,0]
	v_pk_mul_f32 v[8:9], v[8:9], v[152:153] op_sel_hi:[1,0]
	v_cvt_pk_bf16_f32 v17, v22, v23
	v_cvt_pk_bf16_f32 v18, v24, v25
	v_cvt_pk_bf16_f32 v19, v26, v27
	v_lshl_add_u64 v[20:21], v[20:21], 0, v[136:137]
	v_pk_mul_f32 v[14:15], v[14:15], v[152:153] op_sel_hi:[1,0]
	v_pk_mul_f32 v[10:11], v[10:11], v[152:153] op_sel_hi:[1,0]
	v_max_f32_e32 v12, 0, v12
	v_max_f32_e32 v8, 0, v8
	v_max_f32_e32 v13, 0, v13
	v_max_f32_e32 v9, 0, v9
	global_store_dwordx4 v[20:21], v[16:19], off nt
	v_pk_mul_f32 v[12:13], v[12:13], v[12:13]
	v_max_f32_e32 v10, 0, v10
	v_lshlrev_b64 v[16:17], 7, v[144:145]
	v_pk_mul_f32 v[18:19], v[8:9], v[8:9]
	v_max_f32_e32 v8, 0, v14
	v_max_f32_e32 v9, 0, v15
	v_max_f32_e32 v11, 0, v11
	v_pk_mul_f32 v[14:15], v[8:9], v[8:9]
	v_pk_mul_f32 v[20:21], v[10:11], v[10:11]
	v_cvt_pk_bf16_f32 v8, v12, v13
	v_lshl_add_u64 v[12:13], s[0:1], 0, v[16:17]
	v_pk_mul_f32 v[4:5], v[4:5], v[152:153] op_sel_hi:[1,0]
	v_pk_mul_f32 v[0:1], v[0:1], v[152:153] op_sel_hi:[1,0]
	v_cvt_pk_bf16_f32 v9, v14, v15
	v_cvt_pk_bf16_f32 v10, v18, v19
	v_cvt_pk_bf16_f32 v11, v20, v21
	v_lshl_add_u64 v[12:13], v[12:13], 0, v[136:137]
	v_pk_mul_f32 v[6:7], v[6:7], v[152:153] op_sel_hi:[1,0]
	v_pk_mul_f32 v[2:3], v[2:3], v[152:153] op_sel_hi:[1,0]
	v_max_f32_e32 v4, 0, v4
	v_max_f32_e32 v0, 0, v0
	v_max_f32_e32 v5, 0, v5
	v_max_f32_e32 v1, 0, v1
	global_store_dwordx4 v[12:13], v[8:11], off nt
	v_pk_mul_f32 v[4:5], v[4:5], v[4:5]
	v_max_f32_e32 v2, 0, v2
	v_pk_mul_f32 v[8:9], v[0:1], v[0:1]
	v_max_f32_e32 v0, 0, v6
	v_max_f32_e32 v1, 0, v7
	v_max_f32_e32 v3, 0, v3
	v_pk_mul_f32 v[6:7], v[0:1], v[0:1]
	v_pk_mul_f32 v[10:11], v[2:3], v[2:3]
	v_cvt_pk_bf16_f32 v0, v4, v5
	v_lshl_add_u64 v[4:5], s[4:5], 0, v[16:17]
	v_cvt_pk_bf16_f32 v1, v6, v7
	v_cvt_pk_bf16_f32 v2, v8, v9
	v_cvt_pk_bf16_f32 v3, v10, v11
	v_lshl_add_u64 v[4:5], v[4:5], 0, v[136:137]
	s_and_b64 vcc, exec, s[24:25]
	s_mov_b32 s70, s20
	s_mov_b32 s24, s20
	s_mov_b64 s[4:5], s[26:27]
	s_mov_b64 s[0:1], s[22:23]
	global_store_dwordx4 v[4:5], v[0:3], off nt
	s_cbranch_vccz .LBB0_1433
	s_waitcnt vmcnt(0)
	s_cmpk_gt_u32 s7, 0xff
	s_cbranch_scc1 .LBB0_1445
	s_barrier

.LBB0_1512:
	ds_read_b128 v[128:131], v203
	ds_read_b128 v[132:135], v203 offset:1024
	ds_read_b128 v[136:139], v203 offset:2048
	ds_read_b128 v[140:143], v203 offset:3072
	s_add_u32 s26, s24, 0x3fc000
	s_addc_u32 s27, s25, 0
	s_cmp_eq_u32 s49, 60
	s_cselect_b32 s30, s7, s26
	s_cselect_b32 s31, s5, s27
	s_cselect_b32 s26, s15, s17
	s_cselect_b32 s27, s8, s48
	s_add_u32 s28, s30, 0x400000
	s_addc_u32 s29, s31, 0
	v_lshl_add_u64 v[196:197], s[24:25], 0, v[168:169]
	s_add_i32 m0, s33, 0xc000
	ds_read_b128 v[144:147], v204
	ds_read_b128 v[148:151], v204 offset:1024
	ds_read_b128 v[172:175], v204 offset:2048
	ds_read_b128 v[176:179], v204 offset:3072
	ds_read_b128 v[180:183], v204 offset:4096
	ds_read_b128 v[184:187], v204 offset:5120
	ds_read_b128 v[188:191], v204 offset:6144
	ds_read_b128 v[192:195], v204 offset:7168
	global_load_lds_dwordx4 v[196:197], off
	v_lshl_add_u64 v[196:197], s[24:25], 0, v[170:171]
	s_add_i32 m0, s33, 0xe000
	s_nop 0
	global_load_lds_dwordx4 v[196:197], off
	s_waitcnt lgkmcnt(8)
	s_barrier
	s_waitcnt lgkmcnt(0)
	v_mfma_f32_16x16x32_bf16 v[124:127], v[128:131], v[144:147], v[124:127]
	v_mfma_f32_16x16x32_bf16 v[120:123], v[136:139], v[144:147], v[120:123]
	v_mfma_f32_16x16x32_bf16 v[108:111], v[128:131], v[172:175], v[108:111]
	v_mfma_f32_16x16x32_bf16 v[104:107], v[136:139], v[172:175], v[104:107]
	v_mfma_f32_16x16x32_bf16 v[92:95], v[128:131], v[180:183], v[92:95]
	v_mfma_f32_16x16x32_bf16 v[88:91], v[136:139], v[180:183], v[88:91]
	v_mfma_f32_16x16x32_bf16 v[76:79], v[128:131], v[188:191], v[76:79]
	v_mfma_f32_16x16x32_bf16 v[72:75], v[136:139], v[188:191], v[72:75]
	v_mfma_f32_16x16x32_bf16 v[124:127], v[132:135], v[148:151], v[124:127]
	v_mfma_f32_16x16x32_bf16 v[120:123], v[140:143], v[148:151], v[120:123]
	v_mfma_f32_16x16x32_bf16 v[108:111], v[132:135], v[176:179], v[108:111]
	v_mfma_f32_16x16x32_bf16 v[104:107], v[140:143], v[176:179], v[104:107]
	v_mfma_f32_16x16x32_bf16 v[92:95], v[132:135], v[184:187], v[92:95]
	v_mfma_f32_16x16x32_bf16 v[88:91], v[140:143], v[184:187], v[88:91]
	v_mfma_f32_16x16x32_bf16 v[76:79], v[132:135], v[192:195], v[76:79]
	v_mfma_f32_16x16x32_bf16 v[72:75], v[140:143], v[192:195], v[72:75]
	s_barrier
	s_add_i32 s50, s44, s13
	v_lshl_add_u64 v[200:201], s[26:27], 0, v[156:157]
	s_mov_b32 m0, s50
	ds_read_b128 v[196:199], v205
	ds_read_b128 v[208:211], v205 offset:1024
	ds_read_b128 v[212:215], v205 offset:2048
	ds_read_b128 v[216:219], v205 offset:3072
	global_load_lds_dwordx4 v[200:201], off
	v_lshl_add_u64 v[200:201], s[26:27], 0, v[152:153]
	s_add_i32 m0, s50, 0x2000
	s_nop 0
	global_load_lds_dwordx4 v[200:201], off
	s_barrier
	s_waitcnt lgkmcnt(0)
	v_mfma_f32_16x16x32_bf16 v[116:119], v[196:199], v[144:147], v[116:119]
	v_mfma_f32_16x16x32_bf16 v[112:115], v[212:215], v[144:147], v[112:115]
	v_mfma_f32_16x16x32_bf16 v[100:103], v[196:199], v[172:175], v[100:103]
	v_mfma_f32_16x16x32_bf16 v[96:99], v[212:215], v[172:175], v[96:99]
	v_mfma_f32_16x16x32_bf16 v[84:87], v[196:199], v[180:183], v[84:87]
	v_mfma_f32_16x16x32_bf16 v[80:83], v[212:215], v[180:183], v[80:83]
	v_mfma_f32_16x16x32_bf16 v[68:71], v[196:199], v[188:191], v[68:71]
	v_mfma_f32_16x16x32_bf16 v[64:67], v[212:215], v[188:191], v[64:67]
	v_mfma_f32_16x16x32_bf16 v[116:119], v[208:211], v[148:151], v[116:119]
	v_mfma_f32_16x16x32_bf16 v[112:115], v[216:219], v[148:151], v[112:115]
	v_mfma_f32_16x16x32_bf16 v[100:103], v[208:211], v[176:179], v[100:103]
	v_mfma_f32_16x16x32_bf16 v[96:99], v[216:219], v[176:179], v[96:99]
	v_mfma_f32_16x16x32_bf16 v[84:87], v[208:211], v[184:187], v[84:87]
	v_mfma_f32_16x16x32_bf16 v[80:83], v[216:219], v[184:187], v[80:83]
	v_mfma_f32_16x16x32_bf16 v[68:71], v[208:211], v[192:195], v[68:71]
	v_mfma_f32_16x16x32_bf16 v[64:67], v[216:219], v[192:195], v[64:67]
	s_mov_b32 m0, s33
	v_lshl_add_u64 v[200:201], s[30:31], 0, v[158:159]
	s_barrier
	ds_read_b128 v[144:147], v204 offset:16384
	ds_read_b128 v[148:151], v204 offset:17408
	ds_read_b128 v[172:175], v204 offset:18432
	ds_read_b128 v[176:179], v204 offset:19456
	ds_read_b128 v[180:183], v204 offset:20480
	ds_read_b128 v[184:187], v204 offset:21504
	ds_read_b128 v[188:191], v204 offset:22528
	ds_read_b128 v[192:195], v204 offset:23552
	global_load_lds_dwordx4 v[200:201], off
	v_lshl_add_u64 v[200:201], s[30:31], 0, v[154:155]
	s_mov_b32 m0, s35
	s_nop 0
	global_load_lds_dwordx4 v[200:201], off
	s_barrier
	s_waitcnt lgkmcnt(0)
	v_mfma_f32_16x16x32_bf16 v[60:63], v[128:131], v[144:147], v[60:63]
	v_mfma_f32_16x16x32_bf16 v[56:59], v[136:139], v[144:147], v[56:59]
	v_mfma_f32_16x16x32_bf16 v[44:47], v[128:131], v[172:175], v[44:47]
	v_mfma_f32_16x16x32_bf16 v[40:43], v[136:139], v[172:175], v[40:43]
	v_mfma_f32_16x16x32_bf16 v[28:31], v[128:131], v[180:183], v[28:31]
	v_mfma_f32_16x16x32_bf16 v[24:27], v[136:139], v[180:183], v[24:27]
	v_mfma_f32_16x16x32_bf16 v[12:15], v[128:131], v[188:191], v[12:15]
	v_mfma_f32_16x16x32_bf16 v[8:11], v[136:139], v[188:191], v[8:11]
	v_mfma_f32_16x16x32_bf16 v[60:63], v[132:135], v[148:151], v[60:63]
	v_mfma_f32_16x16x32_bf16 v[56:59], v[140:143], v[148:151], v[56:59]
	v_mfma_f32_16x16x32_bf16 v[44:47], v[132:135], v[176:179], v[44:47]
	v_mfma_f32_16x16x32_bf16 v[40:43], v[140:143], v[176:179], v[40:43]
	v_mfma_f32_16x16x32_bf16 v[28:31], v[132:135], v[184:187], v[28:31]
	v_mfma_f32_16x16x32_bf16 v[24:27], v[140:143], v[184:187], v[24:27]
	v_mfma_f32_16x16x32_bf16 v[12:15], v[132:135], v[192:195], v[12:15]
	v_mfma_f32_16x16x32_bf16 v[8:11], v[140:143], v[192:195], v[8:11]
	s_barrier
	s_add_u32 s50, s26, 0x4000
	s_addc_u32 s51, s27, 0
	s_add_i32 s52, s45, s13
	v_lshl_add_u64 v[128:129], s[50:51], 0, v[156:157]
	s_mov_b32 m0, s52
	s_nop 0
	global_load_lds_dwordx4 v[128:129], off
	v_lshl_add_u64 v[128:129], s[50:51], 0, v[152:153]
	s_add_i32 m0, s52, 0x2000
	s_nop 0
	global_load_lds_dwordx4 v[128:129], off
	s_waitcnt vmcnt(6)
	s_barrier
	v_mfma_f32_16x16x32_bf16 v[52:55], v[196:199], v[144:147], v[52:55]
	v_mfma_f32_16x16x32_bf16 v[48:51], v[212:215], v[144:147], v[48:51]
	v_mfma_f32_16x16x32_bf16 v[36:39], v[196:199], v[172:175], v[36:39]
	v_mfma_f32_16x16x32_bf16 v[32:35], v[212:215], v[172:175], v[32:35]
	v_mfma_f32_16x16x32_bf16 v[20:23], v[196:199], v[180:183], v[20:23]
	v_mfma_f32_16x16x32_bf16 v[16:19], v[212:215], v[180:183], v[16:19]
	v_mfma_f32_16x16x32_bf16 v[4:7], v[196:199], v[188:191], v[4:7]
	v_mfma_f32_16x16x32_bf16 v[0:3], v[212:215], v[188:191], v[0:3]
	v_mfma_f32_16x16x32_bf16 v[52:55], v[208:211], v[148:151], v[52:55]
	v_mfma_f32_16x16x32_bf16 v[48:51], v[216:219], v[148:151], v[48:51]
	v_mfma_f32_16x16x32_bf16 v[36:39], v[208:211], v[176:179], v[36:39]
	v_mfma_f32_16x16x32_bf16 v[32:35], v[216:219], v[176:179], v[32:35]
	v_mfma_f32_16x16x32_bf16 v[20:23], v[208:211], v[184:187], v[20:23]
	v_mfma_f32_16x16x32_bf16 v[16:19], v[216:219], v[184:187], v[16:19]
	v_mfma_f32_16x16x32_bf16 v[4:7], v[208:211], v[192:195], v[4:7]
	v_mfma_f32_16x16x32_bf16 v[0:3], v[216:219], v[192:195], v[0:3]
	s_add_i32 s50, 0, 0x18000
	v_add_u32_e32 v140, s50, v202
	s_barrier
	ds_read_b128 v[128:131], v140
	ds_read_b128 v[132:135], v140 offset:1024
	ds_read_b128 v[136:139], v140 offset:2048
	ds_read_b128 v[140:143], v140 offset:3072
	s_add_u32 s30, s30, 0x4000
	s_addc_u32 s31, s31, 0
	s_mov_b32 m0, s36
	v_lshl_add_u64 v[196:197], s[30:31], 0, v[158:159]
	ds_read_b128 v[144:147], v204 offset:32768
	ds_read_b128 v[148:151], v204 offset:33792
	ds_read_b128 v[172:175], v204 offset:34816
	ds_read_b128 v[176:179], v204 offset:35840
	ds_read_b128 v[180:183], v204 offset:36864
	ds_read_b128 v[184:187], v204 offset:37888
	ds_read_b128 v[188:191], v204 offset:38912
	ds_read_b128 v[192:195], v204 offset:39936
	global_load_lds_dwordx4 v[196:197], off
	v_lshl_add_u64 v[196:197], s[30:31], 0, v[154:155]
	s_mov_b32 m0, s37
	s_nop 0
	global_load_lds_dwordx4 v[196:197], off
	s_waitcnt lgkmcnt(8)
	s_barrier
	s_waitcnt lgkmcnt(0)
	v_mfma_f32_16x16x32_bf16 v[124:127], v[128:131], v[144:147], v[124:127]
	v_mfma_f32_16x16x32_bf16 v[120:123], v[136:139], v[144:147], v[120:123]
	v_mfma_f32_16x16x32_bf16 v[108:111], v[128:131], v[172:175], v[108:111]
	v_mfma_f32_16x16x32_bf16 v[104:107], v[136:139], v[172:175], v[104:107]
	v_mfma_f32_16x16x32_bf16 v[92:95], v[128:131], v[180:183], v[92:95]
	v_mfma_f32_16x16x32_bf16 v[88:91], v[136:139], v[180:183], v[88:91]
	v_mfma_f32_16x16x32_bf16 v[76:79], v[128:131], v[188:191], v[76:79]
	v_mfma_f32_16x16x32_bf16 v[72:75], v[136:139], v[188:191], v[72:75]
	v_mfma_f32_16x16x32_bf16 v[124:127], v[132:135], v[148:151], v[124:127]
	v_mfma_f32_16x16x32_bf16 v[120:123], v[140:143], v[148:151], v[120:123]
	v_mfma_f32_16x16x32_bf16 v[108:111], v[132:135], v[176:179], v[108:111]
	v_mfma_f32_16x16x32_bf16 v[104:107], v[140:143], v[176:179], v[104:107]
	v_mfma_f32_16x16x32_bf16 v[92:95], v[132:135], v[184:187], v[92:95]
	v_mfma_f32_16x16x32_bf16 v[88:91], v[140:143], v[184:187], v[88:91]
	v_mfma_f32_16x16x32_bf16 v[76:79], v[132:135], v[192:195], v[76:79]
	v_mfma_f32_16x16x32_bf16 v[72:75], v[140:143], v[192:195], v[72:75]
	s_barrier
	s_add_i32 s51, 0, 0x1c000
	s_add_u32 s30, s26, 0x20000
	v_add_u32_e32 v200, s51, v202
	s_addc_u32 s31, s27, 0
	s_add_i32 s50, s50, s13
	ds_read_b128 v[196:199], v200
	ds_read_b128 v[208:211], v200 offset:1024
	ds_read_b128 v[212:215], v200 offset:2048
	ds_read_b128 v[216:219], v200 offset:3072
	v_lshl_add_u64 v[200:201], s[30:31], 0, v[156:157]
	s_mov_b32 m0, s50
	s_nop 0
	global_load_lds_dwordx4 v[200:201], off
	v_lshl_add_u64 v[200:201], s[30:31], 0, v[152:153]
	s_add_i32 m0, s50, 0x2000
	s_nop 0
	global_load_lds_dwordx4 v[200:201], off
	s_barrier
	s_waitcnt lgkmcnt(0)
	v_mfma_f32_16x16x32_bf16 v[116:119], v[196:199], v[144:147], v[116:119]
	v_mfma_f32_16x16x32_bf16 v[112:115], v[212:215], v[144:147], v[112:115]
	v_mfma_f32_16x16x32_bf16 v[100:103], v[196:199], v[172:175], v[100:103]
	v_mfma_f32_16x16x32_bf16 v[96:99], v[212:215], v[172:175], v[96:99]
	v_mfma_f32_16x16x32_bf16 v[84:87], v[196:199], v[180:183], v[84:87]
	v_mfma_f32_16x16x32_bf16 v[80:83], v[212:215], v[180:183], v[80:83]
	v_mfma_f32_16x16x32_bf16 v[68:71], v[196:199], v[188:191], v[68:71]
	v_mfma_f32_16x16x32_bf16 v[64:67], v[212:215], v[188:191], v[64:67]
	v_mfma_f32_16x16x32_bf16 v[116:119], v[208:211], v[148:151], v[116:119]
	v_mfma_f32_16x16x32_bf16 v[112:115], v[216:219], v[148:151], v[112:115]
	v_mfma_f32_16x16x32_bf16 v[100:103], v[208:211], v[176:179], v[100:103]
	v_mfma_f32_16x16x32_bf16 v[96:99], v[216:219], v[176:179], v[96:99]
	v_mfma_f32_16x16x32_bf16 v[84:87], v[208:211], v[184:187], v[84:87]
	v_mfma_f32_16x16x32_bf16 v[80:83], v[216:219], v[184:187], v[80:83]
	v_mfma_f32_16x16x32_bf16 v[68:71], v[208:211], v[192:195], v[68:71]
	v_mfma_f32_16x16x32_bf16 v[64:67], v[216:219], v[192:195], v[64:67]
	s_mov_b32 m0, s41
	v_lshl_add_u64 v[200:201], s[28:29], 0, v[158:159]
	s_barrier
	ds_read_b128 v[144:147], v204 offset:49152
	ds_read_b128 v[148:151], v204 offset:50176
	ds_read_b128 v[172:175], v204 offset:51200
	ds_read_b128 v[176:179], v204 offset:52224
	ds_read_b128 v[180:183], v204 offset:53248
	ds_read_b128 v[184:187], v204 offset:54272
	ds_read_b128 v[188:191], v204 offset:55296
	ds_read_b128 v[192:195], v204 offset:56320
	global_load_lds_dwordx4 v[200:201], off
	v_lshl_add_u64 v[200:201], s[28:29], 0, v[154:155]
	s_mov_b32 m0, s42
	s_nop 0
	global_load_lds_dwordx4 v[200:201], off
	s_barrier
	s_waitcnt lgkmcnt(0)
	v_mfma_f32_16x16x32_bf16 v[60:63], v[128:131], v[144:147], v[60:63]
	v_mfma_f32_16x16x32_bf16 v[56:59], v[136:139], v[144:147], v[56:59]
	v_mfma_f32_16x16x32_bf16 v[44:47], v[128:131], v[172:175], v[44:47]
	v_mfma_f32_16x16x32_bf16 v[40:43], v[136:139], v[172:175], v[40:43]
	v_mfma_f32_16x16x32_bf16 v[28:31], v[128:131], v[180:183], v[28:31]
	v_mfma_f32_16x16x32_bf16 v[24:27], v[136:139], v[180:183], v[24:27]
	v_mfma_f32_16x16x32_bf16 v[12:15], v[128:131], v[188:191], v[12:15]
	v_mfma_f32_16x16x32_bf16 v[8:11], v[136:139], v[188:191], v[8:11]
	v_mfma_f32_16x16x32_bf16 v[60:63], v[132:135], v[148:151], v[60:63]
	v_mfma_f32_16x16x32_bf16 v[56:59], v[140:143], v[148:151], v[56:59]
	v_mfma_f32_16x16x32_bf16 v[44:47], v[132:135], v[176:179], v[44:47]
	v_mfma_f32_16x16x32_bf16 v[40:43], v[140:143], v[176:179], v[40:43]
	v_mfma_f32_16x16x32_bf16 v[28:31], v[132:135], v[184:187], v[28:31]
	v_mfma_f32_16x16x32_bf16 v[24:27], v[140:143], v[184:187], v[24:27]
	v_mfma_f32_16x16x32_bf16 v[12:15], v[132:135], v[192:195], v[12:15]
	v_mfma_f32_16x16x32_bf16 v[8:11], v[140:143], v[192:195], v[8:11]
	s_barrier
	s_add_u32 s26, s26, 0x24000
	s_addc_u32 s27, s27, 0
	s_add_i32 s28, s51, s13
	v_lshl_add_u64 v[128:129], s[26:27], 0, v[156:157]
	s_mov_b32 m0, s28
	s_nop 0
	global_load_lds_dwordx4 v[128:129], off
	v_lshl_add_u64 v[128:129], s[26:27], 0, v[152:153]
	s_add_i32 m0, s28, 0x2000
	s_nop 0
	global_load_lds_dwordx4 v[128:129], off
	s_waitcnt vmcnt(6)
	s_barrier
	v_mfma_f32_16x16x32_bf16 v[52:55], v[196:199], v[144:147], v[52:55]
	v_mfma_f32_16x16x32_bf16 v[48:51], v[212:215], v[144:147], v[48:51]
	v_mfma_f32_16x16x32_bf16 v[36:39], v[196:199], v[172:175], v[36:39]
	v_mfma_f32_16x16x32_bf16 v[32:35], v[212:215], v[172:175], v[32:35]
	v_mfma_f32_16x16x32_bf16 v[20:23], v[196:199], v[180:183], v[20:23]
	v_mfma_f32_16x16x32_bf16 v[16:19], v[212:215], v[180:183], v[16:19]
	v_mfma_f32_16x16x32_bf16 v[4:7], v[196:199], v[188:191], v[4:7]
	v_mfma_f32_16x16x32_bf16 v[0:3], v[212:215], v[188:191], v[0:3]
	v_mfma_f32_16x16x32_bf16 v[52:55], v[208:211], v[148:151], v[52:55]
	v_mfma_f32_16x16x32_bf16 v[48:51], v[216:219], v[148:151], v[48:51]
	v_mfma_f32_16x16x32_bf16 v[36:39], v[208:211], v[176:179], v[36:39]
	v_mfma_f32_16x16x32_bf16 v[32:35], v[216:219], v[176:179], v[32:35]
	v_mfma_f32_16x16x32_bf16 v[20:23], v[208:211], v[184:187], v[20:23]
	v_mfma_f32_16x16x32_bf16 v[16:19], v[216:219], v[184:187], v[16:19]
	v_mfma_f32_16x16x32_bf16 v[4:7], v[208:211], v[192:195], v[4:7]
	v_mfma_f32_16x16x32_bf16 v[0:3], v[216:219], v[192:195], v[0:3]
	s_add_i32 s49, s49, 2
	s_add_u32 s17, s17, 0x40000
	s_addc_u32 s48, s48, 0
	s_add_u32 s24, s24, 0x800000
	s_addc_u32 s25, s25, 0
	s_cmp_gt_u32 s49, 61
	s_barrier
	s_cbranch_scc0 .LBB0_1512
	s_nop 0
	s_lshl_b32 s24, s4, 8
	v_readlane_b32 s68, v253, 38
	v_readlane_b32 s69, v253, 39
	s_ashr_i32 s25, s24, 31
	s_lshl_b32 s4, s4, 2
	v_readlane_b32 s70, v253, 40
	v_readlane_b32 s71, v253, 41
	s_mov_b64 s[48:49], s[68:69]
	v_lshl_add_u32 v178, s6, 8, v163
	s_ashr_i32 s5, s4, 31
	s_lshl_b64 s[26:27], s[24:25], 1
	s_mov_b64 s[50:51], s[70:71]
	s_add_u32 s26, s50, s26
	v_ashrrev_i32_e32 v179, 31, v178
	s_addc_u32 s27, s51, s27
	v_lshlrev_b64 v[128:129], 11, v[178:179]
	v_lshl_add_u64 v[128:129], s[26:27], 0, v[128:129]
	v_lshl_add_u64 v[128:129], v[128:129], 0, v[160:161]
	global_load_dwordx4 v[180:183], v[128:129], off
	global_load_dwordx4 v[184:187], v[128:129], off offset:256
	v_or_b32_e32 v176, 16, v178
	v_or_b32_e32 v174, 32, v178
	v_or_b32_e32 v172, 48, v178
	v_ashrrev_i32_e32 v177, 31, v176
	v_ashrrev_i32_e32 v175, 31, v174
	v_ashrrev_i32_e32 v173, 31, v172
	v_lshlrev_b64 v[128:129], 11, v[176:177]
	v_lshlrev_b64 v[130:131], 11, v[174:175]
	v_lshlrev_b64 v[132:133], 11, v[172:173]
	v_lshl_add_u64 v[128:129], s[26:27], 0, v[128:129]
	v_lshl_add_u64 v[130:131], s[26:27], 0, v[130:131]
	v_lshl_add_u64 v[132:133], s[26:27], 0, v[132:133]
	v_lshl_add_u64 v[128:129], v[128:129], 0, v[160:161]
	v_lshl_add_u64 v[130:131], v[130:131], 0, v[160:161]
	v_lshl_add_u64 v[188:189], v[132:133], 0, v[160:161]
	global_load_dwordx4 v[148:151], v[128:129], off
	global_load_dwordx4 v[144:147], v[128:129], off offset:256
	global_load_dwordx4 v[140:143], v[130:131], off
	global_load_dwordx4 v[136:139], v[130:131], off offset:256
	global_load_dwordx4 v[132:135], v[188:189], off
	s_nop 0
	global_load_dwordx4 v[128:131], v[188:189], off offset:256
	v_and_b32_e32 v189, 64, v206
	v_xor_b32_e32 v188, 16, v206
	v_add_u32_e32 v196, 64, v189
	v_cmp_lt_i32_e32 vcc, v188, v196
	s_nop 1
	v_cndmask_b32_e32 v188, v206, v188, vcc
	v_lshlrev_b32_e32 v207, 2, v188
	s_nop 7
	s_nop 0
	s_waitcnt vmcnt(0)
	v_lshlrev_b32_e32 v190, 16, v182
	v_and_b32_e32 v191, 0xffff0000, v182
	v_lshlrev_b32_e32 v188, 16, v180
	v_and_b32_e32 v189, 0xffff0000, v180
	v_lshlrev_b32_e32 v180, 16, v181
	v_and_b32_e32 v181, 0xffff0000, v181
	v_lshlrev_b32_e32 v182, 16, v183
	v_and_b32_e32 v183, 0xffff0000, v183
	v_pk_add_f32 v[120:121], v[120:121], v[190:191]
	v_pk_add_f32 v[126:127], v[126:127], v[180:181]
	v_pk_add_f32 v[124:125], v[124:125], v[188:189]
	v_pk_add_f32 v[122:123], v[122:123], v[182:183]
	v_mul_f32_e32 v180, v120, v120
	v_mul_f32_e32 v181, v121, v121
	v_lshlrev_b32_e32 v194, 16, v186
	v_and_b32_e32 v195, 0xffff0000, v186
	v_mul_f32_e32 v182, v122, v122
	v_fmac_f32_e32 v180, v124, v124
	v_fmac_f32_e32 v181, v125, v125
	v_lshlrev_b32_e32 v192, 16, v184
	v_and_b32_e32 v193, 0xffff0000, v184
	v_lshlrev_b32_e32 v184, 16, v185
	v_and_b32_e32 v185, 0xffff0000, v185
	v_pk_add_f32 v[112:113], v[112:113], v[194:195]
	v_mul_f32_e32 v183, v123, v123
	v_fmac_f32_e32 v182, v126, v126
	v_add_f32_e32 v180, v180, v181
	v_lshlrev_b32_e32 v186, 16, v187
	v_and_b32_e32 v187, 0xffff0000, v187
	v_pk_add_f32 v[118:119], v[118:119], v[184:185]
	v_pk_add_f32 v[116:117], v[116:117], v[192:193]
	v_mul_f32_e32 v184, v112, v112
	v_fmac_f32_e32 v183, v127, v127
	v_add_f32_e32 v180, v182, v180
	v_pk_add_f32 v[114:115], v[114:115], v[186:187]
	v_mul_f32_e32 v185, v113, v113
	v_fmac_f32_e32 v184, v116, v116
	v_add_f32_e32 v180, v183, v180
	v_mul_f32_e32 v186, v114, v114
	v_fmac_f32_e32 v185, v117, v117
	v_add_f32_e32 v180, v184, v180
	v_mul_f32_e32 v187, v115, v115
	v_fmac_f32_e32 v186, v118, v118
	v_add_f32_e32 v180, v185, v180
	v_add_f32_e32 v180, v186, v180
	v_fmac_f32_e32 v187, v119, v119
	v_add_f32_e32 v180, v187, v180
	ds_bpermute_b32 v181, v207, v180
	v_xor_b32_e32 v182, 32, v206
	v_cmp_lt_i32_e32 vcc, v182, v196
	v_lshlrev_b64 v[188:189], 6, v[178:179]
	s_waitcnt lgkmcnt(0)
	v_add_f32_e32 v180, v180, v181
	v_cndmask_b32_e32 v182, v206, v182, vcc
	v_lshlrev_b32_e32 v208, 2, v182
	ds_bpermute_b32 v181, v208, v180
	s_and_saveexec_b64 s[28:29], s[0:1]
	s_cbranch_execz .LBB0_1515
	s_waitcnt lgkmcnt(0)
	v_add_f32_e32 v182, v180, v181
	v_lshl_add_u64 v[180:181], s[88:89], 0, v[188:189]
	v_lshl_add_u64 v[180:181], s[4:5], 2, v[180:181]
	s_lshl_b32 s8, s40, 2
	v_lshl_add_u64 v[180:181], v[180:181], 0, s[8:9]
	global_store_dword v[180:181], v182, off sc1
